# removed the 42 duplicated lgkmcnt(0) waits at the head of GEMM compute segments
# speedup vs baseline: 1.0077x; 1.0077x over previous
; #define PG8_STAGE(bufoff, gbase, voff) do { _Pragma("unroll") for (int _i = 0; _i < 2; ++_i) \
;     __builtin_amdgcn_global_load_lds((const unsigned*)((const char*)(gbase) + (voff)[_i]), (PG8_LAS unsigned*)(lds + (bufoff) + ldsw + _i * 8192), 16, 0, 0); } while (0)
; #define PG8_LDA(dst, b, h) do { _Pragma("unroll") for (int m = 0; m < 4; ++m) _Pragma("unroll") for (int k = 0; k < 2; ++k) dst[m][k] = *(const PG8_LAS bf16x8*)(lds + PG8_SA(b, h) + aoff + m * 2048 + k * 1024); } while (0)
; #define PG8_LDB(dst, b, h) do { _Pragma("unroll") for (int n = 0; n < 2; ++n) _Pragma("unroll") for (int k = 0; k < 2; ++k) dst[n][k] = *(const PG8_LAS bf16x8*)(lds + PG8_SB(b, h) + boff + n * 2048 + k * 1024); } while (0)
; #define PG8_MMA(ai, bj, At, Bt) do { __builtin_amdgcn_s_setprio(1); _Pragma("unroll") for (int m = 0; m < 4; ++m) _Pragma("unroll") for (int n = 0; n < 2; ++n) _Pragma("unroll") for (int k = 0; k < 2; ++k) \
;     acc[ai][bj][m][n] = __builtin_amdgcn_mfma_f32_16x16x32_bf16(Bt[n][k], At[m][k], acc[ai][bj][m][n], 0, 0, 0); __builtin_amdgcn_s_setprio(0); } while (0)
; #define PG8_WAIT_V(n) asm volatile("s_waitcnt vmcnt(" #n ")" ::: "memory")
; #define PG8_WAIT_L(n) asm volatile("s_waitcnt lgkmcnt(" #n ")" ::: "memory")
; #define PG8_BAR __builtin_amdgcn_s_barrier()
; template <class Epi, class Sched>
; __device__ __forceinline__ void gemm_phase(PG8_LAS unsigned char* lds, const int lda, const int ldb, const Sched& S, const Epi& E) {
;     ...
;     for (int t = 0; t < nt; t += 2) {
;       const bool last = (t == nt - 2);
;       const char* a1 = cA + (size_t)(t + 1) * kstep;
;       const char* a2 = last ? nA : cA + (size_t)(t + 2) * kstep; const char* b2 = last ? nB : cB + (size_t)(t + 2) * kstep;
;       const char* a3 = a2 + kstep; const char* b3 = b2 + kstep;
;       PG8_LDB(B0, 0, 0); PG8_SCHED; PG8_LDA(At, 0, 0); PG8_STAGE(PG8_SA(1, 1), a1 + hstepA, voffA);
;       PG8_WAIT_L(8); PG8_BAR; PG8_WAIT_L(0); PG8_MMA(0, 0, At, B0); PG8_BAR; PG8_SCHED;
;       PG8_LDB(B1, 0, 1); PG8_STAGE(PG8_SB(0, 0), b2, voffB);
;       PG8_BAR; PG8_WAIT_L(0); PG8_MMA(0, 1, At, B1); PG8_BAR;
;       PG8_LDA(At, 0, 1); PG8_STAGE(PG8_SA(0, 0), a2, voffA);
;       PG8_BAR; PG8_WAIT_L(0); PG8_MMA(1, 0, At, B0); PG8_BAR; PG8_SCHED;
;       PG8_STAGE(PG8_SB(0, 1), b2 + hstepB, voffB);
;       PG8_WAIT_V(6); PG8_BAR; PG8_MMA(1, 1, At, B1); PG8_BAR;
.LBB0_335:
	s_add_u32 s10, s8, 0xfffc0080
	s_addc_u32 s11, s9, -1
	s_add_i32 s31, 0, 0x10000
	v_add_u32_e32 v156, s31, v131
	ds_read_b128 v[144:147], v156
	ds_read_b128 v[148:151], v156 offset:1024
	ds_read_b128 v[152:155], v156 offset:2048
	ds_read_b128 v[200:203], v156 offset:3072
	s_cmp_eq_u32 s30, 12
	s_cselect_b32 s25, s17, s11
	s_cselect_b32 s24, s26, s10
	s_cselect_b32 s11, s15, s29
	s_cselect_b32 s10, s27, s28
	v_lshl_add_u64 v[156:157], s[8:9], 0, v[140:141]
	s_add_i32 m0, s40, 0xc000
	ds_read_b128 v[204:207], v172
	ds_read_b128 v[208:211], v172 offset:1024
	ds_read_b128 v[212:215], v172 offset:2048
	ds_read_b128 v[216:219], v172 offset:3072
	ds_read_b128 v[220:223], v172 offset:4096
	ds_read_b128 v[224:227], v172 offset:5120
	ds_read_b128 v[228:231], v172 offset:6144
	ds_read_b128 v[232:235], v172 offset:7168
	global_load_lds_dwordx4 v[156:157], off
	v_lshl_add_u64 v[156:157], s[8:9], 0, v[142:143]
	s_add_i32 m0, s40, 0xe000
	s_nop 0
	global_load_lds_dwordx4 v[156:157], off
	s_waitcnt lgkmcnt(8)
	s_barrier
	s_waitcnt lgkmcnt(0)
	s_setprio 1
	v_mfma_f32_16x16x32_bf16 v[126:129], v[144:147], v[204:207], v[126:129]
	v_mfma_f32_16x16x32_bf16 v[122:125], v[152:155], v[204:207], v[122:125]
	v_mfma_f32_16x16x32_bf16 v[110:113], v[144:147], v[212:215], v[110:113]
	v_mfma_f32_16x16x32_bf16 v[106:109], v[152:155], v[212:215], v[106:109]
	v_mfma_f32_16x16x32_bf16 v[94:97], v[144:147], v[220:223], v[94:97]
	v_mfma_f32_16x16x32_bf16 v[90:93], v[152:155], v[220:223], v[90:93]
	v_mfma_f32_16x16x32_bf16 v[78:81], v[144:147], v[228:231], v[78:81]
	v_mfma_f32_16x16x32_bf16 v[74:77], v[152:155], v[228:231], v[74:77]
	v_mfma_f32_16x16x32_bf16 v[126:129], v[148:151], v[208:211], v[126:129]
	v_mfma_f32_16x16x32_bf16 v[122:125], v[200:203], v[208:211], v[122:125]
	v_mfma_f32_16x16x32_bf16 v[110:113], v[148:151], v[216:219], v[110:113]
	v_mfma_f32_16x16x32_bf16 v[106:109], v[200:203], v[216:219], v[106:109]
	v_mfma_f32_16x16x32_bf16 v[94:97], v[148:151], v[224:227], v[94:97]
	v_mfma_f32_16x16x32_bf16 v[90:93], v[200:203], v[224:227], v[90:93]
	v_mfma_f32_16x16x32_bf16 v[78:81], v[148:151], v[232:235], v[78:81]
	v_mfma_f32_16x16x32_bf16 v[74:77], v[200:203], v[232:235], v[74:77]
	s_setprio 0
	s_barrier
	s_add_i32 s33, 0, 0x14000
	v_add_u32_e32 v156, s33, v131
	s_add_i32 s31, s31, s39
	ds_read_b128 v[236:239], v156
	ds_read_b128 v[240:243], v156 offset:1024
	ds_read_b128 v[244:247], v156 offset:2048
	ds_read_b128 v[248:251], v156 offset:3072
	v_lshl_add_u64 v[156:157], s[10:11], 0, v[134:135]
	s_mov_b32 m0, s31
	v_lshl_add_u64 v[174:175], s[10:11], 0, v[132:133]
	global_load_lds_dwordx4 v[156:157], off
	s_add_i32 m0, s31, 0x2000
	s_nop 0
	global_load_lds_dwordx4 v[174:175], off
	s_barrier
	s_waitcnt lgkmcnt(0)
	s_setprio 1
	v_mfma_f32_16x16x32_bf16 v[118:121], v[236:239], v[204:207], v[118:121]
	v_mfma_f32_16x16x32_bf16 v[114:117], v[244:247], v[204:207], v[114:117]
	v_mfma_f32_16x16x32_bf16 v[102:105], v[236:239], v[212:215], v[102:105]
	v_mfma_f32_16x16x32_bf16 v[98:101], v[244:247], v[212:215], v[98:101]
	v_mfma_f32_16x16x32_bf16 v[86:89], v[236:239], v[220:223], v[86:89]
	v_mfma_f32_16x16x32_bf16 v[82:85], v[244:247], v[220:223], v[82:85]
	v_mfma_f32_16x16x32_bf16 v[70:73], v[236:239], v[228:231], v[70:73]
	v_mfma_f32_16x16x32_bf16 v[66:69], v[244:247], v[228:231], v[66:69]
	v_mfma_f32_16x16x32_bf16 v[118:121], v[240:243], v[208:211], v[118:121]
	v_mfma_f32_16x16x32_bf16 v[114:117], v[248:251], v[208:211], v[114:117]
	v_mfma_f32_16x16x32_bf16 v[102:105], v[240:243], v[216:219], v[102:105]
	v_mfma_f32_16x16x32_bf16 v[98:101], v[248:251], v[216:219], v[98:101]
	v_mfma_f32_16x16x32_bf16 v[86:89], v[240:243], v[224:227], v[86:89]
	v_mfma_f32_16x16x32_bf16 v[82:85], v[248:251], v[224:227], v[82:85]
	v_mfma_f32_16x16x32_bf16 v[70:73], v[240:243], v[232:235], v[70:73]
	v_mfma_f32_16x16x32_bf16 v[66:69], v[248:251], v[232:235], v[66:69]
	s_setprio 0
	s_mov_b32 m0, s40
	v_lshl_add_u64 v[182:183], s[24:25], 0, v[134:135]
	s_barrier
	ds_read_b128 v[204:207], v172 offset:16384
	ds_read_b128 v[208:211], v172 offset:17408
	ds_read_b128 v[212:215], v172 offset:18432
	ds_read_b128 v[216:219], v172 offset:19456
	ds_read_b128 v[220:223], v172 offset:20480
	ds_read_b128 v[224:227], v172 offset:21504
	ds_read_b128 v[228:231], v172 offset:22528
	ds_read_b128 v[232:235], v172 offset:23552
	global_load_lds_dwordx4 v[182:183], off
	v_lshl_add_u64 v[184:185], s[24:25], 0, v[132:133]
	s_mov_b32 m0, s41
	s_nop 0
	global_load_lds_dwordx4 v[184:185], off
	s_barrier
	s_waitcnt lgkmcnt(0)
	s_setprio 1
	v_mfma_f32_16x16x32_bf16 v[62:65], v[144:147], v[204:207], v[62:65]
	v_mfma_f32_16x16x32_bf16 v[58:61], v[152:155], v[204:207], v[58:61]
	v_mfma_f32_16x16x32_bf16 v[46:49], v[144:147], v[212:215], v[46:49]
	v_mfma_f32_16x16x32_bf16 v[42:45], v[152:155], v[212:215], v[42:45]
	v_mfma_f32_16x16x32_bf16 v[30:33], v[144:147], v[220:223], v[30:33]
	v_mfma_f32_16x16x32_bf16 v[26:29], v[152:155], v[220:223], v[26:29]
	v_mfma_f32_16x16x32_bf16 v[14:17], v[144:147], v[228:231], v[14:17]
	v_mfma_f32_16x16x32_bf16 v[10:13], v[152:155], v[228:231], v[10:13]
	v_mfma_f32_16x16x32_bf16 v[62:65], v[148:151], v[208:211], v[62:65]
	v_mfma_f32_16x16x32_bf16 v[58:61], v[200:203], v[208:211], v[58:61]
	v_mfma_f32_16x16x32_bf16 v[46:49], v[148:151], v[216:219], v[46:49]
	v_mfma_f32_16x16x32_bf16 v[42:45], v[200:203], v[216:219], v[42:45]
	v_mfma_f32_16x16x32_bf16 v[30:33], v[148:151], v[224:227], v[30:33]
	v_mfma_f32_16x16x32_bf16 v[26:29], v[200:203], v[224:227], v[26:29]
	v_mfma_f32_16x16x32_bf16 v[14:17], v[148:151], v[232:235], v[14:17]
	v_mfma_f32_16x16x32_bf16 v[10:13], v[200:203], v[232:235], v[10:13]
	s_setprio 0
	s_barrier
; #define PG8_STAGE(bufoff, gbase, voff) do { _Pragma("unroll") for (int _i = 0; _i < 2; ++_i) \
;     __builtin_amdgcn_global_load_lds((const unsigned*)((const char*)(gbase) + (voff)[_i]), (PG8_LAS unsigned*)(lds + (bufoff) + ldsw + _i * 8192), 16, 0, 0); } while (0)
; #define PG8_LDA(dst, b, h) do { _Pragma("unroll") for (int m = 0; m < 4; ++m) _Pragma("unroll") for (int k = 0; k < 2; ++k) dst[m][k] = *(const PG8_LAS bf16x8*)(lds + PG8_SA(b, h) + aoff + m * 2048 + k * 1024); } while (0)
; #define PG8_LDB(dst, b, h) do { _Pragma("unroll") for (int n = 0; n < 2; ++n) _Pragma("unroll") for (int k = 0; k < 2; ++k) dst[n][k] = *(const PG8_LAS bf16x8*)(lds + PG8_SB(b, h) + boff + n * 2048 + k * 1024); } while (0)
; #define PG8_MMA(ai, bj, At, Bt) do { __builtin_amdgcn_s_setprio(1); _Pragma("unroll") for (int m = 0; m < 4; ++m) _Pragma("unroll") for (int n = 0; n < 2; ++n) _Pragma("unroll") for (int k = 0; k < 2; ++k) \
;     acc[ai][bj][m][n] = __builtin_amdgcn_mfma_f32_16x16x32_bf16(Bt[n][k], At[m][k], acc[ai][bj][m][n], 0, 0, 0); __builtin_amdgcn_s_setprio(0); } while (0)
; #define PG8_WAIT_V(n) asm volatile("s_waitcnt vmcnt(" #n ")" ::: "memory")
; #define PG8_WAIT_L(n) asm volatile("s_waitcnt lgkmcnt(" #n ")" ::: "memory")
; #define PG8_BAR __builtin_amdgcn_s_barrier()
; #define PG8_SCHED __builtin_amdgcn_sched_barrier(0)
; template <class Epi, class Sched>
; __device__ __forceinline__ void gemm_phase(PG8_LAS unsigned char* lds, const int lda, const int ldb, const Sched& S, const Epi& E) {
;     ...
;       PG8_STAGE(PG8_SB(0, 1), b2 + hstepB, voffB);
;       PG8_WAIT_V(6); PG8_BAR; PG8_MMA(1, 1, At, B1); PG8_BAR;
;       PG8_LDB(B0, 1, 0); PG8_SCHED; PG8_LDA(At, 1, 0); PG8_STAGE(PG8_SA(0, 1), a2 + hstepA, voffA);
;       PG8_WAIT_L(8); PG8_BAR; PG8_WAIT_L(0); PG8_MMA(0, 0, At, B0); PG8_BAR; PG8_SCHED;
;       PG8_LDB(B1, 1, 1); PG8_STAGE(PG8_SB(1, 0), b3, voffB);
;       PG8_BAR; PG8_WAIT_L(0); PG8_MMA(0, 1, At, B1); PG8_BAR;
;       PG8_LDA(At, 1, 1); PG8_STAGE(PG8_SA(1, 0), a3, voffA);
;       PG8_BAR; PG8_WAIT_L(0); PG8_MMA(1, 0, At, B0); PG8_BAR; PG8_SCHED;
	s_add_u32 s34, s10, 0x40000
	s_addc_u32 s35, s11, 0
	s_add_i32 s31, s33, s39
	v_lshl_add_u64 v[144:145], s[34:35], 0, v[134:135]
	s_mov_b32 m0, s31
	s_nop 0
	global_load_lds_dwordx4 v[144:145], off
	v_lshl_add_u64 v[144:145], s[34:35], 0, v[132:133]
	s_add_i32 m0, s31, 0x2000
	s_nop 0
	global_load_lds_dwordx4 v[144:145], off
	s_waitcnt vmcnt(6)
	s_barrier
	s_setprio 1
	v_mfma_f32_16x16x32_bf16 v[54:57], v[236:239], v[204:207], v[54:57]
	v_mfma_f32_16x16x32_bf16 v[50:53], v[244:247], v[204:207], v[50:53]
	v_mfma_f32_16x16x32_bf16 v[38:41], v[236:239], v[212:215], v[38:41]
	v_mfma_f32_16x16x32_bf16 v[34:37], v[244:247], v[212:215], v[34:37]
	v_mfma_f32_16x16x32_bf16 v[22:25], v[236:239], v[220:223], v[22:25]
	v_mfma_f32_16x16x32_bf16 v[18:21], v[244:247], v[220:223], v[18:21]
	v_mfma_f32_16x16x32_bf16 v[6:9], v[236:239], v[228:231], v[6:9]
	v_mfma_f32_16x16x32_bf16 v[2:5], v[244:247], v[228:231], v[2:5]
	v_mfma_f32_16x16x32_bf16 v[54:57], v[240:243], v[208:211], v[54:57]
	v_mfma_f32_16x16x32_bf16 v[50:53], v[248:251], v[208:211], v[50:53]
	v_mfma_f32_16x16x32_bf16 v[38:41], v[240:243], v[216:219], v[38:41]
	v_mfma_f32_16x16x32_bf16 v[34:37], v[248:251], v[216:219], v[34:37]
	v_mfma_f32_16x16x32_bf16 v[22:25], v[240:243], v[224:227], v[22:25]
	v_mfma_f32_16x16x32_bf16 v[18:21], v[248:251], v[224:227], v[18:21]
	v_mfma_f32_16x16x32_bf16 v[6:9], v[240:243], v[232:235], v[6:9]
	v_mfma_f32_16x16x32_bf16 v[2:5], v[248:251], v[232:235], v[2:5]
	s_setprio 0
	s_add_i32 s31, 0, 0x18000
	v_add_u32_e32 v173, s31, v131
	s_barrier
	ds_read_b128 v[144:147], v173
	ds_read_b128 v[148:151], v173 offset:1024
	ds_read_b128 v[152:155], v173 offset:2048
	ds_read_b128 v[200:203], v173 offset:3072
	s_add_u32 s24, s24, 0x40000
	s_addc_u32 s25, s25, 0
	s_mov_b32 m0, s42
	v_lshl_add_u64 v[236:237], s[24:25], 0, v[134:135]
	ds_read_b128 v[204:207], v172 offset:32768
	ds_read_b128 v[208:211], v172 offset:33792
	ds_read_b128 v[212:215], v172 offset:34816
	ds_read_b128 v[216:219], v172 offset:35840
	ds_read_b128 v[220:223], v172 offset:36864
	ds_read_b128 v[224:227], v172 offset:37888
	ds_read_b128 v[228:231], v172 offset:38912
	ds_read_b128 v[232:235], v172 offset:39936
	global_load_lds_dwordx4 v[236:237], off
	v_lshl_add_u64 v[236:237], s[24:25], 0, v[132:133]
	s_mov_b32 m0, s43
	s_nop 0
	global_load_lds_dwordx4 v[236:237], off
	s_waitcnt lgkmcnt(8)
	s_barrier
	s_waitcnt lgkmcnt(0)
	s_setprio 1
	v_mfma_f32_16x16x32_bf16 v[126:129], v[144:147], v[204:207], v[126:129]
	v_mfma_f32_16x16x32_bf16 v[122:125], v[152:155], v[204:207], v[122:125]
	v_mfma_f32_16x16x32_bf16 v[110:113], v[144:147], v[212:215], v[110:113]
	v_mfma_f32_16x16x32_bf16 v[106:109], v[152:155], v[212:215], v[106:109]
	v_mfma_f32_16x16x32_bf16 v[94:97], v[144:147], v[220:223], v[94:97]
	v_mfma_f32_16x16x32_bf16 v[90:93], v[152:155], v[220:223], v[90:93]
	v_mfma_f32_16x16x32_bf16 v[78:81], v[144:147], v[228:231], v[78:81]
	v_mfma_f32_16x16x32_bf16 v[74:77], v[152:155], v[228:231], v[74:77]
	v_mfma_f32_16x16x32_bf16 v[126:129], v[148:151], v[208:211], v[126:129]
	v_mfma_f32_16x16x32_bf16 v[122:125], v[200:203], v[208:211], v[122:125]
	v_mfma_f32_16x16x32_bf16 v[110:113], v[148:151], v[216:219], v[110:113]
	v_mfma_f32_16x16x32_bf16 v[106:109], v[200:203], v[216:219], v[106:109]
	v_mfma_f32_16x16x32_bf16 v[94:97], v[148:151], v[224:227], v[94:97]
	v_mfma_f32_16x16x32_bf16 v[90:93], v[200:203], v[224:227], v[90:93]
	v_mfma_f32_16x16x32_bf16 v[78:81], v[148:151], v[232:235], v[78:81]
	v_mfma_f32_16x16x32_bf16 v[74:77], v[200:203], v[232:235], v[74:77]
	s_setprio 0
	s_barrier
	s_add_i32 s24, 0, 0x1c000
	s_add_i32 s25, s31, s39
	v_add_u32_e32 v173, s24, v131
	v_lshl_add_u64 v[156:157], v[156:157], 0, s[86:87]
	s_mov_b32 m0, s25
	ds_read_b128 v[236:239], v173
	ds_read_b128 v[240:243], v173 offset:1024
	ds_read_b128 v[244:247], v173 offset:2048
	ds_read_b128 v[248:251], v173 offset:3072
	global_load_lds_dwordx4 v[156:157], off
	v_lshl_add_u64 v[156:157], v[174:175], 0, s[86:87]
	s_add_i32 m0, s25, 0x2000
	s_nop 0
	global_load_lds_dwordx4 v[156:157], off
	s_barrier
	s_waitcnt lgkmcnt(0)
	s_setprio 1
	v_mfma_f32_16x16x32_bf16 v[118:121], v[236:239], v[204:207], v[118:121]
	v_mfma_f32_16x16x32_bf16 v[114:117], v[244:247], v[204:207], v[114:117]
	v_mfma_f32_16x16x32_bf16 v[102:105], v[236:239], v[212:215], v[102:105]
	v_mfma_f32_16x16x32_bf16 v[98:101], v[244:247], v[212:215], v[98:101]
	v_mfma_f32_16x16x32_bf16 v[86:89], v[236:239], v[220:223], v[86:89]
	v_mfma_f32_16x16x32_bf16 v[82:85], v[244:247], v[220:223], v[82:85]
	v_mfma_f32_16x16x32_bf16 v[70:73], v[236:239], v[228:231], v[70:73]
	v_mfma_f32_16x16x32_bf16 v[66:69], v[244:247], v[228:231], v[66:69]
	v_mfma_f32_16x16x32_bf16 v[118:121], v[240:243], v[208:211], v[118:121]
	v_mfma_f32_16x16x32_bf16 v[114:117], v[248:251], v[208:211], v[114:117]
	v_mfma_f32_16x16x32_bf16 v[102:105], v[240:243], v[216:219], v[102:105]
	v_mfma_f32_16x16x32_bf16 v[98:101], v[248:251], v[216:219], v[98:101]
	v_mfma_f32_16x16x32_bf16 v[86:89], v[240:243], v[224:227], v[86:89]
	v_mfma_f32_16x16x32_bf16 v[82:85], v[248:251], v[224:227], v[82:85]
	v_mfma_f32_16x16x32_bf16 v[70:73], v[240:243], v[232:235], v[70:73]
	v_mfma_f32_16x16x32_bf16 v[66:69], v[248:251], v[232:235], v[66:69]
	s_setprio 0
	s_mov_b32 m0, s45
	v_lshl_add_u64 v[156:157], v[182:183], 0, s[86:87]
	s_barrier
	ds_read_b128 v[204:207], v172 offset:49152
	ds_read_b128 v[208:211], v172 offset:50176
	ds_read_b128 v[212:215], v172 offset:51200
	ds_read_b128 v[216:219], v172 offset:52224
	ds_read_b128 v[220:223], v172 offset:53248
	ds_read_b128 v[224:227], v172 offset:54272
	ds_read_b128 v[228:231], v172 offset:55296
	ds_read_b128 v[232:235], v172 offset:56320
	global_load_lds_dwordx4 v[156:157], off
	v_lshl_add_u64 v[156:157], v[184:185], 0, s[86:87]
	s_mov_b32 m0, s46
	s_nop 0
	global_load_lds_dwordx4 v[156:157], off
	s_barrier
; #define PG8_STAGE(bufoff, gbase, voff) do { _Pragma("unroll") for (int _i = 0; _i < 2; ++_i) \
;     __builtin_amdgcn_global_load_lds((const unsigned*)((const char*)(gbase) + (voff)[_i]), (PG8_LAS unsigned*)(lds + (bufoff) + ldsw + _i * 8192), 16, 0, 0); } while (0)
; template <class Epi, class Sched>
; __device__ __forceinline__ void gemm_phase(PG8_LAS unsigned char* lds, const int lda, const int ldb, const Sched& S, const Epi& E) {
;     ...
;       PG8_WAIT_L(8); PG8_BAR; PG8_WAIT_L(0); PG8_MMA(0, 0, At, B0); PG8_BAR; PG8_SCHED;
;       PG8_LDB(B1, 1, 1); PG8_STAGE(PG8_SB(1, 0), b3, voffB);
;       PG8_BAR; PG8_WAIT_L(0); PG8_MMA(0, 1, At, B1); PG8_BAR;
;       PG8_LDA(At, 1, 1); PG8_STAGE(PG8_SA(1, 0), a3, voffA);
;       PG8_BAR; PG8_WAIT_L(0); PG8_MMA(1, 0, At, B0); PG8_BAR; PG8_SCHED;
;       PG8_STAGE(PG8_SB(1, 1), b3 + hstepB, voffB);
;       PG8_WAIT_V(6); PG8_BAR; PG8_MMA(1, 1, At, B1); PG8_BAR;
;     }
;   __device__ __forceinline__ void operator()(const f32x4 (&acc)[2][2][4][2], const Unit& u, int wr, int wc, int fr, int fq) const {
;     ...
;             const f32x4 v = acc[ai][bj][m][n];
;             const int c = u.pn * 256 + bj * 128 + wc * 32 + n * 16 + 4 * fq;
;             if (u.pn < 7) {
;               uint2 w; w.x = pack2(v[0], v[1]); w.y = pack2(v[2], v[3]);
;               *reinterpret_cast<uint2*>(PB + (size_t)r * PBW + c) = w;
;             } else {
;               const int nn = c - 1792, part = nn >> 8, ch = nn & 255;
;               if (u.pn == 7 && bj == 0 && wc == 1 && n == 1) {
;                 *reinterpret_cast<float4*>(AB + (size_t)r * 16 + 4 * fq) = make_float4(v[0], v[1], v[2], v[3]);
;               } else {
;                 u16* d; int cstride;
;                 if (r < ML) { const int b = r >> 11, tt = r & 2047; d = FT + ((size_t)(b * 256)) * 4096 + part * 2048 + tt; cstride = 4096; }
;                 else { const int rc = r - ML, b = rc >> 8, tt = rc & 255; d = FTC + ((size_t)(b * 256)) * 512 + part * 256 + tt; cstride = 512; }
; #pragma unroll
;                 for (int e = 0; e < 4; ++e) d[(size_t)(ch + e) * cstride] = f2bf(v[e]);
;                 if (u.pn == 7 && bj == 0 && wc == 0) {
; #pragma unroll
;                   for (int e = 0; e < 4; ++e) {
;                     const int kc = n * 16 + 4 * fq + e;
;                     if (kc >= 1 && kc <= 16) d[(size_t)(64 - kc) * cstride] = f2bf(v[e]);
	s_waitcnt lgkmcnt(0)
	s_setprio 1
	v_mfma_f32_16x16x32_bf16 v[62:65], v[144:147], v[204:207], v[62:65]
	v_mfma_f32_16x16x32_bf16 v[58:61], v[152:155], v[204:207], v[58:61]
	v_mfma_f32_16x16x32_bf16 v[46:49], v[144:147], v[212:215], v[46:49]
	v_mfma_f32_16x16x32_bf16 v[42:45], v[152:155], v[212:215], v[42:45]
	v_mfma_f32_16x16x32_bf16 v[30:33], v[144:147], v[220:223], v[30:33]
	v_mfma_f32_16x16x32_bf16 v[26:29], v[152:155], v[220:223], v[26:29]
	v_mfma_f32_16x16x32_bf16 v[14:17], v[144:147], v[228:231], v[14:17]
	v_mfma_f32_16x16x32_bf16 v[10:13], v[152:155], v[228:231], v[10:13]
	v_mfma_f32_16x16x32_bf16 v[62:65], v[148:151], v[208:211], v[62:65]
	v_mfma_f32_16x16x32_bf16 v[58:61], v[200:203], v[208:211], v[58:61]
	v_mfma_f32_16x16x32_bf16 v[46:49], v[148:151], v[216:219], v[46:49]
	v_mfma_f32_16x16x32_bf16 v[42:45], v[200:203], v[216:219], v[42:45]
	v_mfma_f32_16x16x32_bf16 v[30:33], v[148:151], v[224:227], v[30:33]
	v_mfma_f32_16x16x32_bf16 v[26:29], v[200:203], v[224:227], v[26:29]
	v_mfma_f32_16x16x32_bf16 v[14:17], v[148:151], v[232:235], v[14:17]
	v_mfma_f32_16x16x32_bf16 v[10:13], v[200:203], v[232:235], v[10:13]
	s_setprio 0
	s_barrier
	s_add_u32 s10, s10, 0x40080
	s_addc_u32 s11, s11, 0
	s_add_i32 s24, s24, s39
	v_lshl_add_u64 v[144:145], s[10:11], 0, v[134:135]
	s_mov_b32 m0, s24
	s_nop 0
	global_load_lds_dwordx4 v[144:145], off
	v_lshl_add_u64 v[144:145], s[10:11], 0, v[132:133]
	s_add_i32 m0, s24, 0x2000
	s_nop 0
	global_load_lds_dwordx4 v[144:145], off
	s_waitcnt vmcnt(6)
	s_barrier
	s_setprio 1
	v_mfma_f32_16x16x32_bf16 v[54:57], v[236:239], v[204:207], v[54:57]
	v_mfma_f32_16x16x32_bf16 v[50:53], v[244:247], v[204:207], v[50:53]
	v_mfma_f32_16x16x32_bf16 v[38:41], v[236:239], v[212:215], v[38:41]
	v_mfma_f32_16x16x32_bf16 v[34:37], v[244:247], v[212:215], v[34:37]
	v_mfma_f32_16x16x32_bf16 v[22:25], v[236:239], v[220:223], v[22:25]
	v_mfma_f32_16x16x32_bf16 v[18:21], v[244:247], v[220:223], v[18:21]
	v_mfma_f32_16x16x32_bf16 v[6:9], v[236:239], v[228:231], v[6:9]
	v_mfma_f32_16x16x32_bf16 v[2:5], v[244:247], v[228:231], v[2:5]
	v_mfma_f32_16x16x32_bf16 v[54:57], v[240:243], v[208:211], v[54:57]
	v_mfma_f32_16x16x32_bf16 v[50:53], v[248:251], v[208:211], v[50:53]
	v_mfma_f32_16x16x32_bf16 v[38:41], v[240:243], v[216:219], v[38:41]
	v_mfma_f32_16x16x32_bf16 v[34:37], v[248:251], v[216:219], v[34:37]
	v_mfma_f32_16x16x32_bf16 v[22:25], v[240:243], v[224:227], v[22:25]
	v_mfma_f32_16x16x32_bf16 v[18:21], v[248:251], v[224:227], v[18:21]
	v_mfma_f32_16x16x32_bf16 v[6:9], v[240:243], v[232:235], v[6:9]
	v_mfma_f32_16x16x32_bf16 v[2:5], v[248:251], v[232:235], v[2:5]
	s_setprio 0
	s_add_i32 s30, s30, 2
	s_add_u32 s8, s8, 0x100
	s_addc_u32 s9, s9, 0
	s_add_u32 s28, s28, 0x100
	s_addc_u32 s29, s29, 0
	s_cmp_gt_u32 s30, 13
	s_barrier
	s_cbranch_scc0 .LBB0_335
	s_lshl_b32 s15, s2, 8
	s_add_i32 s15, s15, s44
	v_or_b32_e32 v152, s15, v1
	s_mov_b32 s2, 0xffff
	v_cmp_lt_i32_e64 s[10:11], s2, v152
	s_and_b32 s2, s15, 0xffffff00
	s_add_i32 s2, s2, 0xffff0000
	s_lshl_b64 s[28:29], s[2:3], 10
	s_ashr_i32 s2, s15, 3
	s_and_b32 s8, s2, 0xffffff00
	s_ashr_i32 s9, s8, 31
	s_lshl_b64 s[26:27], s[8:9], 13
	s_lshl_b32 s24, s48, 8
	s_cmp_gt_i32 s48, 6
	s_cselect_b64 s[30:31], -1, 0
	v_bitop3_b32 v146, s15, v186, v1 bitop3:0xc8
	v_bitop3_b32 v148, s15, v187, v1 bitop3:0xc8
	s_mov_b64 s[8:9], -1
	s_and_b64 vcc, exec, s[30:31]
	s_cbranch_vccz .LBB0_346
	s_and_saveexec_b64 s[8:9], s[10:11]
	s_xor_b64 s[8:9], exec, s[8:9]
	s_add_u32 s34, s54, s28
	s_addc_u32 s35, s55, s29
	s_or_saveexec_b64 s[8:9], s[8:9]
	s_add_i32 s2, s24, 0xfffff900
	v_mov_b64_e32 v[144:145], 0x200
	v_mov_b32_e32 v150, s2
	v_mov_b64_e32 v[154:155], s[34:35]
	v_mov_b64_e32 v[156:157], v[146:147]
	s_xor_b64 exec, exec, s[8:9]
	s_add_u32 s34, s69, s26
	s_addc_u32 s35, s52, s27
	s_lshl_b32 s2, s2, 3
	v_mov_b64_e32 v[144:145], 0x1000
	v_mov_b32_e32 v150, s2
	v_mov_b64_e32 v[154:155], s[34:35]
	v_mov_b64_e32 v[156:157], v[148:149]
	s_or_b64 exec, exec, s[8:9]
	v_ashrrev_i32_e32 v151, 31, v150
	v_lshl_add_u64 v[150:151], v[150:151], 1, v[154:155]
	v_lshlrev_b32_e32 v154, 1, v156
	v_mov_b32_e32 v155, v0
	v_mul_u32_u24_e32 v145, v144, v136
	v_lshl_add_u64 v[150:151], v[150:151], 0, v[154:155]
	v_lshlrev_b32_e32 v154, 1, v145
	v_cvt_pk_bf16_f32 v149, v126, s0
	v_lshl_add_u64 v[154:155], v[150:151], 0, v[154:155]
	v_mul_u32_u24_e32 v147, v144, v166
	global_store_short v[154:155], v149, off
	v_lshlrev_b32_e32 v154, 1, v147
	v_mov_b32_e32 v155, v0
	v_cvt_pk_bf16_f32 v145, v127, s0
	v_lshl_add_u64 v[154:155], v[150:151], 0, v[154:155]
	v_mul_u32_u24_e32 v153, v144, v167
	global_store_short v[154:155], v145, off
	v_lshlrev_b32_e32 v154, 1, v153
	v_mov_b32_e32 v155, v0
	s_cmp_lg_u32 s48, 7
	v_cvt_pk_bf16_f32 v147, v128, s0
	v_lshl_add_u64 v[154:155], v[150:151], 0, v[154:155]
	s_cselect_b64 s[8:9], -1, 0
	global_store_short v[154:155], v147, off
	v_mul_u32_u24_e32 v154, v144, v168
	s_xor_b64 s[34:35], s[12:13], -1
	v_lshlrev_b32_e32 v154, 1, v154
	v_mov_b32_e32 v155, v0
	s_or_b64 s[8:9], s[34:35], s[8:9]
	v_cvt_pk_bf16_f32 v153, v129, s0
	v_lshl_add_u64 v[154:155], v[150:151], 0, v[154:155]
	s_and_b64 vcc, exec, s[8:9]
	global_store_short v[154:155], v153, off
	s_cbranch_vccnz .LBB0_345
	s_and_saveexec_b64 s[8:9], s[4:5]
	s_cbranch_execz .LBB0_344
	v_mul_u32_u24_e32 v154, v144, v158
	v_lshlrev_b32_e32 v154, 1, v154
	v_mov_b32_e32 v155, v0
	v_lshl_add_u64 v[154:155], v[150:151], 0, v[154:155]
	global_store_short v[154:155], v149, off

; #define PG8_STAGE(bufoff, gbase, voff) do { _Pragma("unroll") for (int _i = 0; _i < 2; ++_i) \
;     __builtin_amdgcn_global_load_lds((const unsigned*)((const char*)(gbase) + (voff)[_i]), (PG8_LAS unsigned*)(lds + (bufoff) + ldsw + _i * 8192), 16, 0, 0); } while (0)
; #define PG8_LDA(dst, b, h) do { _Pragma("unroll") for (int m = 0; m < 4; ++m) _Pragma("unroll") for (int k = 0; k < 2; ++k) dst[m][k] = *(const PG8_LAS bf16x8*)(lds + PG8_SA(b, h) + aoff + m * 2048 + k * 1024); } while (0)
; #define PG8_LDB(dst, b, h) do { _Pragma("unroll") for (int n = 0; n < 2; ++n) _Pragma("unroll") for (int k = 0; k < 2; ++k) dst[n][k] = *(const PG8_LAS bf16x8*)(lds + PG8_SB(b, h) + boff + n * 2048 + k * 1024); } while (0)
; #define PG8_MMA(ai, bj, At, Bt) do { __builtin_amdgcn_s_setprio(1); _Pragma("unroll") for (int m = 0; m < 4; ++m) _Pragma("unroll") for (int n = 0; n < 2; ++n) _Pragma("unroll") for (int k = 0; k < 2; ++k) \
;     acc[ai][bj][m][n] = __builtin_amdgcn_mfma_f32_16x16x32_bf16(Bt[n][k], At[m][k], acc[ai][bj][m][n], 0, 0, 0); __builtin_amdgcn_s_setprio(0); } while (0)
; #define PG8_WAIT_V(n) asm volatile("s_waitcnt vmcnt(" #n ")" ::: "memory")
; #define PG8_WAIT_L(n) asm volatile("s_waitcnt lgkmcnt(" #n ")" ::: "memory")
; #define PG8_BAR __builtin_amdgcn_s_barrier()
; template <class Epi, class Sched>
; __device__ __forceinline__ void gemm_phase(PG8_LAS unsigned char* lds, const int lda, const int ldb, const Sched& S, const Epi& E) {
;     ...
;     for (int t = 0; t < nt; t += 2) {
;       const bool last = (t == nt - 2);
;       const char* a1 = cA + (size_t)(t + 1) * kstep;
;       const char* a2 = last ? nA : cA + (size_t)(t + 2) * kstep; const char* b2 = last ? nB : cB + (size_t)(t + 2) * kstep;
;       const char* a3 = a2 + kstep; const char* b3 = b2 + kstep;
;       PG8_LDB(B0, 0, 0); PG8_SCHED; PG8_LDA(At, 0, 0); PG8_STAGE(PG8_SA(1, 1), a1 + hstepA, voffA);
;       PG8_WAIT_L(8); PG8_BAR; PG8_WAIT_L(0); PG8_MMA(0, 0, At, B0); PG8_BAR; PG8_SCHED;
;       PG8_LDB(B1, 0, 1); PG8_STAGE(PG8_SB(0, 0), b2, voffB);
;       PG8_BAR; PG8_WAIT_L(0); PG8_MMA(0, 1, At, B1); PG8_BAR;
;       PG8_LDA(At, 0, 1); PG8_STAGE(PG8_SA(0, 0), a2, voffA);
;       PG8_BAR; PG8_WAIT_L(0); PG8_MMA(1, 0, At, B0); PG8_BAR; PG8_SCHED;
;       PG8_STAGE(PG8_SB(0, 1), b2 + hstepB, voffB);
;       PG8_WAIT_V(6); PG8_BAR; PG8_MMA(1, 1, At, B1); PG8_BAR;
.LBB0_685:
	s_add_u32 s12, s10, 0xfffc0080
	s_addc_u32 s13, s11, -1
	s_add_i32 s31, 0, 0x10000
	v_add_u32_e32 v156, s31, v131
	ds_read_b128 v[144:147], v156
	ds_read_b128 v[148:151], v156 offset:1024
	ds_read_b128 v[152:155], v156 offset:2048
	ds_read_b128 v[200:203], v156 offset:3072
	s_cmp_eq_u32 s30, 12
	s_cselect_b32 s25, s19, s13
	s_cselect_b32 s24, s26, s12
	s_cselect_b32 s13, s17, s29
	s_cselect_b32 s12, s27, s28
	v_lshl_add_u64 v[156:157], s[10:11], 0, v[140:141]
	s_add_i32 m0, s40, 0xc000
	ds_read_b128 v[204:207], v172
	ds_read_b128 v[208:211], v172 offset:1024
	ds_read_b128 v[212:215], v172 offset:2048
	ds_read_b128 v[216:219], v172 offset:3072
	ds_read_b128 v[220:223], v172 offset:4096
	ds_read_b128 v[224:227], v172 offset:5120
	ds_read_b128 v[228:231], v172 offset:6144
	ds_read_b128 v[232:235], v172 offset:7168
	global_load_lds_dwordx4 v[156:157], off
	v_lshl_add_u64 v[156:157], s[10:11], 0, v[142:143]
	s_add_i32 m0, s40, 0xe000
	s_nop 0
	global_load_lds_dwordx4 v[156:157], off
	s_waitcnt lgkmcnt(8)
	s_barrier
	s_waitcnt lgkmcnt(0)
	s_setprio 1
	v_mfma_f32_16x16x32_bf16 v[126:129], v[144:147], v[204:207], v[126:129]
	v_mfma_f32_16x16x32_bf16 v[122:125], v[152:155], v[204:207], v[122:125]
	v_mfma_f32_16x16x32_bf16 v[110:113], v[144:147], v[212:215], v[110:113]
	v_mfma_f32_16x16x32_bf16 v[106:109], v[152:155], v[212:215], v[106:109]
	v_mfma_f32_16x16x32_bf16 v[94:97], v[144:147], v[220:223], v[94:97]
	v_mfma_f32_16x16x32_bf16 v[90:93], v[152:155], v[220:223], v[90:93]
	v_mfma_f32_16x16x32_bf16 v[78:81], v[144:147], v[228:231], v[78:81]
	v_mfma_f32_16x16x32_bf16 v[74:77], v[152:155], v[228:231], v[74:77]
	v_mfma_f32_16x16x32_bf16 v[126:129], v[148:151], v[208:211], v[126:129]
	v_mfma_f32_16x16x32_bf16 v[122:125], v[200:203], v[208:211], v[122:125]
	v_mfma_f32_16x16x32_bf16 v[110:113], v[148:151], v[216:219], v[110:113]
	v_mfma_f32_16x16x32_bf16 v[106:109], v[200:203], v[216:219], v[106:109]
	v_mfma_f32_16x16x32_bf16 v[94:97], v[148:151], v[224:227], v[94:97]
	v_mfma_f32_16x16x32_bf16 v[90:93], v[200:203], v[224:227], v[90:93]
	v_mfma_f32_16x16x32_bf16 v[78:81], v[148:151], v[232:235], v[78:81]
	v_mfma_f32_16x16x32_bf16 v[74:77], v[200:203], v[232:235], v[74:77]
	s_setprio 0
	s_barrier
	s_add_i32 s33, 0, 0x14000
	v_add_u32_e32 v156, s33, v131
	s_add_i32 s31, s31, s39
	ds_read_b128 v[236:239], v156
	ds_read_b128 v[240:243], v156 offset:1024
	ds_read_b128 v[244:247], v156 offset:2048
	ds_read_b128 v[248:251], v156 offset:3072
	v_lshl_add_u64 v[156:157], s[12:13], 0, v[134:135]
	s_mov_b32 m0, s31
	v_lshl_add_u64 v[174:175], s[12:13], 0, v[132:133]
	global_load_lds_dwordx4 v[156:157], off
	s_add_i32 m0, s31, 0x2000
	s_nop 0
	global_load_lds_dwordx4 v[174:175], off
	s_barrier
	s_waitcnt lgkmcnt(0)
	s_setprio 1
	v_mfma_f32_16x16x32_bf16 v[118:121], v[236:239], v[204:207], v[118:121]
	v_mfma_f32_16x16x32_bf16 v[114:117], v[244:247], v[204:207], v[114:117]
	v_mfma_f32_16x16x32_bf16 v[102:105], v[236:239], v[212:215], v[102:105]
	v_mfma_f32_16x16x32_bf16 v[98:101], v[244:247], v[212:215], v[98:101]
	v_mfma_f32_16x16x32_bf16 v[86:89], v[236:239], v[220:223], v[86:89]
	v_mfma_f32_16x16x32_bf16 v[82:85], v[244:247], v[220:223], v[82:85]
	v_mfma_f32_16x16x32_bf16 v[70:73], v[236:239], v[228:231], v[70:73]
	v_mfma_f32_16x16x32_bf16 v[66:69], v[244:247], v[228:231], v[66:69]
	v_mfma_f32_16x16x32_bf16 v[118:121], v[240:243], v[208:211], v[118:121]
	v_mfma_f32_16x16x32_bf16 v[114:117], v[248:251], v[208:211], v[114:117]
	v_mfma_f32_16x16x32_bf16 v[102:105], v[240:243], v[216:219], v[102:105]
	v_mfma_f32_16x16x32_bf16 v[98:101], v[248:251], v[216:219], v[98:101]
	v_mfma_f32_16x16x32_bf16 v[86:89], v[240:243], v[224:227], v[86:89]
	v_mfma_f32_16x16x32_bf16 v[82:85], v[248:251], v[224:227], v[82:85]
	v_mfma_f32_16x16x32_bf16 v[70:73], v[240:243], v[232:235], v[70:73]
	v_mfma_f32_16x16x32_bf16 v[66:69], v[248:251], v[232:235], v[66:69]
	s_setprio 0
	s_mov_b32 m0, s40
	v_lshl_add_u64 v[182:183], s[24:25], 0, v[134:135]
	s_barrier
	ds_read_b128 v[204:207], v172 offset:16384
	ds_read_b128 v[208:211], v172 offset:17408
	ds_read_b128 v[212:215], v172 offset:18432
	ds_read_b128 v[216:219], v172 offset:19456
	ds_read_b128 v[220:223], v172 offset:20480
	ds_read_b128 v[224:227], v172 offset:21504
	ds_read_b128 v[228:231], v172 offset:22528
	ds_read_b128 v[232:235], v172 offset:23552
	global_load_lds_dwordx4 v[182:183], off
	v_lshl_add_u64 v[184:185], s[24:25], 0, v[132:133]
	s_mov_b32 m0, s41
	s_nop 0
	global_load_lds_dwordx4 v[184:185], off
	s_barrier
	s_waitcnt lgkmcnt(0)
	s_setprio 1
	v_mfma_f32_16x16x32_bf16 v[62:65], v[144:147], v[204:207], v[62:65]
	v_mfma_f32_16x16x32_bf16 v[58:61], v[152:155], v[204:207], v[58:61]
	v_mfma_f32_16x16x32_bf16 v[46:49], v[144:147], v[212:215], v[46:49]
	v_mfma_f32_16x16x32_bf16 v[42:45], v[152:155], v[212:215], v[42:45]
	v_mfma_f32_16x16x32_bf16 v[30:33], v[144:147], v[220:223], v[30:33]
	v_mfma_f32_16x16x32_bf16 v[26:29], v[152:155], v[220:223], v[26:29]
	v_mfma_f32_16x16x32_bf16 v[14:17], v[144:147], v[228:231], v[14:17]
	v_mfma_f32_16x16x32_bf16 v[10:13], v[152:155], v[228:231], v[10:13]
	v_mfma_f32_16x16x32_bf16 v[62:65], v[148:151], v[208:211], v[62:65]
	v_mfma_f32_16x16x32_bf16 v[58:61], v[200:203], v[208:211], v[58:61]
	v_mfma_f32_16x16x32_bf16 v[46:49], v[148:151], v[216:219], v[46:49]
	v_mfma_f32_16x16x32_bf16 v[42:45], v[200:203], v[216:219], v[42:45]
	v_mfma_f32_16x16x32_bf16 v[30:33], v[148:151], v[224:227], v[30:33]
	v_mfma_f32_16x16x32_bf16 v[26:29], v[200:203], v[224:227], v[26:29]
	v_mfma_f32_16x16x32_bf16 v[14:17], v[148:151], v[232:235], v[14:17]
	v_mfma_f32_16x16x32_bf16 v[10:13], v[200:203], v[232:235], v[10:13]
	s_setprio 0
	s_barrier
; #define PG8_STAGE(bufoff, gbase, voff) do { _Pragma("unroll") for (int _i = 0; _i < 2; ++_i) \
;     __builtin_amdgcn_global_load_lds((const unsigned*)((const char*)(gbase) + (voff)[_i]), (PG8_LAS unsigned*)(lds + (bufoff) + ldsw + _i * 8192), 16, 0, 0); } while (0)
; #define PG8_LDA(dst, b, h) do { _Pragma("unroll") for (int m = 0; m < 4; ++m) _Pragma("unroll") for (int k = 0; k < 2; ++k) dst[m][k] = *(const PG8_LAS bf16x8*)(lds + PG8_SA(b, h) + aoff + m * 2048 + k * 1024); } while (0)
; #define PG8_LDB(dst, b, h) do { _Pragma("unroll") for (int n = 0; n < 2; ++n) _Pragma("unroll") for (int k = 0; k < 2; ++k) dst[n][k] = *(const PG8_LAS bf16x8*)(lds + PG8_SB(b, h) + boff + n * 2048 + k * 1024); } while (0)
; #define PG8_MMA(ai, bj, At, Bt) do { __builtin_amdgcn_s_setprio(1); _Pragma("unroll") for (int m = 0; m < 4; ++m) _Pragma("unroll") for (int n = 0; n < 2; ++n) _Pragma("unroll") for (int k = 0; k < 2; ++k) \
;     acc[ai][bj][m][n] = __builtin_amdgcn_mfma_f32_16x16x32_bf16(Bt[n][k], At[m][k], acc[ai][bj][m][n], 0, 0, 0); __builtin_amdgcn_s_setprio(0); } while (0)
; #define PG8_WAIT_V(n) asm volatile("s_waitcnt vmcnt(" #n ")" ::: "memory")
; #define PG8_WAIT_L(n) asm volatile("s_waitcnt lgkmcnt(" #n ")" ::: "memory")
; #define PG8_BAR __builtin_amdgcn_s_barrier()
; #define PG8_SCHED __builtin_amdgcn_sched_barrier(0)
; template <class Epi, class Sched>
; __device__ __forceinline__ void gemm_phase(PG8_LAS unsigned char* lds, const int lda, const int ldb, const Sched& S, const Epi& E) {
;     ...
;       PG8_STAGE(PG8_SB(0, 1), b2 + hstepB, voffB);
;       PG8_WAIT_V(6); PG8_BAR; PG8_MMA(1, 1, At, B1); PG8_BAR;
;       PG8_LDB(B0, 1, 0); PG8_SCHED; PG8_LDA(At, 1, 0); PG8_STAGE(PG8_SA(0, 1), a2 + hstepA, voffA);
;       PG8_WAIT_L(8); PG8_BAR; PG8_WAIT_L(0); PG8_MMA(0, 0, At, B0); PG8_BAR; PG8_SCHED;
;       PG8_LDB(B1, 1, 1); PG8_STAGE(PG8_SB(1, 0), b3, voffB);
;       PG8_BAR; PG8_WAIT_L(0); PG8_MMA(0, 1, At, B1); PG8_BAR;
;       PG8_LDA(At, 1, 1); PG8_STAGE(PG8_SA(1, 0), a3, voffA);
;       PG8_BAR; PG8_WAIT_L(0); PG8_MMA(1, 0, At, B0); PG8_BAR; PG8_SCHED;
	s_add_u32 s34, s12, 0x40000
	s_addc_u32 s35, s13, 0
	s_add_i32 s31, s33, s39
	v_lshl_add_u64 v[144:145], s[34:35], 0, v[134:135]
	s_mov_b32 m0, s31
	s_nop 0
	global_load_lds_dwordx4 v[144:145], off
	v_lshl_add_u64 v[144:145], s[34:35], 0, v[132:133]
	s_add_i32 m0, s31, 0x2000
	s_nop 0
	global_load_lds_dwordx4 v[144:145], off
	s_waitcnt vmcnt(6)
	s_barrier
	s_setprio 1
	v_mfma_f32_16x16x32_bf16 v[54:57], v[236:239], v[204:207], v[54:57]
	v_mfma_f32_16x16x32_bf16 v[50:53], v[244:247], v[204:207], v[50:53]
	v_mfma_f32_16x16x32_bf16 v[38:41], v[236:239], v[212:215], v[38:41]
	v_mfma_f32_16x16x32_bf16 v[34:37], v[244:247], v[212:215], v[34:37]
	v_mfma_f32_16x16x32_bf16 v[22:25], v[236:239], v[220:223], v[22:25]
	v_mfma_f32_16x16x32_bf16 v[18:21], v[244:247], v[220:223], v[18:21]
	v_mfma_f32_16x16x32_bf16 v[6:9], v[236:239], v[228:231], v[6:9]
	v_mfma_f32_16x16x32_bf16 v[2:5], v[244:247], v[228:231], v[2:5]
	v_mfma_f32_16x16x32_bf16 v[54:57], v[240:243], v[208:211], v[54:57]
	v_mfma_f32_16x16x32_bf16 v[50:53], v[248:251], v[208:211], v[50:53]
	v_mfma_f32_16x16x32_bf16 v[38:41], v[240:243], v[216:219], v[38:41]
	v_mfma_f32_16x16x32_bf16 v[34:37], v[248:251], v[216:219], v[34:37]
	v_mfma_f32_16x16x32_bf16 v[22:25], v[240:243], v[224:227], v[22:25]
	v_mfma_f32_16x16x32_bf16 v[18:21], v[248:251], v[224:227], v[18:21]
	v_mfma_f32_16x16x32_bf16 v[6:9], v[240:243], v[232:235], v[6:9]
	v_mfma_f32_16x16x32_bf16 v[2:5], v[248:251], v[232:235], v[2:5]
	s_setprio 0
	s_add_i32 s31, 0, 0x18000
	v_add_u32_e32 v173, s31, v131
	s_barrier
	ds_read_b128 v[144:147], v173
	ds_read_b128 v[148:151], v173 offset:1024
	ds_read_b128 v[152:155], v173 offset:2048
	ds_read_b128 v[200:203], v173 offset:3072
	s_add_u32 s24, s24, 0x40000
	s_addc_u32 s25, s25, 0
	s_mov_b32 m0, s42
	v_lshl_add_u64 v[236:237], s[24:25], 0, v[134:135]
	ds_read_b128 v[204:207], v172 offset:32768
	ds_read_b128 v[208:211], v172 offset:33792
	ds_read_b128 v[212:215], v172 offset:34816
	ds_read_b128 v[216:219], v172 offset:35840
	ds_read_b128 v[220:223], v172 offset:36864
	ds_read_b128 v[224:227], v172 offset:37888
	ds_read_b128 v[228:231], v172 offset:38912
	ds_read_b128 v[232:235], v172 offset:39936
	global_load_lds_dwordx4 v[236:237], off
	v_lshl_add_u64 v[236:237], s[24:25], 0, v[132:133]
	s_mov_b32 m0, s43
	s_nop 0
	global_load_lds_dwordx4 v[236:237], off
	s_waitcnt lgkmcnt(8)
	s_barrier
	s_waitcnt lgkmcnt(0)
	s_setprio 1
	v_mfma_f32_16x16x32_bf16 v[126:129], v[144:147], v[204:207], v[126:129]
	v_mfma_f32_16x16x32_bf16 v[122:125], v[152:155], v[204:207], v[122:125]
	v_mfma_f32_16x16x32_bf16 v[110:113], v[144:147], v[212:215], v[110:113]
	v_mfma_f32_16x16x32_bf16 v[106:109], v[152:155], v[212:215], v[106:109]
	v_mfma_f32_16x16x32_bf16 v[94:97], v[144:147], v[220:223], v[94:97]
	v_mfma_f32_16x16x32_bf16 v[90:93], v[152:155], v[220:223], v[90:93]
	v_mfma_f32_16x16x32_bf16 v[78:81], v[144:147], v[228:231], v[78:81]
	v_mfma_f32_16x16x32_bf16 v[74:77], v[152:155], v[228:231], v[74:77]
	v_mfma_f32_16x16x32_bf16 v[126:129], v[148:151], v[208:211], v[126:129]
	v_mfma_f32_16x16x32_bf16 v[122:125], v[200:203], v[208:211], v[122:125]
	v_mfma_f32_16x16x32_bf16 v[110:113], v[148:151], v[216:219], v[110:113]
	v_mfma_f32_16x16x32_bf16 v[106:109], v[200:203], v[216:219], v[106:109]
	v_mfma_f32_16x16x32_bf16 v[94:97], v[148:151], v[224:227], v[94:97]
	v_mfma_f32_16x16x32_bf16 v[90:93], v[200:203], v[224:227], v[90:93]
	v_mfma_f32_16x16x32_bf16 v[78:81], v[148:151], v[232:235], v[78:81]
	v_mfma_f32_16x16x32_bf16 v[74:77], v[200:203], v[232:235], v[74:77]
	s_setprio 0
	s_barrier
	s_add_i32 s24, 0, 0x1c000
	s_add_i32 s25, s31, s39
	v_add_u32_e32 v173, s24, v131
	v_lshl_add_u64 v[156:157], v[156:157], 0, s[86:87]
	s_mov_b32 m0, s25
	ds_read_b128 v[236:239], v173
	ds_read_b128 v[240:243], v173 offset:1024
	ds_read_b128 v[244:247], v173 offset:2048
	ds_read_b128 v[248:251], v173 offset:3072
	global_load_lds_dwordx4 v[156:157], off
	v_lshl_add_u64 v[156:157], v[174:175], 0, s[86:87]
	s_add_i32 m0, s25, 0x2000
	s_nop 0
	global_load_lds_dwordx4 v[156:157], off
	s_barrier
	s_waitcnt lgkmcnt(0)
	s_setprio 1
	v_mfma_f32_16x16x32_bf16 v[118:121], v[236:239], v[204:207], v[118:121]
	v_mfma_f32_16x16x32_bf16 v[114:117], v[244:247], v[204:207], v[114:117]
	v_mfma_f32_16x16x32_bf16 v[102:105], v[236:239], v[212:215], v[102:105]
	v_mfma_f32_16x16x32_bf16 v[98:101], v[244:247], v[212:215], v[98:101]
	v_mfma_f32_16x16x32_bf16 v[86:89], v[236:239], v[220:223], v[86:89]
	v_mfma_f32_16x16x32_bf16 v[82:85], v[244:247], v[220:223], v[82:85]
	v_mfma_f32_16x16x32_bf16 v[70:73], v[236:239], v[228:231], v[70:73]
	v_mfma_f32_16x16x32_bf16 v[66:69], v[244:247], v[228:231], v[66:69]
	v_mfma_f32_16x16x32_bf16 v[118:121], v[240:243], v[208:211], v[118:121]
	v_mfma_f32_16x16x32_bf16 v[114:117], v[248:251], v[208:211], v[114:117]
	v_mfma_f32_16x16x32_bf16 v[102:105], v[240:243], v[216:219], v[102:105]
	v_mfma_f32_16x16x32_bf16 v[98:101], v[248:251], v[216:219], v[98:101]
	v_mfma_f32_16x16x32_bf16 v[86:89], v[240:243], v[224:227], v[86:89]
	v_mfma_f32_16x16x32_bf16 v[82:85], v[248:251], v[224:227], v[82:85]
	v_mfma_f32_16x16x32_bf16 v[70:73], v[240:243], v[232:235], v[70:73]
	v_mfma_f32_16x16x32_bf16 v[66:69], v[248:251], v[232:235], v[66:69]
	s_setprio 0
	s_mov_b32 m0, s45
	v_lshl_add_u64 v[156:157], v[182:183], 0, s[86:87]
	s_barrier
	ds_read_b128 v[204:207], v172 offset:49152
	ds_read_b128 v[208:211], v172 offset:50176
	ds_read_b128 v[212:215], v172 offset:51200
	ds_read_b128 v[216:219], v172 offset:52224
	ds_read_b128 v[220:223], v172 offset:53248
	ds_read_b128 v[224:227], v172 offset:54272
	ds_read_b128 v[228:231], v172 offset:55296
	ds_read_b128 v[232:235], v172 offset:56320
	global_load_lds_dwordx4 v[156:157], off
	v_lshl_add_u64 v[156:157], v[184:185], 0, s[86:87]
	s_mov_b32 m0, s46
	s_nop 0
	global_load_lds_dwordx4 v[156:157], off
	s_barrier
; #define PG8_STAGE(bufoff, gbase, voff) do { _Pragma("unroll") for (int _i = 0; _i < 2; ++_i) \
;     __builtin_amdgcn_global_load_lds((const unsigned*)((const char*)(gbase) + (voff)[_i]), (PG8_LAS unsigned*)(lds + (bufoff) + ldsw + _i * 8192), 16, 0, 0); } while (0)
; template <class Epi, class Sched>
; __device__ __forceinline__ void gemm_phase(PG8_LAS unsigned char* lds, const int lda, const int ldb, const Sched& S, const Epi& E) {
;     ...
;       PG8_WAIT_L(8); PG8_BAR; PG8_WAIT_L(0); PG8_MMA(0, 0, At, B0); PG8_BAR; PG8_SCHED;
;       PG8_LDB(B1, 1, 1); PG8_STAGE(PG8_SB(1, 0), b3, voffB);
;       PG8_BAR; PG8_WAIT_L(0); PG8_MMA(0, 1, At, B1); PG8_BAR;
;       PG8_LDA(At, 1, 1); PG8_STAGE(PG8_SA(1, 0), a3, voffA);
;       PG8_BAR; PG8_WAIT_L(0); PG8_MMA(1, 0, At, B0); PG8_BAR; PG8_SCHED;
;       PG8_STAGE(PG8_SB(1, 1), b3 + hstepB, voffB);
;       PG8_WAIT_V(6); PG8_BAR; PG8_MMA(1, 1, At, B1); PG8_BAR;
;     }
;   __device__ __forceinline__ void operator()(const f32x4 (&acc)[2][2][4][2], const Unit& u, int wr, int wc, int fr, int fq) const {
;     ...
;             const f32x4 v = acc[ai][bj][m][n];
;             const int c = u.pn * 256 + bj * 128 + wc * 32 + n * 16 + 4 * fq;
;             if (u.pn < 7) {
;               uint2 w; w.x = pack2(v[0], v[1]); w.y = pack2(v[2], v[3]);
;               *reinterpret_cast<uint2*>(PB + (size_t)r * PBW + c) = w;
;             } else {
;               const int nn = c - 1792, part = nn >> 8, ch = nn & 255;
;               if (u.pn == 7 && bj == 0 && wc == 1 && n == 1) {
;                 *reinterpret_cast<float4*>(AB + (size_t)r * 16 + 4 * fq) = make_float4(v[0], v[1], v[2], v[3]);
;               } else {
;                 u16* d; int cstride;
;                 if (r < ML) { const int b = r >> 11, tt = r & 2047; d = FT + ((size_t)(b * 256)) * 4096 + part * 2048 + tt; cstride = 4096; }
;                 else { const int rc = r - ML, b = rc >> 8, tt = rc & 255; d = FTC + ((size_t)(b * 256)) * 512 + part * 256 + tt; cstride = 512; }
; #pragma unroll
;                 for (int e = 0; e < 4; ++e) d[(size_t)(ch + e) * cstride] = f2bf(v[e]);
;                 if (u.pn == 7 && bj == 0 && wc == 0) {
; #pragma unroll
;                   for (int e = 0; e < 4; ++e) {
;                     const int kc = n * 16 + 4 * fq + e;
;                     if (kc >= 1 && kc <= 16) d[(size_t)(64 - kc) * cstride] = f2bf(v[e]);
	s_waitcnt lgkmcnt(0)
	s_setprio 1
	v_mfma_f32_16x16x32_bf16 v[62:65], v[144:147], v[204:207], v[62:65]
	v_mfma_f32_16x16x32_bf16 v[58:61], v[152:155], v[204:207], v[58:61]
	v_mfma_f32_16x16x32_bf16 v[46:49], v[144:147], v[212:215], v[46:49]
	v_mfma_f32_16x16x32_bf16 v[42:45], v[152:155], v[212:215], v[42:45]
	v_mfma_f32_16x16x32_bf16 v[30:33], v[144:147], v[220:223], v[30:33]
	v_mfma_f32_16x16x32_bf16 v[26:29], v[152:155], v[220:223], v[26:29]
	v_mfma_f32_16x16x32_bf16 v[14:17], v[144:147], v[228:231], v[14:17]
	v_mfma_f32_16x16x32_bf16 v[10:13], v[152:155], v[228:231], v[10:13]
	v_mfma_f32_16x16x32_bf16 v[62:65], v[148:151], v[208:211], v[62:65]
	v_mfma_f32_16x16x32_bf16 v[58:61], v[200:203], v[208:211], v[58:61]
	v_mfma_f32_16x16x32_bf16 v[46:49], v[148:151], v[216:219], v[46:49]
	v_mfma_f32_16x16x32_bf16 v[42:45], v[200:203], v[216:219], v[42:45]
	v_mfma_f32_16x16x32_bf16 v[30:33], v[148:151], v[224:227], v[30:33]
	v_mfma_f32_16x16x32_bf16 v[26:29], v[200:203], v[224:227], v[26:29]
	v_mfma_f32_16x16x32_bf16 v[14:17], v[148:151], v[232:235], v[14:17]
	v_mfma_f32_16x16x32_bf16 v[10:13], v[200:203], v[232:235], v[10:13]
	s_setprio 0
	s_barrier
	s_add_u32 s12, s12, 0x40080
	s_addc_u32 s13, s13, 0
	s_add_i32 s24, s24, s39
	v_lshl_add_u64 v[144:145], s[12:13], 0, v[134:135]
	s_mov_b32 m0, s24
	s_nop 0
	global_load_lds_dwordx4 v[144:145], off
	v_lshl_add_u64 v[144:145], s[12:13], 0, v[132:133]
	s_add_i32 m0, s24, 0x2000
	s_nop 0
	global_load_lds_dwordx4 v[144:145], off
	s_waitcnt vmcnt(6)
	s_barrier
	s_setprio 1
	v_mfma_f32_16x16x32_bf16 v[54:57], v[236:239], v[204:207], v[54:57]
	v_mfma_f32_16x16x32_bf16 v[50:53], v[244:247], v[204:207], v[50:53]
	v_mfma_f32_16x16x32_bf16 v[38:41], v[236:239], v[212:215], v[38:41]
	v_mfma_f32_16x16x32_bf16 v[34:37], v[244:247], v[212:215], v[34:37]
	v_mfma_f32_16x16x32_bf16 v[22:25], v[236:239], v[220:223], v[22:25]
	v_mfma_f32_16x16x32_bf16 v[18:21], v[244:247], v[220:223], v[18:21]
	v_mfma_f32_16x16x32_bf16 v[6:9], v[236:239], v[228:231], v[6:9]
	v_mfma_f32_16x16x32_bf16 v[2:5], v[244:247], v[228:231], v[2:5]
	v_mfma_f32_16x16x32_bf16 v[54:57], v[240:243], v[208:211], v[54:57]
	v_mfma_f32_16x16x32_bf16 v[50:53], v[248:251], v[208:211], v[50:53]
	v_mfma_f32_16x16x32_bf16 v[38:41], v[240:243], v[216:219], v[38:41]
	v_mfma_f32_16x16x32_bf16 v[34:37], v[248:251], v[216:219], v[34:37]
	v_mfma_f32_16x16x32_bf16 v[22:25], v[240:243], v[224:227], v[22:25]
	v_mfma_f32_16x16x32_bf16 v[18:21], v[248:251], v[224:227], v[18:21]
	v_mfma_f32_16x16x32_bf16 v[6:9], v[240:243], v[232:235], v[6:9]
	v_mfma_f32_16x16x32_bf16 v[2:5], v[248:251], v[232:235], v[2:5]
	s_setprio 0
	s_add_i32 s30, s30, 2
	s_add_u32 s10, s10, 0x100
	s_addc_u32 s11, s11, 0
	s_add_u32 s28, s28, 0x100
	s_addc_u32 s29, s29, 0
	s_cmp_gt_u32 s30, 13
	s_barrier
	s_cbranch_scc0 .LBB0_685
	s_lshl_b32 s17, s2, 8
	s_add_i32 s17, s17, s44
	v_or_b32_e32 v152, s17, v1
	s_mov_b32 s2, 0xffff
	v_cmp_lt_i32_e64 s[12:13], s2, v152
	s_and_b32 s2, s17, 0xffffff00
	s_add_i32 s2, s2, 0xffff0000
	s_lshl_b64 s[28:29], s[2:3], 10
	s_ashr_i32 s2, s17, 3
	s_and_b32 s10, s2, 0xffffff00
	s_ashr_i32 s11, s10, 31
	s_lshl_b64 s[26:27], s[10:11], 13
	s_lshl_b32 s24, s48, 8
	s_cmp_gt_i32 s48, 6
	s_cselect_b64 s[30:31], -1, 0
	v_bitop3_b32 v146, s17, v186, v1 bitop3:0xc8
	v_bitop3_b32 v148, s17, v187, v1 bitop3:0xc8
	s_mov_b64 s[10:11], -1
	s_and_b64 vcc, exec, s[30:31]
	s_cbranch_vccz .LBB0_696
	s_and_saveexec_b64 s[10:11], s[12:13]
	s_xor_b64 s[10:11], exec, s[10:11]
	s_add_u32 s34, s54, s28
	s_addc_u32 s35, s55, s29
	s_or_saveexec_b64 s[10:11], s[10:11]
	s_add_i32 s2, s24, 0xfffff900
	v_mov_b64_e32 v[144:145], 0x200
	v_mov_b32_e32 v150, s2
	v_mov_b64_e32 v[154:155], s[34:35]
	v_mov_b64_e32 v[156:157], v[146:147]
	s_xor_b64 exec, exec, s[10:11]
	s_add_u32 s34, s69, s26
	s_addc_u32 s35, s52, s27
	s_lshl_b32 s2, s2, 3
	v_mov_b64_e32 v[144:145], 0x1000
	v_mov_b32_e32 v150, s2
	v_mov_b64_e32 v[154:155], s[34:35]
	v_mov_b64_e32 v[156:157], v[148:149]
	s_or_b64 exec, exec, s[10:11]
	v_ashrrev_i32_e32 v151, 31, v150
	v_lshl_add_u64 v[150:151], v[150:151], 1, v[154:155]
	v_lshlrev_b32_e32 v154, 1, v156
	v_mov_b32_e32 v155, v0
	v_mul_u32_u24_e32 v145, v144, v136
	v_lshl_add_u64 v[150:151], v[150:151], 0, v[154:155]
	v_lshlrev_b32_e32 v154, 1, v145
	v_cvt_pk_bf16_f32 v149, v126, s0
	v_lshl_add_u64 v[154:155], v[150:151], 0, v[154:155]
	v_mul_u32_u24_e32 v147, v144, v166
	global_store_short v[154:155], v149, off
	v_lshlrev_b32_e32 v154, 1, v147
	v_mov_b32_e32 v155, v0
	v_cvt_pk_bf16_f32 v145, v127, s0
	v_lshl_add_u64 v[154:155], v[150:151], 0, v[154:155]
	v_mul_u32_u24_e32 v153, v144, v167
	global_store_short v[154:155], v145, off
	v_lshlrev_b32_e32 v154, 1, v153
	v_mov_b32_e32 v155, v0
	s_cmp_lg_u32 s48, 7
	v_cvt_pk_bf16_f32 v147, v128, s0
	v_lshl_add_u64 v[154:155], v[150:151], 0, v[154:155]
	s_cselect_b64 s[10:11], -1, 0
	global_store_short v[154:155], v147, off
	v_mul_u32_u24_e32 v154, v144, v168
	s_xor_b64 s[34:35], s[14:15], -1
	v_lshlrev_b32_e32 v154, 1, v154
	v_mov_b32_e32 v155, v0
	s_or_b64 s[10:11], s[34:35], s[10:11]
	v_cvt_pk_bf16_f32 v153, v129, s0
	v_lshl_add_u64 v[154:155], v[150:151], 0, v[154:155]
	s_and_b64 vcc, exec, s[10:11]
	global_store_short v[154:155], v153, off
	s_cbranch_vccnz .LBB0_695
	s_and_saveexec_b64 s[10:11], s[4:5]
	s_cbranch_execz .LBB0_694
	v_mul_u32_u24_e32 v154, v144, v158
	v_lshlrev_b32_e32 v154, 1, v154
	v_mov_b32_e32 v155, v0
	v_lshl_add_u64 v[154:155], v[150:151], 0, v[154:155]
	global_store_short v[154:155], v149, off

; #define PG8_STAGE(bufoff, gbase, voff) do { _Pragma("unroll") for (int _i = 0; _i < 2; ++_i) \
;     __builtin_amdgcn_global_load_lds((const unsigned*)((const char*)(gbase) + (voff)[_i]), (PG8_LAS unsigned*)(lds + (bufoff) + ldsw + _i * 8192), 16, 0, 0); } while (0)
; #define PG8_LDA(dst, b, h) do { _Pragma("unroll") for (int m = 0; m < 4; ++m) _Pragma("unroll") for (int k = 0; k < 2; ++k) dst[m][k] = *(const PG8_LAS bf16x8*)(lds + PG8_SA(b, h) + aoff + m * 2048 + k * 1024); } while (0)
; #define PG8_LDB(dst, b, h) do { _Pragma("unroll") for (int n = 0; n < 2; ++n) _Pragma("unroll") for (int k = 0; k < 2; ++k) dst[n][k] = *(const PG8_LAS bf16x8*)(lds + PG8_SB(b, h) + boff + n * 2048 + k * 1024); } while (0)
; #define PG8_MMA(ai, bj, At, Bt) do { __builtin_amdgcn_s_setprio(1); _Pragma("unroll") for (int m = 0; m < 4; ++m) _Pragma("unroll") for (int n = 0; n < 2; ++n) _Pragma("unroll") for (int k = 0; k < 2; ++k) \
;     acc[ai][bj][m][n] = __builtin_amdgcn_mfma_f32_16x16x32_bf16(Bt[n][k], At[m][k], acc[ai][bj][m][n], 0, 0, 0); __builtin_amdgcn_s_setprio(0); } while (0)
; #define PG8_WAIT_V(n) asm volatile("s_waitcnt vmcnt(" #n ")" ::: "memory")
; #define PG8_WAIT_L(n) asm volatile("s_waitcnt lgkmcnt(" #n ")" ::: "memory")
; #define PG8_BAR __builtin_amdgcn_s_barrier()
; template <class Epi, class Sched>
; __device__ __forceinline__ void gemm_phase(PG8_LAS unsigned char* lds, const int lda, const int ldb, const Sched& S, const Epi& E) {
;     ...
;     for (int t = 0; t < nt; t += 2) {
;       const bool last = (t == nt - 2);
;       const char* a1 = cA + (size_t)(t + 1) * kstep;
;       const char* a2 = last ? nA : cA + (size_t)(t + 2) * kstep; const char* b2 = last ? nB : cB + (size_t)(t + 2) * kstep;
;       const char* a3 = a2 + kstep; const char* b3 = b2 + kstep;
;       PG8_LDB(B0, 0, 0); PG8_SCHED; PG8_LDA(At, 0, 0); PG8_STAGE(PG8_SA(1, 1), a1 + hstepA, voffA);
;       PG8_WAIT_L(8); PG8_BAR; PG8_WAIT_L(0); PG8_MMA(0, 0, At, B0); PG8_BAR; PG8_SCHED;
;       PG8_LDB(B1, 0, 1); PG8_STAGE(PG8_SB(0, 0), b2, voffB);
;       PG8_BAR; PG8_WAIT_L(0); PG8_MMA(0, 1, At, B1); PG8_BAR;
;       PG8_LDA(At, 0, 1); PG8_STAGE(PG8_SA(0, 0), a2, voffA);
;       PG8_BAR; PG8_WAIT_L(0); PG8_MMA(1, 0, At, B0); PG8_BAR; PG8_SCHED;
;       PG8_STAGE(PG8_SB(0, 1), b2 + hstepB, voffB);
;       PG8_WAIT_V(6); PG8_BAR; PG8_MMA(1, 1, At, B1); PG8_BAR;
.LBB0_1088:
	s_add_u32 s16, s14, 0xfff00080
	s_addc_u32 s17, s15, -1
	s_add_i32 s33, 0, 0x10000
	v_add_u32_e32 v145, s33, v1
	ds_read_b128 v[152:155], v145
	ds_read_b128 v[156:159], v145 offset:1024
	ds_read_b128 v[160:163], v145 offset:2048
	ds_read_b128 v[164:167], v145 offset:3072
	s_cmp_eq_u32 s34, 60
	s_cselect_b32 s19, s7, s17
	s_cselect_b32 s18, s13, s16
	s_cselect_b32 s17, s1, s31
	s_cselect_b32 s16, s29, s30
	v_lshl_add_u64 v[182:183], s[14:15], 0, v[140:141]
	s_add_i32 m0, s21, 0xc000
	ds_read_b128 v[168:171], v131
	ds_read_b128 v[172:175], v131 offset:1024
	ds_read_b128 v[200:203], v131 offset:2048
	ds_read_b128 v[204:207], v131 offset:3072
	ds_read_b128 v[208:211], v131 offset:4096
	ds_read_b128 v[212:215], v131 offset:5120
	ds_read_b128 v[216:219], v131 offset:6144
	ds_read_b128 v[220:223], v131 offset:7168
	global_load_lds_dwordx4 v[182:183], off
	v_lshl_add_u64 v[182:183], s[14:15], 0, v[142:143]
	s_add_i32 m0, s21, 0xe000
	s_nop 0
	global_load_lds_dwordx4 v[182:183], off
	s_waitcnt lgkmcnt(8)
	s_barrier
	s_waitcnt lgkmcnt(0)
	s_setprio 1
	v_mfma_f32_16x16x32_bf16 v[126:129], v[152:155], v[168:171], v[126:129]
	v_mfma_f32_16x16x32_bf16 v[122:125], v[160:163], v[168:171], v[122:125]
	v_mfma_f32_16x16x32_bf16 v[118:121], v[152:155], v[200:203], v[118:121]
	v_mfma_f32_16x16x32_bf16 v[114:117], v[160:163], v[200:203], v[114:117]
	v_mfma_f32_16x16x32_bf16 v[102:105], v[152:155], v[208:211], v[102:105]
	v_mfma_f32_16x16x32_bf16 v[98:101], v[160:163], v[208:211], v[98:101]
	v_mfma_f32_16x16x32_bf16 v[86:89], v[152:155], v[216:219], v[86:89]
	v_mfma_f32_16x16x32_bf16 v[82:85], v[160:163], v[216:219], v[82:85]
	v_mfma_f32_16x16x32_bf16 v[126:129], v[156:159], v[172:175], v[126:129]
	v_mfma_f32_16x16x32_bf16 v[122:125], v[164:167], v[172:175], v[122:125]
	v_mfma_f32_16x16x32_bf16 v[118:121], v[156:159], v[204:207], v[118:121]
	v_mfma_f32_16x16x32_bf16 v[114:117], v[164:167], v[204:207], v[114:117]
	v_mfma_f32_16x16x32_bf16 v[102:105], v[156:159], v[212:215], v[102:105]
	v_mfma_f32_16x16x32_bf16 v[98:101], v[164:167], v[212:215], v[98:101]
	v_mfma_f32_16x16x32_bf16 v[86:89], v[156:159], v[220:223], v[86:89]
	v_mfma_f32_16x16x32_bf16 v[82:85], v[164:167], v[220:223], v[82:85]
	s_setprio 0
	s_barrier
	s_add_i32 s35, 0, 0x14000
	s_add_i32 s33, s33, s20
	v_add_u32_e32 v145, s35, v1
	v_lshl_add_u64 v[182:183], s[16:17], 0, v[134:135]
	s_mov_b32 m0, s33
	ds_read_b128 v[224:227], v145
	ds_read_b128 v[228:231], v145 offset:1024
	ds_read_b128 v[232:235], v145 offset:2048
	ds_read_b128 v[236:239], v145 offset:3072
	global_load_lds_dwordx4 v[182:183], off
	v_lshl_add_u64 v[184:185], s[16:17], 0, v[132:133]
	s_add_i32 m0, s33, 0x2000
	s_nop 0
	global_load_lds_dwordx4 v[184:185], off
	s_barrier
	s_waitcnt lgkmcnt(0)
	s_setprio 1
	v_mfma_f32_16x16x32_bf16 v[110:113], v[224:227], v[168:171], v[110:113]
	v_mfma_f32_16x16x32_bf16 v[106:109], v[232:235], v[168:171], v[106:109]
	v_mfma_f32_16x16x32_bf16 v[94:97], v[224:227], v[200:203], v[94:97]
	v_mfma_f32_16x16x32_bf16 v[90:93], v[232:235], v[200:203], v[90:93]
	v_mfma_f32_16x16x32_bf16 v[78:81], v[224:227], v[208:211], v[78:81]
	v_mfma_f32_16x16x32_bf16 v[74:77], v[232:235], v[208:211], v[74:77]
	v_mfma_f32_16x16x32_bf16 v[70:73], v[224:227], v[216:219], v[70:73]
	v_mfma_f32_16x16x32_bf16 v[66:69], v[232:235], v[216:219], v[66:69]
	v_mfma_f32_16x16x32_bf16 v[110:113], v[228:231], v[172:175], v[110:113]
	v_mfma_f32_16x16x32_bf16 v[106:109], v[236:239], v[172:175], v[106:109]
	v_mfma_f32_16x16x32_bf16 v[94:97], v[228:231], v[204:207], v[94:97]
	v_mfma_f32_16x16x32_bf16 v[90:93], v[236:239], v[204:207], v[90:93]
	v_mfma_f32_16x16x32_bf16 v[78:81], v[228:231], v[212:215], v[78:81]
	v_mfma_f32_16x16x32_bf16 v[74:77], v[236:239], v[212:215], v[74:77]
	v_mfma_f32_16x16x32_bf16 v[70:73], v[228:231], v[220:223], v[70:73]
	v_mfma_f32_16x16x32_bf16 v[66:69], v[236:239], v[220:223], v[66:69]
	s_setprio 0
	s_mov_b32 m0, s21
	v_lshl_add_u64 v[240:241], s[18:19], 0, v[134:135]
	s_barrier
	ds_read_b128 v[168:171], v131 offset:16384
	ds_read_b128 v[172:175], v131 offset:17408
	ds_read_b128 v[200:203], v131 offset:18432
	ds_read_b128 v[204:207], v131 offset:19456
	ds_read_b128 v[208:211], v131 offset:20480
	ds_read_b128 v[212:215], v131 offset:21504
	ds_read_b128 v[216:219], v131 offset:22528
	ds_read_b128 v[220:223], v131 offset:23552
	global_load_lds_dwordx4 v[240:241], off
	v_lshl_add_u64 v[242:243], s[18:19], 0, v[132:133]
	s_mov_b32 m0, s22
	s_nop 0
	global_load_lds_dwordx4 v[242:243], off
	s_barrier
	s_waitcnt lgkmcnt(0)
	s_setprio 1
	v_mfma_f32_16x16x32_bf16 v[62:65], v[152:155], v[168:171], v[62:65]
	v_mfma_f32_16x16x32_bf16 v[58:61], v[160:163], v[168:171], v[58:61]
	v_mfma_f32_16x16x32_bf16 v[54:57], v[152:155], v[200:203], v[54:57]
	v_mfma_f32_16x16x32_bf16 v[46:49], v[160:163], v[200:203], v[46:49]
	v_mfma_f32_16x16x32_bf16 v[38:41], v[152:155], v[208:211], v[38:41]
	v_mfma_f32_16x16x32_bf16 v[34:37], v[160:163], v[208:211], v[34:37]
	v_mfma_f32_16x16x32_bf16 v[22:25], v[152:155], v[216:219], v[22:25]
	v_mfma_f32_16x16x32_bf16 v[18:21], v[160:163], v[216:219], v[18:21]
	v_mfma_f32_16x16x32_bf16 v[62:65], v[156:159], v[172:175], v[62:65]
	v_mfma_f32_16x16x32_bf16 v[58:61], v[164:167], v[172:175], v[58:61]
	v_mfma_f32_16x16x32_bf16 v[54:57], v[156:159], v[204:207], v[54:57]
	v_mfma_f32_16x16x32_bf16 v[46:49], v[164:167], v[204:207], v[46:49]
	v_mfma_f32_16x16x32_bf16 v[38:41], v[156:159], v[212:215], v[38:41]
	v_mfma_f32_16x16x32_bf16 v[34:37], v[164:167], v[212:215], v[34:37]
	v_mfma_f32_16x16x32_bf16 v[22:25], v[156:159], v[220:223], v[22:25]
	v_mfma_f32_16x16x32_bf16 v[18:21], v[164:167], v[220:223], v[18:21]
	s_setprio 0
	s_barrier
; #define PG8_STAGE(bufoff, gbase, voff) do { _Pragma("unroll") for (int _i = 0; _i < 2; ++_i) \
;     __builtin_amdgcn_global_load_lds((const unsigned*)((const char*)(gbase) + (voff)[_i]), (PG8_LAS unsigned*)(lds + (bufoff) + ldsw + _i * 8192), 16, 0, 0); } while (0)
; #define PG8_LDA(dst, b, h) do { _Pragma("unroll") for (int m = 0; m < 4; ++m) _Pragma("unroll") for (int k = 0; k < 2; ++k) dst[m][k] = *(const PG8_LAS bf16x8*)(lds + PG8_SA(b, h) + aoff + m * 2048 + k * 1024); } while (0)
; #define PG8_LDB(dst, b, h) do { _Pragma("unroll") for (int n = 0; n < 2; ++n) _Pragma("unroll") for (int k = 0; k < 2; ++k) dst[n][k] = *(const PG8_LAS bf16x8*)(lds + PG8_SB(b, h) + boff + n * 2048 + k * 1024); } while (0)
; #define PG8_MMA(ai, bj, At, Bt) do { __builtin_amdgcn_s_setprio(1); _Pragma("unroll") for (int m = 0; m < 4; ++m) _Pragma("unroll") for (int n = 0; n < 2; ++n) _Pragma("unroll") for (int k = 0; k < 2; ++k) \
;     acc[ai][bj][m][n] = __builtin_amdgcn_mfma_f32_16x16x32_bf16(Bt[n][k], At[m][k], acc[ai][bj][m][n], 0, 0, 0); __builtin_amdgcn_s_setprio(0); } while (0)
; #define PG8_WAIT_V(n) asm volatile("s_waitcnt vmcnt(" #n ")" ::: "memory")
; #define PG8_WAIT_L(n) asm volatile("s_waitcnt lgkmcnt(" #n ")" ::: "memory")
; #define PG8_BAR __builtin_amdgcn_s_barrier()
; #define PG8_SCHED __builtin_amdgcn_sched_barrier(0)
; template <class Epi, class Sched>
; __device__ __forceinline__ void gemm_phase(PG8_LAS unsigned char* lds, const int lda, const int ldb, const Sched& S, const Epi& E) {
;     ...
;       PG8_STAGE(PG8_SB(0, 1), b2 + hstepB, voffB);
;       PG8_WAIT_V(6); PG8_BAR; PG8_MMA(1, 1, At, B1); PG8_BAR;
;       PG8_LDB(B0, 1, 0); PG8_SCHED; PG8_LDA(At, 1, 0); PG8_STAGE(PG8_SA(0, 1), a2 + hstepA, voffA);
;       PG8_WAIT_L(8); PG8_BAR; PG8_WAIT_L(0); PG8_MMA(0, 0, At, B0); PG8_BAR; PG8_SCHED;
;       PG8_LDB(B1, 1, 1); PG8_STAGE(PG8_SB(1, 0), b3, voffB);
;       PG8_BAR; PG8_WAIT_L(0); PG8_MMA(0, 1, At, B1); PG8_BAR;
;       PG8_LDA(At, 1, 1); PG8_STAGE(PG8_SA(1, 0), a3, voffA);
;       PG8_BAR; PG8_WAIT_L(0); PG8_MMA(1, 0, At, B0); PG8_BAR; PG8_SCHED;
	s_add_u32 s36, s16, 0x100000
	s_addc_u32 s37, s17, 0
	s_add_i32 s33, s35, s20
	v_lshl_add_u64 v[152:153], s[36:37], 0, v[134:135]
	s_mov_b32 m0, s33
	s_nop 0
	global_load_lds_dwordx4 v[152:153], off
	v_lshl_add_u64 v[152:153], s[36:37], 0, v[132:133]
	s_add_i32 m0, s33, 0x2000
	s_nop 0
	global_load_lds_dwordx4 v[152:153], off
	s_waitcnt vmcnt(6)
	s_barrier
	s_setprio 1
	v_mfma_f32_16x16x32_bf16 v[50:53], v[224:227], v[168:171], v[50:53]
	v_mfma_f32_16x16x32_bf16 v[42:45], v[232:235], v[168:171], v[42:45]
	v_mfma_f32_16x16x32_bf16 v[30:33], v[224:227], v[200:203], v[30:33]
	v_mfma_f32_16x16x32_bf16 v[26:29], v[232:235], v[200:203], v[26:29]
	v_mfma_f32_16x16x32_bf16 v[14:17], v[224:227], v[208:211], v[14:17]
	v_mfma_f32_16x16x32_bf16 v[10:13], v[232:235], v[208:211], v[10:13]
	v_mfma_f32_16x16x32_bf16 v[6:9], v[224:227], v[216:219], v[6:9]
	v_mfma_f32_16x16x32_bf16 v[2:5], v[232:235], v[216:219], v[2:5]
	v_mfma_f32_16x16x32_bf16 v[50:53], v[228:231], v[172:175], v[50:53]
	v_mfma_f32_16x16x32_bf16 v[42:45], v[236:239], v[172:175], v[42:45]
	v_mfma_f32_16x16x32_bf16 v[30:33], v[228:231], v[204:207], v[30:33]
	v_mfma_f32_16x16x32_bf16 v[26:29], v[236:239], v[204:207], v[26:29]
	v_mfma_f32_16x16x32_bf16 v[14:17], v[228:231], v[212:215], v[14:17]
	v_mfma_f32_16x16x32_bf16 v[10:13], v[236:239], v[212:215], v[10:13]
	v_mfma_f32_16x16x32_bf16 v[6:9], v[228:231], v[220:223], v[6:9]
	v_mfma_f32_16x16x32_bf16 v[2:5], v[236:239], v[220:223], v[2:5]
	s_setprio 0
	s_add_i32 s33, 0, 0x18000
	v_add_u32_e32 v145, s33, v1
	s_barrier
	ds_read_b128 v[152:155], v145
	ds_read_b128 v[156:159], v145 offset:1024
	ds_read_b128 v[160:163], v145 offset:2048
	ds_read_b128 v[164:167], v145 offset:3072
	s_add_u32 s18, s18, 0x100000
	s_addc_u32 s19, s19, 0
	s_mov_b32 m0, s23
	v_lshl_add_u64 v[224:225], s[18:19], 0, v[134:135]
	ds_read_b128 v[168:171], v131 offset:32768
	ds_read_b128 v[172:175], v131 offset:33792
	ds_read_b128 v[200:203], v131 offset:34816
	ds_read_b128 v[204:207], v131 offset:35840
	ds_read_b128 v[208:211], v131 offset:36864
	ds_read_b128 v[212:215], v131 offset:37888
	ds_read_b128 v[216:219], v131 offset:38912
	ds_read_b128 v[220:223], v131 offset:39936
	global_load_lds_dwordx4 v[224:225], off
	v_lshl_add_u64 v[224:225], s[18:19], 0, v[132:133]
	s_mov_b32 m0, s24
	s_nop 0
	global_load_lds_dwordx4 v[224:225], off
	s_waitcnt lgkmcnt(8)
	s_barrier
	s_waitcnt lgkmcnt(0)
	s_setprio 1
	v_mfma_f32_16x16x32_bf16 v[126:129], v[152:155], v[168:171], v[126:129]
	v_mfma_f32_16x16x32_bf16 v[122:125], v[160:163], v[168:171], v[122:125]
	v_mfma_f32_16x16x32_bf16 v[118:121], v[152:155], v[200:203], v[118:121]
	v_mfma_f32_16x16x32_bf16 v[114:117], v[160:163], v[200:203], v[114:117]
	v_mfma_f32_16x16x32_bf16 v[102:105], v[152:155], v[208:211], v[102:105]
	v_mfma_f32_16x16x32_bf16 v[98:101], v[160:163], v[208:211], v[98:101]
	v_mfma_f32_16x16x32_bf16 v[86:89], v[152:155], v[216:219], v[86:89]
	v_mfma_f32_16x16x32_bf16 v[82:85], v[160:163], v[216:219], v[82:85]
	v_mfma_f32_16x16x32_bf16 v[126:129], v[156:159], v[172:175], v[126:129]
	v_mfma_f32_16x16x32_bf16 v[122:125], v[164:167], v[172:175], v[122:125]
	v_mfma_f32_16x16x32_bf16 v[118:121], v[156:159], v[204:207], v[118:121]
	v_mfma_f32_16x16x32_bf16 v[114:117], v[164:167], v[204:207], v[114:117]
	v_mfma_f32_16x16x32_bf16 v[102:105], v[156:159], v[212:215], v[102:105]
	v_mfma_f32_16x16x32_bf16 v[98:101], v[164:167], v[212:215], v[98:101]
	v_mfma_f32_16x16x32_bf16 v[86:89], v[156:159], v[220:223], v[86:89]
	v_mfma_f32_16x16x32_bf16 v[82:85], v[164:167], v[220:223], v[82:85]
	s_setprio 0
	s_barrier
	s_add_i32 s18, 0, 0x1c000
	s_add_i32 s19, s33, s20
	v_add_u32_e32 v145, s18, v1
	v_lshl_add_u64 v[182:183], v[182:183], 0, s[86:87]
	s_mov_b32 m0, s19
	ds_read_b128 v[224:227], v145
	ds_read_b128 v[228:231], v145 offset:1024
	ds_read_b128 v[232:235], v145 offset:2048
	ds_read_b128 v[236:239], v145 offset:3072
	global_load_lds_dwordx4 v[182:183], off
	v_lshl_add_u64 v[182:183], v[184:185], 0, s[86:87]
	s_add_i32 m0, s19, 0x2000
	s_nop 0
	global_load_lds_dwordx4 v[182:183], off
	s_barrier
	s_waitcnt lgkmcnt(0)
	s_setprio 1
	v_mfma_f32_16x16x32_bf16 v[110:113], v[224:227], v[168:171], v[110:113]
	v_mfma_f32_16x16x32_bf16 v[106:109], v[232:235], v[168:171], v[106:109]
	v_mfma_f32_16x16x32_bf16 v[94:97], v[224:227], v[200:203], v[94:97]
	v_mfma_f32_16x16x32_bf16 v[90:93], v[232:235], v[200:203], v[90:93]
	v_mfma_f32_16x16x32_bf16 v[78:81], v[224:227], v[208:211], v[78:81]
	v_mfma_f32_16x16x32_bf16 v[74:77], v[232:235], v[208:211], v[74:77]
	v_mfma_f32_16x16x32_bf16 v[70:73], v[224:227], v[216:219], v[70:73]
	v_mfma_f32_16x16x32_bf16 v[66:69], v[232:235], v[216:219], v[66:69]
	v_mfma_f32_16x16x32_bf16 v[110:113], v[228:231], v[172:175], v[110:113]
	v_mfma_f32_16x16x32_bf16 v[106:109], v[236:239], v[172:175], v[106:109]
	v_mfma_f32_16x16x32_bf16 v[94:97], v[228:231], v[204:207], v[94:97]
	v_mfma_f32_16x16x32_bf16 v[90:93], v[236:239], v[204:207], v[90:93]
	v_mfma_f32_16x16x32_bf16 v[78:81], v[228:231], v[212:215], v[78:81]
	v_mfma_f32_16x16x32_bf16 v[74:77], v[236:239], v[212:215], v[74:77]
	v_mfma_f32_16x16x32_bf16 v[70:73], v[228:231], v[220:223], v[70:73]
	v_mfma_f32_16x16x32_bf16 v[66:69], v[236:239], v[220:223], v[66:69]
	s_setprio 0
	s_mov_b32 m0, s25
	v_lshl_add_u64 v[182:183], v[240:241], 0, s[86:87]
	s_barrier
	ds_read_b128 v[168:171], v131 offset:49152
	ds_read_b128 v[172:175], v131 offset:50176
	ds_read_b128 v[200:203], v131 offset:51200
	ds_read_b128 v[204:207], v131 offset:52224
	ds_read_b128 v[208:211], v131 offset:53248
	ds_read_b128 v[212:215], v131 offset:54272
	ds_read_b128 v[216:219], v131 offset:55296
	ds_read_b128 v[220:223], v131 offset:56320
	global_load_lds_dwordx4 v[182:183], off
	v_lshl_add_u64 v[182:183], v[242:243], 0, s[86:87]
	s_mov_b32 m0, s26
	s_nop 0
	global_load_lds_dwordx4 v[182:183], off
	s_barrier
; #define PG8_STAGE(bufoff, gbase, voff) do { _Pragma("unroll") for (int _i = 0; _i < 2; ++_i) \
;     __builtin_amdgcn_global_load_lds((const unsigned*)((const char*)(gbase) + (voff)[_i]), (PG8_LAS unsigned*)(lds + (bufoff) + ldsw + _i * 8192), 16, 0, 0); } while (0)
; #define PG8_LDA(dst, b, h) do { _Pragma("unroll") for (int m = 0; m < 4; ++m) _Pragma("unroll") for (int k = 0; k < 2; ++k) dst[m][k] = *(const PG8_LAS bf16x8*)(lds + PG8_SA(b, h) + aoff + m * 2048 + k * 1024); } while (0)
; #define PG8_LDB(dst, b, h) do { _Pragma("unroll") for (int n = 0; n < 2; ++n) _Pragma("unroll") for (int k = 0; k < 2; ++k) dst[n][k] = *(const PG8_LAS bf16x8*)(lds + PG8_SB(b, h) + boff + n * 2048 + k * 1024); } while (0)
; #define PG8_MMA(ai, bj, At, Bt) do { __builtin_amdgcn_s_setprio(1); _Pragma("unroll") for (int m = 0; m < 4; ++m) _Pragma("unroll") for (int n = 0; n < 2; ++n) _Pragma("unroll") for (int k = 0; k < 2; ++k) \
;     acc[ai][bj][m][n] = __builtin_amdgcn_mfma_f32_16x16x32_bf16(Bt[n][k], At[m][k], acc[ai][bj][m][n], 0, 0, 0); __builtin_amdgcn_s_setprio(0); } while (0)
; #define PG8_WAIT_V(n) asm volatile("s_waitcnt vmcnt(" #n ")" ::: "memory")
; #define PG8_WAIT_L(n) asm volatile("s_waitcnt lgkmcnt(" #n ")" ::: "memory")
; #define PG8_BAR __builtin_amdgcn_s_barrier()
; #define PG8_SCHED __builtin_amdgcn_sched_barrier(0)
; template <class Epi, class Sched>
; __device__ __forceinline__ void gemm_phase(PG8_LAS unsigned char* lds, const int lda, const int ldb, const Sched& S, const Epi& E) {
;     ...
;       PG8_WAIT_L(8); PG8_BAR; PG8_WAIT_L(0); PG8_MMA(0, 0, At, B0); PG8_BAR; PG8_SCHED;
;       PG8_LDB(B1, 1, 1); PG8_STAGE(PG8_SB(1, 0), b3, voffB);
;       PG8_BAR; PG8_WAIT_L(0); PG8_MMA(0, 1, At, B1); PG8_BAR;
;       PG8_LDA(At, 1, 1); PG8_STAGE(PG8_SA(1, 0), a3, voffA);
;       PG8_BAR; PG8_WAIT_L(0); PG8_MMA(1, 0, At, B0); PG8_BAR; PG8_SCHED;
;       PG8_STAGE(PG8_SB(1, 1), b3 + hstepB, voffB);
;       PG8_WAIT_V(6); PG8_BAR; PG8_MMA(1, 1, At, B1); PG8_BAR;
;     }
	s_waitcnt lgkmcnt(0)
	s_setprio 1
	v_mfma_f32_16x16x32_bf16 v[62:65], v[152:155], v[168:171], v[62:65]
	v_mfma_f32_16x16x32_bf16 v[58:61], v[160:163], v[168:171], v[58:61]
	v_mfma_f32_16x16x32_bf16 v[54:57], v[152:155], v[200:203], v[54:57]
	v_mfma_f32_16x16x32_bf16 v[46:49], v[160:163], v[200:203], v[46:49]
	v_mfma_f32_16x16x32_bf16 v[38:41], v[152:155], v[208:211], v[38:41]
	v_mfma_f32_16x16x32_bf16 v[34:37], v[160:163], v[208:211], v[34:37]
	v_mfma_f32_16x16x32_bf16 v[22:25], v[152:155], v[216:219], v[22:25]
	v_mfma_f32_16x16x32_bf16 v[18:21], v[160:163], v[216:219], v[18:21]
	v_mfma_f32_16x16x32_bf16 v[62:65], v[156:159], v[172:175], v[62:65]
	v_mfma_f32_16x16x32_bf16 v[58:61], v[164:167], v[172:175], v[58:61]
	v_mfma_f32_16x16x32_bf16 v[54:57], v[156:159], v[204:207], v[54:57]
	v_mfma_f32_16x16x32_bf16 v[46:49], v[164:167], v[204:207], v[46:49]
	v_mfma_f32_16x16x32_bf16 v[38:41], v[156:159], v[212:215], v[38:41]
	v_mfma_f32_16x16x32_bf16 v[34:37], v[164:167], v[212:215], v[34:37]
	v_mfma_f32_16x16x32_bf16 v[22:25], v[156:159], v[220:223], v[22:25]
	v_mfma_f32_16x16x32_bf16 v[18:21], v[164:167], v[220:223], v[18:21]
	s_setprio 0
	s_barrier
	s_add_u32 s16, s16, 0x100080
	s_addc_u32 s17, s17, 0
	s_add_i32 s18, s18, s20
	v_lshl_add_u64 v[152:153], s[16:17], 0, v[134:135]
	s_mov_b32 m0, s18
	s_nop 0
	global_load_lds_dwordx4 v[152:153], off
	v_lshl_add_u64 v[152:153], s[16:17], 0, v[132:133]
	s_add_i32 m0, s18, 0x2000
	s_nop 0
	global_load_lds_dwordx4 v[152:153], off
	s_waitcnt vmcnt(6)
	s_barrier
	s_setprio 1
	v_mfma_f32_16x16x32_bf16 v[50:53], v[224:227], v[168:171], v[50:53]
	v_mfma_f32_16x16x32_bf16 v[42:45], v[232:235], v[168:171], v[42:45]
	v_mfma_f32_16x16x32_bf16 v[30:33], v[224:227], v[200:203], v[30:33]
	v_mfma_f32_16x16x32_bf16 v[26:29], v[232:235], v[200:203], v[26:29]
	v_mfma_f32_16x16x32_bf16 v[14:17], v[224:227], v[208:211], v[14:17]
	v_mfma_f32_16x16x32_bf16 v[10:13], v[232:235], v[208:211], v[10:13]
	v_mfma_f32_16x16x32_bf16 v[6:9], v[224:227], v[216:219], v[6:9]
	v_mfma_f32_16x16x32_bf16 v[2:5], v[232:235], v[216:219], v[2:5]
	v_mfma_f32_16x16x32_bf16 v[50:53], v[228:231], v[172:175], v[50:53]
	v_mfma_f32_16x16x32_bf16 v[42:45], v[236:239], v[172:175], v[42:45]
	v_mfma_f32_16x16x32_bf16 v[30:33], v[228:231], v[204:207], v[30:33]
	v_mfma_f32_16x16x32_bf16 v[26:29], v[236:239], v[204:207], v[26:29]
	v_mfma_f32_16x16x32_bf16 v[14:17], v[228:231], v[212:215], v[14:17]
	v_mfma_f32_16x16x32_bf16 v[10:13], v[236:239], v[212:215], v[10:13]
	v_mfma_f32_16x16x32_bf16 v[6:9], v[228:231], v[220:223], v[6:9]
	v_mfma_f32_16x16x32_bf16 v[2:5], v[236:239], v[220:223], v[2:5]
	s_setprio 0
	s_add_i32 s34, s34, 2
	s_add_u32 s14, s14, 0x100
	s_addc_u32 s15, s15, 0
	s_add_u32 s30, s30, 0x100
	s_addc_u32 s31, s31, 0
	s_cmp_gt_u32 s34, 61
	s_barrier
	s_cbranch_scc0 .LBB0_1088
;   __device__ __forceinline__ void operator()(const f32x4 (&acc)[2][2][4][2], const Unit& u, int wr, int wc, int fr, int fq) const {
; #pragma unroll
;     for (int ai = 0; ai < 2; ++ai)
; #pragma unroll
;       for (int m = 0; m < 4; ++m) {
;         const size_t r = (size_t)rowbase + (size_t)u.pn * rows_per_b + u.pm * 256 + ai * 128 + wr * 64 + m * 16 + fr;
; #pragma unroll
;         for (int bj = 0; bj < 2; ++bj)
; #pragma unroll
;           for (int n = 0; n < 2; ++n) {
;             const f32x4 v = acc[ai][bj][m][n];
;             const int c = 256 + bj * 128 + wc * 32 + n * 16 + 4 * fq;
;             uint2 w; w.x = pack2(v[0], v[1]); w.y = pack2(v[2], v[3]);
;             *reinterpret_cast<uint2*>(Y + r * 1024 + c) = w;
;           }
;       }
	s_lshl_b32 s14, s28, 8
	s_ashr_i32 s15, s14, 31
	s_ashr_i32 s13, s12, 31
	v_lshl_add_u64 v[152:153], v[136:137], 0, s[14:15]
	s_lshl_b64 s[12:13], s[12:13], 22
	v_lshlrev_b64 v[152:153], 11, v[152:153]
	v_lshl_add_u64 v[152:153], v[152:153], 0, s[12:13]
	v_readlane_b32 s12, v253, 54
	v_readlane_b32 s13, v253, 55
	v_mov_b32_e32 v145, v0
	v_cvt_pk_bf16_f32 v109, v108, v109
	v_lshl_add_u64 v[154:155], s[12:13], 0, v[152:153]
	v_lshl_add_u64 v[156:157], v[154:155], 0, v[144:145]
	v_cvt_pk_bf16_f32 v108, v106, v107
	v_or_b32_e32 v106, 0x8000, v152
	v_mov_b32_e32 v107, v153
	s_mov_b64 s[12:13], 0x40000
	v_cvt_pk_bf16_f32 v129, v128, v129
	v_cvt_pk_bf16_f32 v128, v126, v127
	v_cvt_pk_bf16_f32 v125, v124, v125
	v_cvt_pk_bf16_f32 v124, v122, v123
	v_cvt_pk_bf16_f32 v113, v112, v113
	v_cvt_pk_bf16_f32 v112, v110, v111
	global_store_dwordx2 v[156:157], v[108:109], off offset:800
	v_lshl_add_u64 v[106:107], v[138:139], 0, v[106:107]
	v_cvt_pk_bf16_f32 v109, v120, v121
	v_cvt_pk_bf16_f32 v108, v118, v119
	v_cvt_pk_bf16_f32 v93, v92, v93
	v_cvt_pk_bf16_f32 v92, v90, v91
	v_or_b32_e32 v90, 0x10000, v152
	v_mov_b32_e32 v91, v153
	v_cvt_pk_bf16_f32 v69, v68, v69
	v_cvt_pk_bf16_f32 v68, v66, v67
	v_lshl_add_u64 v[66:67], v[154:155], 0, s[12:13]
	s_mov_b64 s[12:13], 0x48000
	global_store_dwordx2 v[156:157], v[128:129], off offset:512
	global_store_dwordx2 v[156:157], v[124:125], off offset:544
	global_store_dwordx2 v[156:157], v[112:113], off offset:768
	global_store_dwordx2 v[106:107], v[108:109], off offset:512
	v_cvt_pk_bf16_f32 v109, v116, v117
	v_cvt_pk_bf16_f32 v108, v114, v115
	v_cvt_pk_bf16_f32 v97, v96, v97
	v_cvt_pk_bf16_f32 v96, v94, v95
	global_store_dwordx2 v[106:107], v[92:93], off offset:800
	v_lshl_add_u64 v[90:91], v[138:139], 0, v[90:91]
	v_cvt_pk_bf16_f32 v93, v104, v105
	v_cvt_pk_bf16_f32 v92, v102, v103
	v_cvt_pk_bf16_f32 v77, v76, v77
	v_cvt_pk_bf16_f32 v76, v74, v75
	v_or_b32_e32 v152, 0x18000, v152
	v_cvt_pk_bf16_f32 v45, v44, v45
	v_cvt_pk_bf16_f32 v44, v42, v43
	v_lshl_add_u64 v[42:43], v[154:155], 0, s[12:13]
	s_mov_b64 s[12:13], 0x50000
	global_store_dwordx2 v[106:107], v[108:109], off offset:544
	global_store_dwordx2 v[106:107], v[96:97], off offset:768
	global_store_dwordx2 v[90:91], v[92:93], off offset:512
	v_cvt_pk_bf16_f32 v93, v100, v101
	v_cvt_pk_bf16_f32 v92, v98, v99
	v_cvt_pk_bf16_f32 v81, v80, v81
	v_cvt_pk_bf16_f32 v80, v78, v79
	global_store_dwordx2 v[90:91], v[76:77], off offset:800
	v_lshl_add_u64 v[74:75], v[138:139], 0, v[152:153]
	v_cvt_pk_bf16_f32 v77, v88, v89
	v_cvt_pk_bf16_f32 v76, v86, v87
	v_mov_b32_e32 v151, v0
	v_cvt_pk_bf16_f32 v29, v28, v29
	v_cvt_pk_bf16_f32 v28, v26, v27
	v_lshl_add_u64 v[26:27], v[154:155], 0, s[12:13]
	s_mov_b64 s[12:13], 0x58000
	global_store_dwordx2 v[90:91], v[92:93], off offset:544
	global_store_dwordx2 v[90:91], v[80:81], off offset:768
	global_store_dwordx2 v[74:75], v[76:77], off offset:512
	v_cvt_pk_bf16_f32 v77, v84, v85
	v_cvt_pk_bf16_f32 v76, v82, v83
	v_cvt_pk_bf16_f32 v73, v72, v73
	v_cvt_pk_bf16_f32 v72, v70, v71
	v_cvt_pk_bf16_f32 v53, v52, v53
	v_cvt_pk_bf16_f32 v52, v50, v51
	v_lshl_add_u64 v[50:51], v[66:67], 0, v[150:151]
	v_cvt_pk_bf16_f32 v33, v32, v33
	v_cvt_pk_bf16_f32 v32, v30, v31
	v_lshl_add_u64 v[30:31], v[42:43], 0, v[150:151]
	v_cvt_pk_bf16_f32 v17, v16, v17
	v_cvt_pk_bf16_f32 v16, v14, v15
	v_lshl_add_u64 v[14:15], v[26:27], 0, v[150:151]
	v_cvt_pk_bf16_f32 v13, v12, v13
	v_cvt_pk_bf16_f32 v12, v10, v11
	v_lshl_add_u64 v[10:11], v[154:155], 0, s[12:13]
	global_store_dwordx2 v[74:75], v[76:77], off offset:544
	global_store_dwordx2 v[74:75], v[72:73], off offset:768
	global_store_dwordx2 v[74:75], v[68:69], off offset:800
	v_mov_b32_e32 v147, v0
	global_store_dwordx2 v[50:51], v[44:45], off offset:512
	v_lshl_add_u64 v[44:45], v[42:43], 0, v[144:145]
	v_cvt_pk_bf16_f32 v51, v56, v57
	v_cvt_pk_bf16_f32 v50, v54, v55
	global_store_dwordx2 v[30:31], v[28:29], off offset:512
	v_lshl_add_u64 v[28:29], v[26:27], 0, v[144:145]
	v_cvt_pk_bf16_f32 v31, v40, v41
	v_cvt_pk_bf16_f32 v30, v38, v39
	global_store_dwordx2 v[14:15], v[12:13], off offset:512
	v_lshl_add_u64 v[12:13], v[10:11], 0, v[144:145]
	v_cvt_pk_bf16_f32 v15, v24, v25
	v_cvt_pk_bf16_f32 v14, v22, v23
	v_mov_b32_e32 v149, v0
	global_store_dwordx2 v[44:45], v[50:51], off offset:512
	v_lshl_add_u64 v[44:45], v[42:43], 0, v[146:147]
	v_cvt_pk_bf16_f32 v49, v48, v49
	v_cvt_pk_bf16_f32 v48, v46, v47
	global_store_dwordx2 v[28:29], v[30:31], off offset:512
	v_lshl_add_u64 v[28:29], v[26:27], 0, v[146:147]
	v_cvt_pk_bf16_f32 v31, v36, v37
	v_cvt_pk_bf16_f32 v30, v34, v35
	global_store_dwordx2 v[12:13], v[14:15], off offset:512
	v_lshl_add_u64 v[12:13], v[10:11], 0, v[146:147]
	v_cvt_pk_bf16_f32 v15, v20, v21
	v_cvt_pk_bf16_f32 v14, v18, v19
	v_lshl_add_u64 v[68:69], v[66:67], 0, v[144:145]
	v_cvt_pk_bf16_f32 v65, v64, v65
	v_cvt_pk_bf16_f32 v64, v62, v63
	v_lshl_add_u64 v[62:63], v[66:67], 0, v[146:147]
	v_cvt_pk_bf16_f32 v61, v60, v61
	v_cvt_pk_bf16_f32 v60, v58, v59
	v_lshl_add_u64 v[58:59], v[66:67], 0, v[148:149]
	global_store_dwordx2 v[44:45], v[48:49], off offset:512
	v_lshl_add_u64 v[44:45], v[42:43], 0, v[148:149]
	global_store_dwordx2 v[28:29], v[30:31], off offset:512
	v_lshl_add_u64 v[28:29], v[26:27], 0, v[148:149]
	global_store_dwordx2 v[12:13], v[14:15], off offset:512
	v_lshl_add_u64 v[12:13], v[10:11], 0, v[148:149]
	v_cvt_pk_bf16_f32 v9, v8, v9
	v_cvt_pk_bf16_f32 v8, v6, v7
	v_lshl_add_u64 v[6:7], v[10:11], 0, v[150:151]
	v_cvt_pk_bf16_f32 v5, v4, v5
	v_cvt_pk_bf16_f32 v4, v2, v3
	s_and_b64 vcc, exec, s[4:5]
	s_mov_b32 s12, s0
	s_mov_b32 s28, s6
	s_mov_b64 s[16:17], s[10:11]
	s_mov_b64 s[14:15], s[8:9]
	global_store_dwordx2 v[68:69], v[64:65], off offset:512
	global_store_dwordx2 v[62:63], v[60:61], off offset:512
	global_store_dwordx2 v[58:59], v[52:53], off offset:512
	global_store_dwordx2 v[44:45], v[32:33], off offset:512
	global_store_dwordx2 v[28:29], v[16:17], off offset:512
	global_store_dwordx2 v[12:13], v[8:9], off offset:512
	global_store_dwordx2 v[6:7], v[4:5], off offset:512
	s_cbranch_vccz .LBB0_1081
	s_waitcnt vmcnt(0)
	s_cmpk_gt_u32 s2, 0xff
	s_movk_i32 s21, 0x210
	s_mov_b32 s26, 0x2aaaaaab
	s_movk_i32 s27, 0xff40
	s_cbranch_scc1 .LBB0_1092
	s_barrier

; #define PG8_STAGE(bufoff, gbase, voff) do { _Pragma("unroll") for (int _i = 0; _i < 2; ++_i) \
;     __builtin_amdgcn_global_load_lds((const unsigned*)((const char*)(gbase) + (voff)[_i]), (PG8_LAS unsigned*)(lds + (bufoff) + ldsw + _i * 8192), 16, 0, 0); } while (0)
; #define PG8_LDA(dst, b, h) do { _Pragma("unroll") for (int m = 0; m < 4; ++m) _Pragma("unroll") for (int k = 0; k < 2; ++k) dst[m][k] = *(const PG8_LAS bf16x8*)(lds + PG8_SA(b, h) + aoff + m * 2048 + k * 1024); } while (0)
; #define PG8_LDB(dst, b, h) do { _Pragma("unroll") for (int n = 0; n < 2; ++n) _Pragma("unroll") for (int k = 0; k < 2; ++k) dst[n][k] = *(const PG8_LAS bf16x8*)(lds + PG8_SB(b, h) + boff + n * 2048 + k * 1024); } while (0)
; #define PG8_MMA(ai, bj, At, Bt) do { __builtin_amdgcn_s_setprio(1); _Pragma("unroll") for (int m = 0; m < 4; ++m) _Pragma("unroll") for (int n = 0; n < 2; ++n) _Pragma("unroll") for (int k = 0; k < 2; ++k) \
;     acc[ai][bj][m][n] = __builtin_amdgcn_mfma_f32_16x16x32_bf16(Bt[n][k], At[m][k], acc[ai][bj][m][n], 0, 0, 0); __builtin_amdgcn_s_setprio(0); } while (0)
; #define PG8_WAIT_V(n) asm volatile("s_waitcnt vmcnt(" #n ")" ::: "memory")
; #define PG8_WAIT_L(n) asm volatile("s_waitcnt lgkmcnt(" #n ")" ::: "memory")
; #define PG8_BAR __builtin_amdgcn_s_barrier()
; template <class Epi, class Sched>
; __device__ __forceinline__ void gemm_phase(PG8_LAS unsigned char* lds, const int lda, const int ldb, const Sched& S, const Epi& E) {
;     ...
;     for (int t = 0; t < nt; t += 2) {
;       const bool last = (t == nt - 2);
;       const char* a1 = cA + (size_t)(t + 1) * kstep;
;       const char* a2 = last ? nA : cA + (size_t)(t + 2) * kstep; const char* b2 = last ? nB : cB + (size_t)(t + 2) * kstep;
;       const char* a3 = a2 + kstep; const char* b3 = b2 + kstep;
;       PG8_LDB(B0, 0, 0); PG8_SCHED; PG8_LDA(At, 0, 0); PG8_STAGE(PG8_SA(1, 1), a1 + hstepA, voffA);
;       PG8_WAIT_L(8); PG8_BAR; PG8_WAIT_L(0); PG8_MMA(0, 0, At, B0); PG8_BAR; PG8_SCHED;
;       PG8_LDB(B1, 0, 1); PG8_STAGE(PG8_SB(0, 0), b2, voffB);
;       PG8_BAR; PG8_WAIT_L(0); PG8_MMA(0, 1, At, B1); PG8_BAR;
;       PG8_LDA(At, 0, 1); PG8_STAGE(PG8_SA(0, 0), a2, voffA);
;       PG8_BAR; PG8_WAIT_L(0); PG8_MMA(1, 0, At, B0); PG8_BAR; PG8_SCHED;
;       PG8_STAGE(PG8_SB(0, 1), b2 + hstepB, voffB);
;       PG8_WAIT_V(6); PG8_BAR; PG8_MMA(1, 1, At, B1); PG8_BAR;
.LBB0_1412:
	s_add_i32 s33, s18, 2
	s_add_u32 s19, s14, 0xfffc0080
	s_addc_u32 s20, s15, -1
	s_add_i32 s44, 0, 0x10000
	v_add_u32_e32 v152, s44, v131
	ds_read_b128 v[140:143], v152
	ds_read_b128 v[144:147], v152 offset:1024
	ds_read_b128 v[148:151], v152 offset:2048
	ds_read_b128 v[152:155], v152 offset:3072
	s_cmp_eq_u32 s11, s18
	s_cselect_b32 s18, s12, s22
	s_cselect_b32 s21, s7, s20
	s_cselect_b32 s20, s6, s19
	s_cselect_b32 s19, s13, s23
	v_lshl_add_u64 v[182:183], s[14:15], 0, v[136:137]
	s_add_i32 m0, s17, 0xc000
	ds_read_b128 v[156:159], v201
	ds_read_b128 v[160:163], v201 offset:1024
	ds_read_b128 v[164:167], v201 offset:2048
	ds_read_b128 v[168:171], v201 offset:3072
	ds_read_b128 v[172:175], v201 offset:4096
	ds_read_b128 v[202:205], v201 offset:5120
	ds_read_b128 v[206:209], v201 offset:6144
	ds_read_b128 v[210:213], v201 offset:7168
	global_load_lds_dwordx4 v[182:183], off
	v_lshl_add_u64 v[182:183], s[14:15], 0, v[138:139]
	s_add_i32 m0, s17, 0xe000
	s_nop 0
	global_load_lds_dwordx4 v[182:183], off
	s_waitcnt lgkmcnt(8)
	s_barrier
	s_waitcnt lgkmcnt(0)
	s_setprio 1
	v_mfma_f32_16x16x32_bf16 v[126:129], v[140:143], v[156:159], v[126:129]
	v_mfma_f32_16x16x32_bf16 v[122:125], v[148:151], v[156:159], v[122:125]
	v_mfma_f32_16x16x32_bf16 v[118:121], v[140:143], v[164:167], v[118:121]
	v_mfma_f32_16x16x32_bf16 v[114:117], v[148:151], v[164:167], v[114:117]
	v_mfma_f32_16x16x32_bf16 v[110:113], v[140:143], v[172:175], v[110:113]
	v_mfma_f32_16x16x32_bf16 v[106:109], v[148:151], v[172:175], v[106:109]
	v_mfma_f32_16x16x32_bf16 v[102:105], v[140:143], v[206:209], v[102:105]
	v_mfma_f32_16x16x32_bf16 v[98:101], v[148:151], v[206:209], v[98:101]
	v_mfma_f32_16x16x32_bf16 v[126:129], v[144:147], v[160:163], v[126:129]
	v_mfma_f32_16x16x32_bf16 v[122:125], v[152:155], v[160:163], v[122:125]
	v_mfma_f32_16x16x32_bf16 v[118:121], v[144:147], v[168:171], v[118:121]
	v_mfma_f32_16x16x32_bf16 v[114:117], v[152:155], v[168:171], v[114:117]
	v_mfma_f32_16x16x32_bf16 v[110:113], v[144:147], v[202:205], v[110:113]
	v_mfma_f32_16x16x32_bf16 v[106:109], v[152:155], v[202:205], v[106:109]
	v_mfma_f32_16x16x32_bf16 v[102:105], v[144:147], v[210:213], v[102:105]
	v_mfma_f32_16x16x32_bf16 v[98:101], v[152:155], v[210:213], v[98:101]
	s_setprio 0
	s_barrier
	s_add_i32 s46, 0, 0x14000
	v_add_u32_e32 v182, s46, v131
	s_add_i32 s44, s44, s29
	ds_read_b128 v[214:217], v182
	ds_read_b128 v[218:221], v182 offset:1024
	ds_read_b128 v[222:225], v182 offset:2048
	ds_read_b128 v[226:229], v182 offset:3072
	v_lshl_add_u64 v[182:183], s[18:19], 0, v[134:135]
	s_mov_b32 m0, s44
	v_lshl_add_u64 v[184:185], s[18:19], 0, v[132:133]
	global_load_lds_dwordx4 v[182:183], off
	s_add_i32 m0, s44, 0x2000
	s_nop 0
	global_load_lds_dwordx4 v[184:185], off
	s_barrier
	s_waitcnt lgkmcnt(0)
	s_setprio 1
	v_mfma_f32_16x16x32_bf16 v[94:97], v[214:217], v[156:159], v[94:97]
	v_mfma_f32_16x16x32_bf16 v[90:93], v[222:225], v[156:159], v[90:93]
	v_mfma_f32_16x16x32_bf16 v[86:89], v[214:217], v[164:167], v[86:89]
	v_mfma_f32_16x16x32_bf16 v[82:85], v[222:225], v[164:167], v[82:85]
	v_mfma_f32_16x16x32_bf16 v[78:81], v[214:217], v[172:175], v[78:81]
	v_mfma_f32_16x16x32_bf16 v[74:77], v[222:225], v[172:175], v[74:77]
	v_mfma_f32_16x16x32_bf16 v[70:73], v[214:217], v[206:209], v[70:73]
	v_mfma_f32_16x16x32_bf16 v[66:69], v[222:225], v[206:209], v[66:69]
	v_mfma_f32_16x16x32_bf16 v[94:97], v[218:221], v[160:163], v[94:97]
	v_mfma_f32_16x16x32_bf16 v[90:93], v[226:229], v[160:163], v[90:93]
	v_mfma_f32_16x16x32_bf16 v[86:89], v[218:221], v[168:171], v[86:89]
	v_mfma_f32_16x16x32_bf16 v[82:85], v[226:229], v[168:171], v[82:85]
	v_mfma_f32_16x16x32_bf16 v[78:81], v[218:221], v[202:205], v[78:81]
	v_mfma_f32_16x16x32_bf16 v[74:77], v[226:229], v[202:205], v[74:77]
	v_mfma_f32_16x16x32_bf16 v[70:73], v[218:221], v[210:213], v[70:73]
	v_mfma_f32_16x16x32_bf16 v[66:69], v[226:229], v[210:213], v[66:69]
	s_setprio 0
	s_mov_b32 m0, s17
	v_lshl_add_u64 v[230:231], s[20:21], 0, v[134:135]
	s_barrier
	ds_read_b128 v[156:159], v201 offset:16384
	ds_read_b128 v[160:163], v201 offset:17408
	ds_read_b128 v[164:167], v201 offset:18432
	ds_read_b128 v[168:171], v201 offset:19456
	ds_read_b128 v[172:175], v201 offset:20480
	ds_read_b128 v[202:205], v201 offset:21504
	ds_read_b128 v[206:209], v201 offset:22528
	ds_read_b128 v[210:213], v201 offset:23552
	global_load_lds_dwordx4 v[230:231], off
	v_lshl_add_u64 v[232:233], s[20:21], 0, v[132:133]
	s_mov_b32 m0, s34
	s_nop 0
	global_load_lds_dwordx4 v[232:233], off
	s_barrier
	s_waitcnt lgkmcnt(0)
	s_setprio 1
	v_mfma_f32_16x16x32_bf16 v[62:65], v[140:143], v[156:159], v[62:65]
	v_mfma_f32_16x16x32_bf16 v[58:61], v[148:151], v[156:159], v[58:61]
	v_mfma_f32_16x16x32_bf16 v[54:57], v[140:143], v[164:167], v[54:57]
	v_mfma_f32_16x16x32_bf16 v[50:53], v[148:151], v[164:167], v[50:53]
	v_mfma_f32_16x16x32_bf16 v[46:49], v[140:143], v[172:175], v[46:49]
	v_mfma_f32_16x16x32_bf16 v[42:45], v[148:151], v[172:175], v[42:45]
	v_mfma_f32_16x16x32_bf16 v[38:41], v[140:143], v[206:209], v[38:41]
	v_mfma_f32_16x16x32_bf16 v[34:37], v[148:151], v[206:209], v[34:37]
	v_mfma_f32_16x16x32_bf16 v[62:65], v[144:147], v[160:163], v[62:65]
	v_mfma_f32_16x16x32_bf16 v[58:61], v[152:155], v[160:163], v[58:61]
	v_mfma_f32_16x16x32_bf16 v[54:57], v[144:147], v[168:171], v[54:57]
	v_mfma_f32_16x16x32_bf16 v[50:53], v[152:155], v[168:171], v[50:53]
	v_mfma_f32_16x16x32_bf16 v[46:49], v[144:147], v[202:205], v[46:49]
	v_mfma_f32_16x16x32_bf16 v[42:45], v[152:155], v[202:205], v[42:45]
	v_mfma_f32_16x16x32_bf16 v[38:41], v[144:147], v[210:213], v[38:41]
	v_mfma_f32_16x16x32_bf16 v[34:37], v[152:155], v[210:213], v[34:37]
	s_setprio 0
	s_barrier
; #define PG8_STAGE(bufoff, gbase, voff) do { _Pragma("unroll") for (int _i = 0; _i < 2; ++_i) \
;     __builtin_amdgcn_global_load_lds((const unsigned*)((const char*)(gbase) + (voff)[_i]), (PG8_LAS unsigned*)(lds + (bufoff) + ldsw + _i * 8192), 16, 0, 0); } while (0)
; #define PG8_LDA(dst, b, h) do { _Pragma("unroll") for (int m = 0; m < 4; ++m) _Pragma("unroll") for (int k = 0; k < 2; ++k) dst[m][k] = *(const PG8_LAS bf16x8*)(lds + PG8_SA(b, h) + aoff + m * 2048 + k * 1024); } while (0)
; #define PG8_LDB(dst, b, h) do { _Pragma("unroll") for (int n = 0; n < 2; ++n) _Pragma("unroll") for (int k = 0; k < 2; ++k) dst[n][k] = *(const PG8_LAS bf16x8*)(lds + PG8_SB(b, h) + boff + n * 2048 + k * 1024); } while (0)
; #define PG8_MMA(ai, bj, At, Bt) do { __builtin_amdgcn_s_setprio(1); _Pragma("unroll") for (int m = 0; m < 4; ++m) _Pragma("unroll") for (int n = 0; n < 2; ++n) _Pragma("unroll") for (int k = 0; k < 2; ++k) \
;     acc[ai][bj][m][n] = __builtin_amdgcn_mfma_f32_16x16x32_bf16(Bt[n][k], At[m][k], acc[ai][bj][m][n], 0, 0, 0); __builtin_amdgcn_s_setprio(0); } while (0)
; #define PG8_WAIT_V(n) asm volatile("s_waitcnt vmcnt(" #n ")" ::: "memory")
; #define PG8_WAIT_L(n) asm volatile("s_waitcnt lgkmcnt(" #n ")" ::: "memory")
; #define PG8_BAR __builtin_amdgcn_s_barrier()
; #define PG8_SCHED __builtin_amdgcn_sched_barrier(0)
; template <class Epi, class Sched>
; __device__ __forceinline__ void gemm_phase(PG8_LAS unsigned char* lds, const int lda, const int ldb, const Sched& S, const Epi& E) {
;     ...
;       PG8_STAGE(PG8_SB(0, 1), b2 + hstepB, voffB);
;       PG8_WAIT_V(6); PG8_BAR; PG8_MMA(1, 1, At, B1); PG8_BAR;
;       PG8_LDB(B0, 1, 0); PG8_SCHED; PG8_LDA(At, 1, 0); PG8_STAGE(PG8_SA(0, 1), a2 + hstepA, voffA);
;       PG8_WAIT_L(8); PG8_BAR; PG8_WAIT_L(0); PG8_MMA(0, 0, At, B0); PG8_BAR; PG8_SCHED;
;       PG8_LDB(B1, 1, 1); PG8_STAGE(PG8_SB(1, 0), b3, voffB);
;       PG8_BAR; PG8_WAIT_L(0); PG8_MMA(0, 1, At, B1); PG8_BAR;
	s_add_u32 s44, s18, 0x40000
	s_addc_u32 s45, s19, 0
	s_add_i32 s46, s46, s29
	v_lshl_add_u64 v[140:141], s[44:45], 0, v[134:135]
	s_mov_b32 m0, s46
	s_nop 0
	global_load_lds_dwordx4 v[140:141], off
	v_lshl_add_u64 v[140:141], s[44:45], 0, v[132:133]
	s_add_i32 m0, s46, 0x2000
	s_nop 0
	global_load_lds_dwordx4 v[140:141], off
	s_waitcnt vmcnt(6)
	s_barrier
	s_setprio 1
	v_mfma_f32_16x16x32_bf16 v[30:33], v[214:217], v[156:159], v[30:33]
	v_mfma_f32_16x16x32_bf16 v[26:29], v[222:225], v[156:159], v[26:29]
	v_mfma_f32_16x16x32_bf16 v[22:25], v[214:217], v[164:167], v[22:25]
	v_mfma_f32_16x16x32_bf16 v[18:21], v[222:225], v[164:167], v[18:21]
	v_mfma_f32_16x16x32_bf16 v[14:17], v[214:217], v[172:175], v[14:17]
	v_mfma_f32_16x16x32_bf16 v[10:13], v[222:225], v[172:175], v[10:13]
	v_mfma_f32_16x16x32_bf16 v[6:9], v[214:217], v[206:209], v[6:9]
	v_mfma_f32_16x16x32_bf16 v[2:5], v[222:225], v[206:209], v[2:5]
	v_mfma_f32_16x16x32_bf16 v[30:33], v[218:221], v[160:163], v[30:33]
	v_mfma_f32_16x16x32_bf16 v[26:29], v[226:229], v[160:163], v[26:29]
	v_mfma_f32_16x16x32_bf16 v[22:25], v[218:221], v[168:171], v[22:25]
	v_mfma_f32_16x16x32_bf16 v[18:21], v[226:229], v[168:171], v[18:21]
	v_mfma_f32_16x16x32_bf16 v[14:17], v[218:221], v[202:205], v[14:17]
	v_mfma_f32_16x16x32_bf16 v[10:13], v[226:229], v[202:205], v[10:13]
	v_mfma_f32_16x16x32_bf16 v[6:9], v[218:221], v[210:213], v[6:9]
	v_mfma_f32_16x16x32_bf16 v[2:5], v[226:229], v[210:213], v[2:5]
	s_setprio 0
	s_add_i32 s44, 0, 0x18000
	v_add_u32_e32 v152, s44, v131
	s_barrier
	ds_read_b128 v[140:143], v152
	ds_read_b128 v[144:147], v152 offset:1024
	ds_read_b128 v[148:151], v152 offset:2048
	ds_read_b128 v[152:155], v152 offset:3072
	s_add_u32 s20, s20, 0x40000
	s_addc_u32 s21, s21, 0
	s_mov_b32 m0, s35
	v_lshl_add_u64 v[214:215], s[20:21], 0, v[134:135]
	ds_read_b128 v[156:159], v201 offset:32768
	ds_read_b128 v[160:163], v201 offset:33792
	ds_read_b128 v[164:167], v201 offset:34816
	ds_read_b128 v[168:171], v201 offset:35840
	ds_read_b128 v[172:175], v201 offset:36864
	ds_read_b128 v[202:205], v201 offset:37888
	ds_read_b128 v[206:209], v201 offset:38912
	ds_read_b128 v[210:213], v201 offset:39936
	global_load_lds_dwordx4 v[214:215], off
	v_lshl_add_u64 v[214:215], s[20:21], 0, v[132:133]
	s_mov_b32 m0, s36
	s_nop 0
	global_load_lds_dwordx4 v[214:215], off
	s_waitcnt lgkmcnt(8)
	s_barrier
	s_waitcnt lgkmcnt(0)
	s_setprio 1
	v_mfma_f32_16x16x32_bf16 v[126:129], v[140:143], v[156:159], v[126:129]
	v_mfma_f32_16x16x32_bf16 v[122:125], v[148:151], v[156:159], v[122:125]
	v_mfma_f32_16x16x32_bf16 v[118:121], v[140:143], v[164:167], v[118:121]
	v_mfma_f32_16x16x32_bf16 v[114:117], v[148:151], v[164:167], v[114:117]
	v_mfma_f32_16x16x32_bf16 v[110:113], v[140:143], v[172:175], v[110:113]
	v_mfma_f32_16x16x32_bf16 v[106:109], v[148:151], v[172:175], v[106:109]
	v_mfma_f32_16x16x32_bf16 v[102:105], v[140:143], v[206:209], v[102:105]
	v_mfma_f32_16x16x32_bf16 v[98:101], v[148:151], v[206:209], v[98:101]
	v_mfma_f32_16x16x32_bf16 v[126:129], v[144:147], v[160:163], v[126:129]
	v_mfma_f32_16x16x32_bf16 v[122:125], v[152:155], v[160:163], v[122:125]
	v_mfma_f32_16x16x32_bf16 v[118:121], v[144:147], v[168:171], v[118:121]
	v_mfma_f32_16x16x32_bf16 v[114:117], v[152:155], v[168:171], v[114:117]
	v_mfma_f32_16x16x32_bf16 v[110:113], v[144:147], v[202:205], v[110:113]
	v_mfma_f32_16x16x32_bf16 v[106:109], v[152:155], v[202:205], v[106:109]
	v_mfma_f32_16x16x32_bf16 v[102:105], v[144:147], v[210:213], v[102:105]
	v_mfma_f32_16x16x32_bf16 v[98:101], v[152:155], v[210:213], v[98:101]
	s_setprio 0
	s_barrier
	s_add_i32 s20, 0, 0x1c000
	s_add_i32 s21, s44, s29
	v_add_u32_e32 v226, s20, v131
	v_lshl_add_u64 v[182:183], v[182:183], 0, s[86:87]
	s_mov_b32 m0, s21
	ds_read_b128 v[214:217], v226
	ds_read_b128 v[218:221], v226 offset:1024
	ds_read_b128 v[222:225], v226 offset:2048
	ds_read_b128 v[226:229], v226 offset:3072
	global_load_lds_dwordx4 v[182:183], off
	v_lshl_add_u64 v[182:183], v[184:185], 0, s[86:87]
	s_add_i32 m0, s21, 0x2000
	s_nop 0
	global_load_lds_dwordx4 v[182:183], off
	s_barrier
; __device__ __forceinline__ int tid_l() { int t = threadIdx.x; asm volatile("" : "+v"(t)); return t; }
; #define PG8_STAGE(bufoff, gbase, voff) do { _Pragma("unroll") for (int _i = 0; _i < 2; ++_i) \
;     __builtin_amdgcn_global_load_lds((const unsigned*)((const char*)(gbase) + (voff)[_i]), (PG8_LAS unsigned*)(lds + (bufoff) + ldsw + _i * 8192), 16, 0, 0); } while (0)
; #define PG8_LDA(dst, b, h) do { _Pragma("unroll") for (int m = 0; m < 4; ++m) _Pragma("unroll") for (int k = 0; k < 2; ++k) dst[m][k] = *(const PG8_LAS bf16x8*)(lds + PG8_SA(b, h) + aoff + m * 2048 + k * 1024); } while (0)
; #define PG8_MMA(ai, bj, At, Bt) do { __builtin_amdgcn_s_setprio(1); _Pragma("unroll") for (int m = 0; m < 4; ++m) _Pragma("unroll") for (int n = 0; n < 2; ++n) _Pragma("unroll") for (int k = 0; k < 2; ++k) \
;     acc[ai][bj][m][n] = __builtin_amdgcn_mfma_f32_16x16x32_bf16(Bt[n][k], At[m][k], acc[ai][bj][m][n], 0, 0, 0); __builtin_amdgcn_s_setprio(0); } while (0)
; #define PG8_WAIT_V(n) asm volatile("s_waitcnt vmcnt(" #n ")" ::: "memory")
; #define PG8_WAIT_L(n) asm volatile("s_waitcnt lgkmcnt(" #n ")" ::: "memory")
; #define PG8_BAR __builtin_amdgcn_s_barrier()
; #define PG8_SCHED __builtin_amdgcn_sched_barrier(0)
; template <class Epi, class Sched>
; __device__ __forceinline__ void gemm_phase(PG8_LAS unsigned char* lds, const int lda, const int ldb, const Sched& S, const Epi& E) {
;     ...
;       PG8_BAR; PG8_WAIT_L(0); PG8_MMA(0, 1, At, B1); PG8_BAR;
;       PG8_LDA(At, 1, 1); PG8_STAGE(PG8_SA(1, 0), a3, voffA);
;       PG8_BAR; PG8_WAIT_L(0); PG8_MMA(1, 0, At, B0); PG8_BAR; PG8_SCHED;
;       PG8_STAGE(PG8_SB(1, 1), b3 + hstepB, voffB);
;       PG8_WAIT_V(6); PG8_BAR; PG8_MMA(1, 1, At, B1); PG8_BAR;
;     }
;   __device__ __forceinline__ void operator()(const f32x4 (&acc)[2][2][4][2], const Unit& u, int wr, int wc, int fr, int fq) const {
;     const int s = u.pn & 7, dq = u.pn >> 3;
;     const int tid = tid_l();
;     if (s < 4) {
	s_waitcnt lgkmcnt(0)
	s_setprio 1
	v_mfma_f32_16x16x32_bf16 v[94:97], v[214:217], v[156:159], v[94:97]
	v_mfma_f32_16x16x32_bf16 v[90:93], v[222:225], v[156:159], v[90:93]
	v_mfma_f32_16x16x32_bf16 v[86:89], v[214:217], v[164:167], v[86:89]
	v_mfma_f32_16x16x32_bf16 v[82:85], v[222:225], v[164:167], v[82:85]
	v_mfma_f32_16x16x32_bf16 v[78:81], v[214:217], v[172:175], v[78:81]
	v_mfma_f32_16x16x32_bf16 v[74:77], v[222:225], v[172:175], v[74:77]
	v_mfma_f32_16x16x32_bf16 v[70:73], v[214:217], v[206:209], v[70:73]
	v_mfma_f32_16x16x32_bf16 v[66:69], v[222:225], v[206:209], v[66:69]
	v_mfma_f32_16x16x32_bf16 v[94:97], v[218:221], v[160:163], v[94:97]
	v_mfma_f32_16x16x32_bf16 v[90:93], v[226:229], v[160:163], v[90:93]
	v_mfma_f32_16x16x32_bf16 v[86:89], v[218:221], v[168:171], v[86:89]
	v_mfma_f32_16x16x32_bf16 v[82:85], v[226:229], v[168:171], v[82:85]
	v_mfma_f32_16x16x32_bf16 v[78:81], v[218:221], v[202:205], v[78:81]
	v_mfma_f32_16x16x32_bf16 v[74:77], v[226:229], v[202:205], v[74:77]
	v_mfma_f32_16x16x32_bf16 v[70:73], v[218:221], v[210:213], v[70:73]
	v_mfma_f32_16x16x32_bf16 v[66:69], v[226:229], v[210:213], v[66:69]
	s_setprio 0
	s_mov_b32 m0, s39
	v_lshl_add_u64 v[182:183], v[230:231], 0, s[86:87]
	s_barrier
	ds_read_b128 v[156:159], v201 offset:49152
	ds_read_b128 v[160:163], v201 offset:50176
	ds_read_b128 v[164:167], v201 offset:51200
	ds_read_b128 v[168:171], v201 offset:52224
	ds_read_b128 v[172:175], v201 offset:53248
	ds_read_b128 v[202:205], v201 offset:54272
	ds_read_b128 v[206:209], v201 offset:55296
	ds_read_b128 v[210:213], v201 offset:56320
	global_load_lds_dwordx4 v[182:183], off
	v_lshl_add_u64 v[182:183], v[232:233], 0, s[86:87]
	s_mov_b32 m0, s40
	s_nop 0
	global_load_lds_dwordx4 v[182:183], off
	s_barrier
	s_waitcnt lgkmcnt(0)
	s_setprio 1
	v_mfma_f32_16x16x32_bf16 v[62:65], v[140:143], v[156:159], v[62:65]
	v_mfma_f32_16x16x32_bf16 v[58:61], v[148:151], v[156:159], v[58:61]
	v_mfma_f32_16x16x32_bf16 v[54:57], v[140:143], v[164:167], v[54:57]
	v_mfma_f32_16x16x32_bf16 v[50:53], v[148:151], v[164:167], v[50:53]
	v_mfma_f32_16x16x32_bf16 v[46:49], v[140:143], v[172:175], v[46:49]
	v_mfma_f32_16x16x32_bf16 v[42:45], v[148:151], v[172:175], v[42:45]
	v_mfma_f32_16x16x32_bf16 v[38:41], v[140:143], v[206:209], v[38:41]
	v_mfma_f32_16x16x32_bf16 v[34:37], v[148:151], v[206:209], v[34:37]
	v_mfma_f32_16x16x32_bf16 v[62:65], v[144:147], v[160:163], v[62:65]
	v_mfma_f32_16x16x32_bf16 v[58:61], v[152:155], v[160:163], v[58:61]
	v_mfma_f32_16x16x32_bf16 v[54:57], v[144:147], v[168:171], v[54:57]
	v_mfma_f32_16x16x32_bf16 v[50:53], v[152:155], v[168:171], v[50:53]
	v_mfma_f32_16x16x32_bf16 v[46:49], v[144:147], v[202:205], v[46:49]
	v_mfma_f32_16x16x32_bf16 v[42:45], v[152:155], v[202:205], v[42:45]
	v_mfma_f32_16x16x32_bf16 v[38:41], v[144:147], v[210:213], v[38:41]
	v_mfma_f32_16x16x32_bf16 v[34:37], v[152:155], v[210:213], v[34:37]
	s_setprio 0
	s_barrier
	s_add_u32 s18, s18, 0x40080
	s_addc_u32 s19, s19, 0
	s_add_i32 s20, s20, s29
	v_lshl_add_u64 v[140:141], s[18:19], 0, v[134:135]
	s_mov_b32 m0, s20
	s_nop 0
	global_load_lds_dwordx4 v[140:141], off
	v_lshl_add_u64 v[140:141], s[18:19], 0, v[132:133]
	s_add_i32 m0, s20, 0x2000
	s_nop 0
	global_load_lds_dwordx4 v[140:141], off
	s_waitcnt vmcnt(6)
	s_barrier
	s_setprio 1
	v_mfma_f32_16x16x32_bf16 v[30:33], v[214:217], v[156:159], v[30:33]
	v_mfma_f32_16x16x32_bf16 v[26:29], v[222:225], v[156:159], v[26:29]
	v_mfma_f32_16x16x32_bf16 v[22:25], v[214:217], v[164:167], v[22:25]
	v_mfma_f32_16x16x32_bf16 v[18:21], v[222:225], v[164:167], v[18:21]
	v_mfma_f32_16x16x32_bf16 v[14:17], v[214:217], v[172:175], v[14:17]
	v_mfma_f32_16x16x32_bf16 v[10:13], v[222:225], v[172:175], v[10:13]
	v_mfma_f32_16x16x32_bf16 v[6:9], v[214:217], v[206:209], v[6:9]
	v_mfma_f32_16x16x32_bf16 v[2:5], v[222:225], v[206:209], v[2:5]
	v_mfma_f32_16x16x32_bf16 v[30:33], v[218:221], v[160:163], v[30:33]
	v_mfma_f32_16x16x32_bf16 v[26:29], v[226:229], v[160:163], v[26:29]
	v_mfma_f32_16x16x32_bf16 v[22:25], v[218:221], v[168:171], v[22:25]
	v_mfma_f32_16x16x32_bf16 v[18:21], v[226:229], v[168:171], v[18:21]
	v_mfma_f32_16x16x32_bf16 v[14:17], v[218:221], v[202:205], v[14:17]
	v_mfma_f32_16x16x32_bf16 v[10:13], v[226:229], v[202:205], v[10:13]
	v_mfma_f32_16x16x32_bf16 v[6:9], v[218:221], v[210:213], v[6:9]
	v_mfma_f32_16x16x32_bf16 v[2:5], v[226:229], v[210:213], v[2:5]
	s_setprio 0
	s_add_u32 s14, s14, 0x100
	s_addc_u32 s15, s15, 0
	s_add_u32 s22, s22, 0x100
	s_addc_u32 s23, s23, 0
	s_cmp_ge_u32 s33, s43
	s_mov_b32 s18, s33
	s_barrier
	s_cbranch_scc0 .LBB0_1412
	s_and_b32 s11, s2, 7
	v_mov_b32_e32 v140, v176
	s_mov_b64 s[14:15], -1
	s_cmp_gt_u32 s11, 3
	v_ashrrev_i32_e32 v141, 31, v140
	s_cbranch_scc1 .LBB0_1416
	s_andn2_b64 vcc, exec, s[14:15]
	s_cbranch_vccz .LBB0_1417

; #define PG8_STAGE(bufoff, gbase, voff) do { _Pragma("unroll") for (int _i = 0; _i < 2; ++_i) \
;     __builtin_amdgcn_global_load_lds((const unsigned*)((const char*)(gbase) + (voff)[_i]), (PG8_LAS unsigned*)(lds + (bufoff) + ldsw + _i * 8192), 16, 0, 0); } while (0)
; #define PG8_LDA(dst, b, h) do { _Pragma("unroll") for (int m = 0; m < 4; ++m) _Pragma("unroll") for (int k = 0; k < 2; ++k) dst[m][k] = *(const PG8_LAS bf16x8*)(lds + PG8_SA(b, h) + aoff + m * 2048 + k * 1024); } while (0)
; #define PG8_LDB(dst, b, h) do { _Pragma("unroll") for (int n = 0; n < 2; ++n) _Pragma("unroll") for (int k = 0; k < 2; ++k) dst[n][k] = *(const PG8_LAS bf16x8*)(lds + PG8_SB(b, h) + boff + n * 2048 + k * 1024); } while (0)
; #define PG8_MMA(ai, bj, At, Bt) do { __builtin_amdgcn_s_setprio(1); _Pragma("unroll") for (int m = 0; m < 4; ++m) _Pragma("unroll") for (int n = 0; n < 2; ++n) _Pragma("unroll") for (int k = 0; k < 2; ++k) \
;     acc[ai][bj][m][n] = __builtin_amdgcn_mfma_f32_16x16x32_bf16(Bt[n][k], At[m][k], acc[ai][bj][m][n], 0, 0, 0); __builtin_amdgcn_s_setprio(0); } while (0)
; #define PG8_WAIT_V(n) asm volatile("s_waitcnt vmcnt(" #n ")" ::: "memory")
; #define PG8_WAIT_L(n) asm volatile("s_waitcnt lgkmcnt(" #n ")" ::: "memory")
; #define PG8_BAR __builtin_amdgcn_s_barrier()
; template <class Epi, class Sched>
; __device__ __forceinline__ void gemm_phase(PG8_LAS unsigned char* lds, const int lda, const int ldb, const Sched& S, const Epi& E) {
;     ...
;     for (int t = 0; t < nt; t += 2) {
;       const bool last = (t == nt - 2);
;       const char* a1 = cA + (size_t)(t + 1) * kstep;
;       const char* a2 = last ? nA : cA + (size_t)(t + 2) * kstep; const char* b2 = last ? nB : cB + (size_t)(t + 2) * kstep;
;       const char* a3 = a2 + kstep; const char* b3 = b2 + kstep;
;       PG8_LDB(B0, 0, 0); PG8_SCHED; PG8_LDA(At, 0, 0); PG8_STAGE(PG8_SA(1, 1), a1 + hstepA, voffA);
;       PG8_WAIT_L(8); PG8_BAR; PG8_WAIT_L(0); PG8_MMA(0, 0, At, B0); PG8_BAR; PG8_SCHED;
;       PG8_LDB(B1, 0, 1); PG8_STAGE(PG8_SB(0, 0), b2, voffB);
;       PG8_BAR; PG8_WAIT_L(0); PG8_MMA(0, 1, At, B1); PG8_BAR;
;       PG8_LDA(At, 0, 1); PG8_STAGE(PG8_SA(0, 0), a2, voffA);
;       PG8_BAR; PG8_WAIT_L(0); PG8_MMA(1, 0, At, B0); PG8_BAR; PG8_SCHED;
;       PG8_STAGE(PG8_SB(0, 1), b2 + hstepB, voffB);
;       PG8_WAIT_V(6); PG8_BAR; PG8_MMA(1, 1, At, B1); PG8_BAR;
.LBB0_1482:
	s_add_u32 s20, s18, 0x100
	s_addc_u32 s21, s19, 0
	s_add_i32 s33, 0, 0x10000
	v_add_u32_e32 v154, s33, v131
	ds_read_b128 v[140:143], v154
	ds_read_b128 v[146:149], v154 offset:1024
	ds_read_b128 v[150:153], v154 offset:2048
	ds_read_b128 v[154:157], v154 offset:3072
	s_cmp_eq_u32 s54, 12
	s_cselect_b32 s25, s11, s21
	s_cselect_b32 s24, s50, s20
	s_cselect_b32 s23, s1, s53
	s_cselect_b32 s22, s51, s52
	v_lshl_add_u64 v[174:175], s[18:19], 0, v[136:137]
	s_add_i32 m0, s17, 0xc000
	ds_read_b128 v[158:161], v145
	ds_read_b128 v[162:165], v145 offset:1024
	ds_read_b128 v[166:169], v145 offset:2048
	ds_read_b128 v[170:173], v145 offset:3072
	ds_read_b128 v[200:203], v145 offset:4096
	ds_read_b128 v[204:207], v145 offset:5120
	ds_read_b128 v[208:211], v145 offset:6144
	ds_read_b128 v[212:215], v145 offset:7168
	global_load_lds_dwordx4 v[174:175], off
	v_lshl_add_u64 v[174:175], s[18:19], 0, v[138:139]
	s_add_i32 m0, s17, 0xe000
	s_nop 0
	global_load_lds_dwordx4 v[174:175], off
	s_waitcnt lgkmcnt(8)
	s_barrier
	s_waitcnt lgkmcnt(0)
	s_setprio 1
	v_mfma_f32_16x16x32_bf16 v[126:129], v[140:143], v[158:161], v[126:129]
	v_mfma_f32_16x16x32_bf16 v[122:125], v[150:153], v[158:161], v[122:125]
	v_mfma_f32_16x16x32_bf16 v[110:113], v[140:143], v[166:169], v[110:113]
	v_mfma_f32_16x16x32_bf16 v[106:109], v[150:153], v[166:169], v[106:109]
	v_mfma_f32_16x16x32_bf16 v[94:97], v[140:143], v[200:203], v[94:97]
	v_mfma_f32_16x16x32_bf16 v[90:93], v[150:153], v[200:203], v[90:93]
	v_mfma_f32_16x16x32_bf16 v[78:81], v[140:143], v[208:211], v[78:81]
	v_mfma_f32_16x16x32_bf16 v[74:77], v[150:153], v[208:211], v[74:77]
	v_mfma_f32_16x16x32_bf16 v[126:129], v[146:149], v[162:165], v[126:129]
	v_mfma_f32_16x16x32_bf16 v[122:125], v[154:157], v[162:165], v[122:125]
	v_mfma_f32_16x16x32_bf16 v[110:113], v[146:149], v[170:173], v[110:113]
	v_mfma_f32_16x16x32_bf16 v[106:109], v[154:157], v[170:173], v[106:109]
	v_mfma_f32_16x16x32_bf16 v[94:97], v[146:149], v[204:207], v[94:97]
	v_mfma_f32_16x16x32_bf16 v[90:93], v[154:157], v[204:207], v[90:93]
	v_mfma_f32_16x16x32_bf16 v[78:81], v[146:149], v[212:215], v[78:81]
	v_mfma_f32_16x16x32_bf16 v[74:77], v[154:157], v[212:215], v[74:77]
	s_setprio 0
	s_barrier
	s_add_i32 s55, 0, 0x14000
	v_add_u32_e32 v174, s55, v131
	s_add_i32 s18, s33, s34
	ds_read_b128 v[216:219], v174
	ds_read_b128 v[220:223], v174 offset:1024
	ds_read_b128 v[224:227], v174 offset:2048
	ds_read_b128 v[228:231], v174 offset:3072
	v_lshl_add_u64 v[174:175], s[22:23], 0, v[134:135]
	s_mov_b32 m0, s18
	v_lshl_add_u64 v[182:183], s[22:23], 0, v[132:133]
	global_load_lds_dwordx4 v[174:175], off
	s_add_i32 m0, s18, 0x2000
	s_nop 0
	global_load_lds_dwordx4 v[182:183], off
	s_barrier
	s_waitcnt lgkmcnt(0)
	s_setprio 1
	v_mfma_f32_16x16x32_bf16 v[118:121], v[216:219], v[158:161], v[118:121]
	v_mfma_f32_16x16x32_bf16 v[114:117], v[224:227], v[158:161], v[114:117]
	v_mfma_f32_16x16x32_bf16 v[102:105], v[216:219], v[166:169], v[102:105]
	v_mfma_f32_16x16x32_bf16 v[98:101], v[224:227], v[166:169], v[98:101]
	v_mfma_f32_16x16x32_bf16 v[86:89], v[216:219], v[200:203], v[86:89]
	v_mfma_f32_16x16x32_bf16 v[82:85], v[224:227], v[200:203], v[82:85]
	v_mfma_f32_16x16x32_bf16 v[70:73], v[216:219], v[208:211], v[70:73]
	v_mfma_f32_16x16x32_bf16 v[66:69], v[224:227], v[208:211], v[66:69]
	v_mfma_f32_16x16x32_bf16 v[118:121], v[220:223], v[162:165], v[118:121]
	v_mfma_f32_16x16x32_bf16 v[114:117], v[228:231], v[162:165], v[114:117]
	v_mfma_f32_16x16x32_bf16 v[102:105], v[220:223], v[170:173], v[102:105]
	v_mfma_f32_16x16x32_bf16 v[98:101], v[228:231], v[170:173], v[98:101]
	v_mfma_f32_16x16x32_bf16 v[86:89], v[220:223], v[204:207], v[86:89]
	v_mfma_f32_16x16x32_bf16 v[82:85], v[228:231], v[204:207], v[82:85]
	v_mfma_f32_16x16x32_bf16 v[70:73], v[220:223], v[212:215], v[70:73]
	v_mfma_f32_16x16x32_bf16 v[66:69], v[228:231], v[212:215], v[66:69]
	s_setprio 0
	s_mov_b32 m0, s17
	v_lshl_add_u64 v[184:185], s[24:25], 0, v[134:135]
	s_barrier
	ds_read_b128 v[158:161], v145 offset:16384
	ds_read_b128 v[162:165], v145 offset:17408
	ds_read_b128 v[166:169], v145 offset:18432
	ds_read_b128 v[170:173], v145 offset:19456
	ds_read_b128 v[200:203], v145 offset:20480
	ds_read_b128 v[204:207], v145 offset:21504
	ds_read_b128 v[208:211], v145 offset:22528
	ds_read_b128 v[212:215], v145 offset:23552
	global_load_lds_dwordx4 v[184:185], off
	v_lshl_add_u64 v[232:233], s[24:25], 0, v[132:133]
	s_mov_b32 m0, s37
	s_nop 0
	global_load_lds_dwordx4 v[232:233], off
	s_barrier
	s_waitcnt lgkmcnt(0)
	s_setprio 1
	v_mfma_f32_16x16x32_bf16 v[62:65], v[140:143], v[158:161], v[62:65]
	v_mfma_f32_16x16x32_bf16 v[58:61], v[150:153], v[158:161], v[58:61]
	v_mfma_f32_16x16x32_bf16 v[46:49], v[140:143], v[166:169], v[46:49]
	v_mfma_f32_16x16x32_bf16 v[42:45], v[150:153], v[166:169], v[42:45]
	v_mfma_f32_16x16x32_bf16 v[30:33], v[140:143], v[200:203], v[30:33]
	v_mfma_f32_16x16x32_bf16 v[26:29], v[150:153], v[200:203], v[26:29]
	v_mfma_f32_16x16x32_bf16 v[14:17], v[140:143], v[208:211], v[14:17]
	v_mfma_f32_16x16x32_bf16 v[10:13], v[150:153], v[208:211], v[10:13]
	v_mfma_f32_16x16x32_bf16 v[62:65], v[146:149], v[162:165], v[62:65]
	v_mfma_f32_16x16x32_bf16 v[58:61], v[154:157], v[162:165], v[58:61]
	v_mfma_f32_16x16x32_bf16 v[46:49], v[146:149], v[170:173], v[46:49]
	v_mfma_f32_16x16x32_bf16 v[42:45], v[154:157], v[170:173], v[42:45]
	v_mfma_f32_16x16x32_bf16 v[30:33], v[146:149], v[204:207], v[30:33]
	v_mfma_f32_16x16x32_bf16 v[26:29], v[154:157], v[204:207], v[26:29]
	v_mfma_f32_16x16x32_bf16 v[14:17], v[146:149], v[212:215], v[14:17]
	v_mfma_f32_16x16x32_bf16 v[10:13], v[154:157], v[212:215], v[10:13]
	s_setprio 0
	s_barrier
; #define PG8_STAGE(bufoff, gbase, voff) do { _Pragma("unroll") for (int _i = 0; _i < 2; ++_i) \
;     __builtin_amdgcn_global_load_lds((const unsigned*)((const char*)(gbase) + (voff)[_i]), (PG8_LAS unsigned*)(lds + (bufoff) + ldsw + _i * 8192), 16, 0, 0); } while (0)
; #define PG8_LDA(dst, b, h) do { _Pragma("unroll") for (int m = 0; m < 4; ++m) _Pragma("unroll") for (int k = 0; k < 2; ++k) dst[m][k] = *(const PG8_LAS bf16x8*)(lds + PG8_SA(b, h) + aoff + m * 2048 + k * 1024); } while (0)
; #define PG8_LDB(dst, b, h) do { _Pragma("unroll") for (int n = 0; n < 2; ++n) _Pragma("unroll") for (int k = 0; k < 2; ++k) dst[n][k] = *(const PG8_LAS bf16x8*)(lds + PG8_SB(b, h) + boff + n * 2048 + k * 1024); } while (0)
; #define PG8_MMA(ai, bj, At, Bt) do { __builtin_amdgcn_s_setprio(1); _Pragma("unroll") for (int m = 0; m < 4; ++m) _Pragma("unroll") for (int n = 0; n < 2; ++n) _Pragma("unroll") for (int k = 0; k < 2; ++k) \
;     acc[ai][bj][m][n] = __builtin_amdgcn_mfma_f32_16x16x32_bf16(Bt[n][k], At[m][k], acc[ai][bj][m][n], 0, 0, 0); __builtin_amdgcn_s_setprio(0); } while (0)
; #define PG8_WAIT_V(n) asm volatile("s_waitcnt vmcnt(" #n ")" ::: "memory")
; #define PG8_WAIT_L(n) asm volatile("s_waitcnt lgkmcnt(" #n ")" ::: "memory")
; #define PG8_BAR __builtin_amdgcn_s_barrier()
; #define PG8_SCHED __builtin_amdgcn_sched_barrier(0)
; template <class Epi, class Sched>
; __device__ __forceinline__ void gemm_phase(PG8_LAS unsigned char* lds, const int lda, const int ldb, const Sched& S, const Epi& E) {
;     ...
;       PG8_STAGE(PG8_SB(0, 1), b2 + hstepB, voffB);
;       PG8_WAIT_V(6); PG8_BAR; PG8_MMA(1, 1, At, B1); PG8_BAR;
;       PG8_LDB(B0, 1, 0); PG8_SCHED; PG8_LDA(At, 1, 0); PG8_STAGE(PG8_SA(0, 1), a2 + hstepA, voffA);
;       PG8_WAIT_L(8); PG8_BAR; PG8_WAIT_L(0); PG8_MMA(0, 0, At, B0); PG8_BAR; PG8_SCHED;
;       PG8_LDB(B1, 1, 1); PG8_STAGE(PG8_SB(1, 0), b3, voffB);
;       PG8_BAR; PG8_WAIT_L(0); PG8_MMA(0, 1, At, B1); PG8_BAR;
	s_add_u32 s18, s22, 0x40000
	s_addc_u32 s19, s23, 0
	s_add_i32 s33, s55, s34
	v_lshl_add_u64 v[140:141], s[18:19], 0, v[134:135]
	s_mov_b32 m0, s33
	s_nop 0
	global_load_lds_dwordx4 v[140:141], off
	v_lshl_add_u64 v[140:141], s[18:19], 0, v[132:133]
	s_add_i32 m0, s33, 0x2000
	s_nop 0
	global_load_lds_dwordx4 v[140:141], off
	s_waitcnt vmcnt(6)
	s_barrier
	s_setprio 1
	v_mfma_f32_16x16x32_bf16 v[54:57], v[216:219], v[158:161], v[54:57]
	v_mfma_f32_16x16x32_bf16 v[50:53], v[224:227], v[158:161], v[50:53]
	v_mfma_f32_16x16x32_bf16 v[38:41], v[216:219], v[166:169], v[38:41]
	v_mfma_f32_16x16x32_bf16 v[34:37], v[224:227], v[166:169], v[34:37]
	v_mfma_f32_16x16x32_bf16 v[22:25], v[216:219], v[200:203], v[22:25]
	v_mfma_f32_16x16x32_bf16 v[18:21], v[224:227], v[200:203], v[18:21]
	v_mfma_f32_16x16x32_bf16 v[6:9], v[216:219], v[208:211], v[6:9]
	v_mfma_f32_16x16x32_bf16 v[2:5], v[224:227], v[208:211], v[2:5]
	v_mfma_f32_16x16x32_bf16 v[54:57], v[220:223], v[162:165], v[54:57]
	v_mfma_f32_16x16x32_bf16 v[50:53], v[228:231], v[162:165], v[50:53]
	v_mfma_f32_16x16x32_bf16 v[38:41], v[220:223], v[170:173], v[38:41]
	v_mfma_f32_16x16x32_bf16 v[34:37], v[228:231], v[170:173], v[34:37]
	v_mfma_f32_16x16x32_bf16 v[22:25], v[220:223], v[204:207], v[22:25]
	v_mfma_f32_16x16x32_bf16 v[18:21], v[228:231], v[204:207], v[18:21]
	v_mfma_f32_16x16x32_bf16 v[6:9], v[220:223], v[212:215], v[6:9]
	v_mfma_f32_16x16x32_bf16 v[2:5], v[228:231], v[212:215], v[2:5]
	s_setprio 0
	s_add_i32 s33, 0, 0x18000
	v_add_u32_e32 v154, s33, v131
	s_barrier
	ds_read_b128 v[140:143], v154
	ds_read_b128 v[146:149], v154 offset:1024
	ds_read_b128 v[150:153], v154 offset:2048
	ds_read_b128 v[154:157], v154 offset:3072
	s_add_u32 s18, s24, 0x40000
	s_addc_u32 s19, s25, 0
	s_mov_b32 m0, s38
	v_lshl_add_u64 v[216:217], s[18:19], 0, v[134:135]
	ds_read_b128 v[158:161], v145 offset:32768
	ds_read_b128 v[162:165], v145 offset:33792
	ds_read_b128 v[166:169], v145 offset:34816
	ds_read_b128 v[170:173], v145 offset:35840
	ds_read_b128 v[200:203], v145 offset:36864
	ds_read_b128 v[204:207], v145 offset:37888
	ds_read_b128 v[208:211], v145 offset:38912
	ds_read_b128 v[212:215], v145 offset:39936
	global_load_lds_dwordx4 v[216:217], off
	v_lshl_add_u64 v[216:217], s[18:19], 0, v[132:133]
	s_mov_b32 m0, s39
	s_nop 0
	global_load_lds_dwordx4 v[216:217], off
	s_waitcnt lgkmcnt(8)
	s_barrier
	s_waitcnt lgkmcnt(0)
	s_setprio 1
	v_mfma_f32_16x16x32_bf16 v[126:129], v[140:143], v[158:161], v[126:129]
	v_mfma_f32_16x16x32_bf16 v[122:125], v[150:153], v[158:161], v[122:125]
	v_mfma_f32_16x16x32_bf16 v[110:113], v[140:143], v[166:169], v[110:113]
	v_mfma_f32_16x16x32_bf16 v[106:109], v[150:153], v[166:169], v[106:109]
	v_mfma_f32_16x16x32_bf16 v[94:97], v[140:143], v[200:203], v[94:97]
	v_mfma_f32_16x16x32_bf16 v[90:93], v[150:153], v[200:203], v[90:93]
	v_mfma_f32_16x16x32_bf16 v[78:81], v[140:143], v[208:211], v[78:81]
	v_mfma_f32_16x16x32_bf16 v[74:77], v[150:153], v[208:211], v[74:77]
	v_mfma_f32_16x16x32_bf16 v[126:129], v[146:149], v[162:165], v[126:129]
	v_mfma_f32_16x16x32_bf16 v[122:125], v[154:157], v[162:165], v[122:125]
	v_mfma_f32_16x16x32_bf16 v[110:113], v[146:149], v[170:173], v[110:113]
	v_mfma_f32_16x16x32_bf16 v[106:109], v[154:157], v[170:173], v[106:109]
	v_mfma_f32_16x16x32_bf16 v[94:97], v[146:149], v[204:207], v[94:97]
	v_mfma_f32_16x16x32_bf16 v[90:93], v[154:157], v[204:207], v[90:93]
	v_mfma_f32_16x16x32_bf16 v[78:81], v[146:149], v[212:215], v[78:81]
	v_mfma_f32_16x16x32_bf16 v[74:77], v[154:157], v[212:215], v[74:77]
	s_setprio 0
	s_barrier
	s_add_i32 s24, 0, 0x1c000
	s_add_i32 s18, s33, s34
	v_add_u32_e32 v228, s24, v131
	v_lshl_add_u64 v[174:175], v[174:175], 0, s[86:87]
	s_mov_b32 m0, s18
	ds_read_b128 v[216:219], v228
	ds_read_b128 v[220:223], v228 offset:1024
	ds_read_b128 v[224:227], v228 offset:2048
	ds_read_b128 v[228:231], v228 offset:3072
	global_load_lds_dwordx4 v[174:175], off
	v_lshl_add_u64 v[174:175], v[182:183], 0, s[86:87]
	s_add_i32 m0, s18, 0x2000
	s_nop 0
	global_load_lds_dwordx4 v[174:175], off
	s_barrier
; #define PG8_STAGE(bufoff, gbase, voff) do { _Pragma("unroll") for (int _i = 0; _i < 2; ++_i) \
;     __builtin_amdgcn_global_load_lds((const unsigned*)((const char*)(gbase) + (voff)[_i]), (PG8_LAS unsigned*)(lds + (bufoff) + ldsw + _i * 8192), 16, 0, 0); } while (0)
; #define PG8_LDA(dst, b, h) do { _Pragma("unroll") for (int m = 0; m < 4; ++m) _Pragma("unroll") for (int k = 0; k < 2; ++k) dst[m][k] = *(const PG8_LAS bf16x8*)(lds + PG8_SA(b, h) + aoff + m * 2048 + k * 1024); } while (0)
; #define PG8_MMA(ai, bj, At, Bt) do { __builtin_amdgcn_s_setprio(1); _Pragma("unroll") for (int m = 0; m < 4; ++m) _Pragma("unroll") for (int n = 0; n < 2; ++n) _Pragma("unroll") for (int k = 0; k < 2; ++k) \
;     acc[ai][bj][m][n] = __builtin_amdgcn_mfma_f32_16x16x32_bf16(Bt[n][k], At[m][k], acc[ai][bj][m][n], 0, 0, 0); __builtin_amdgcn_s_setprio(0); } while (0)
; #define PG8_WAIT_V(n) asm volatile("s_waitcnt vmcnt(" #n ")" ::: "memory")
; #define PG8_WAIT_L(n) asm volatile("s_waitcnt lgkmcnt(" #n ")" ::: "memory")
; #define PG8_BAR __builtin_amdgcn_s_barrier()
; #define PG8_SCHED __builtin_amdgcn_sched_barrier(0)
; template <class Epi, class Sched>
; __device__ __forceinline__ void gemm_phase(PG8_LAS unsigned char* lds, const int lda, const int ldb, const Sched& S, const Epi& E) {
;     ...
;       PG8_BAR; PG8_WAIT_L(0); PG8_MMA(0, 1, At, B1); PG8_BAR;
;       PG8_LDA(At, 1, 1); PG8_STAGE(PG8_SA(1, 0), a3, voffA);
;       PG8_BAR; PG8_WAIT_L(0); PG8_MMA(1, 0, At, B0); PG8_BAR; PG8_SCHED;
;       PG8_STAGE(PG8_SB(1, 1), b3 + hstepB, voffB);
;       PG8_WAIT_V(6); PG8_BAR; PG8_MMA(1, 1, At, B1); PG8_BAR;
;     }
;   __device__ __forceinline__ void operator()(const f32x4 (&acc)[2][2][4][2], const Unit& u, int wr, int wc, int fr, int fq) const {
;     const int mr = (u.pm * 256 < ML) ? ((u.pm * 256) >> 11) : 32;
;     const float* gp = mod + (size_t)mr * 6144 + gate_off;
	s_waitcnt lgkmcnt(0)
	s_setprio 1
	v_mfma_f32_16x16x32_bf16 v[118:121], v[216:219], v[158:161], v[118:121]
	v_mfma_f32_16x16x32_bf16 v[114:117], v[224:227], v[158:161], v[114:117]
	v_mfma_f32_16x16x32_bf16 v[102:105], v[216:219], v[166:169], v[102:105]
	v_mfma_f32_16x16x32_bf16 v[98:101], v[224:227], v[166:169], v[98:101]
	v_mfma_f32_16x16x32_bf16 v[86:89], v[216:219], v[200:203], v[86:89]
	v_mfma_f32_16x16x32_bf16 v[82:85], v[224:227], v[200:203], v[82:85]
	v_mfma_f32_16x16x32_bf16 v[70:73], v[216:219], v[208:211], v[70:73]
	v_mfma_f32_16x16x32_bf16 v[66:69], v[224:227], v[208:211], v[66:69]
	v_mfma_f32_16x16x32_bf16 v[118:121], v[220:223], v[162:165], v[118:121]
	v_mfma_f32_16x16x32_bf16 v[114:117], v[228:231], v[162:165], v[114:117]
	v_mfma_f32_16x16x32_bf16 v[102:105], v[220:223], v[170:173], v[102:105]
	v_mfma_f32_16x16x32_bf16 v[98:101], v[228:231], v[170:173], v[98:101]
	v_mfma_f32_16x16x32_bf16 v[86:89], v[220:223], v[204:207], v[86:89]
	v_mfma_f32_16x16x32_bf16 v[82:85], v[228:231], v[204:207], v[82:85]
	v_mfma_f32_16x16x32_bf16 v[70:73], v[220:223], v[212:215], v[70:73]
	v_mfma_f32_16x16x32_bf16 v[66:69], v[228:231], v[212:215], v[66:69]
	s_setprio 0
	s_mov_b32 m0, s44
	v_lshl_add_u64 v[174:175], v[184:185], 0, s[86:87]
	s_barrier
	ds_read_b128 v[158:161], v145 offset:49152
	ds_read_b128 v[162:165], v145 offset:50176
	ds_read_b128 v[166:169], v145 offset:51200
	ds_read_b128 v[170:173], v145 offset:52224
	ds_read_b128 v[200:203], v145 offset:53248
	ds_read_b128 v[204:207], v145 offset:54272
	ds_read_b128 v[208:211], v145 offset:55296
	ds_read_b128 v[212:215], v145 offset:56320
	global_load_lds_dwordx4 v[174:175], off
	v_lshl_add_u64 v[174:175], v[232:233], 0, s[86:87]
	s_mov_b32 m0, s45
	s_nop 0
	global_load_lds_dwordx4 v[174:175], off
	s_barrier
	s_waitcnt lgkmcnt(0)
	s_setprio 1
	v_mfma_f32_16x16x32_bf16 v[62:65], v[140:143], v[158:161], v[62:65]
	v_mfma_f32_16x16x32_bf16 v[58:61], v[150:153], v[158:161], v[58:61]
	v_mfma_f32_16x16x32_bf16 v[46:49], v[140:143], v[166:169], v[46:49]
	v_mfma_f32_16x16x32_bf16 v[42:45], v[150:153], v[166:169], v[42:45]
	v_mfma_f32_16x16x32_bf16 v[30:33], v[140:143], v[200:203], v[30:33]
	v_mfma_f32_16x16x32_bf16 v[26:29], v[150:153], v[200:203], v[26:29]
	v_mfma_f32_16x16x32_bf16 v[14:17], v[140:143], v[208:211], v[14:17]
	v_mfma_f32_16x16x32_bf16 v[10:13], v[150:153], v[208:211], v[10:13]
	v_mfma_f32_16x16x32_bf16 v[62:65], v[146:149], v[162:165], v[62:65]
	v_mfma_f32_16x16x32_bf16 v[58:61], v[154:157], v[162:165], v[58:61]
	v_mfma_f32_16x16x32_bf16 v[46:49], v[146:149], v[170:173], v[46:49]
	v_mfma_f32_16x16x32_bf16 v[42:45], v[154:157], v[170:173], v[42:45]
	v_mfma_f32_16x16x32_bf16 v[30:33], v[146:149], v[204:207], v[30:33]
	v_mfma_f32_16x16x32_bf16 v[26:29], v[154:157], v[204:207], v[26:29]
	v_mfma_f32_16x16x32_bf16 v[14:17], v[146:149], v[212:215], v[14:17]
	v_mfma_f32_16x16x32_bf16 v[10:13], v[154:157], v[212:215], v[10:13]
	s_setprio 0
	s_barrier
	s_add_u32 s18, s22, 0x40080
	s_addc_u32 s19, s23, 0
	s_add_i32 s22, s24, s34
	v_lshl_add_u64 v[140:141], s[18:19], 0, v[134:135]
	s_mov_b32 m0, s22
	s_nop 0
	global_load_lds_dwordx4 v[140:141], off
	v_lshl_add_u64 v[140:141], s[18:19], 0, v[132:133]
	s_add_i32 m0, s22, 0x2000
	s_nop 0
	global_load_lds_dwordx4 v[140:141], off
	s_waitcnt vmcnt(6)
	s_barrier
	s_setprio 1
	v_mfma_f32_16x16x32_bf16 v[54:57], v[216:219], v[158:161], v[54:57]
	v_mfma_f32_16x16x32_bf16 v[50:53], v[224:227], v[158:161], v[50:53]
	v_mfma_f32_16x16x32_bf16 v[38:41], v[216:219], v[166:169], v[38:41]
	v_mfma_f32_16x16x32_bf16 v[34:37], v[224:227], v[166:169], v[34:37]
	v_mfma_f32_16x16x32_bf16 v[22:25], v[216:219], v[200:203], v[22:25]
	v_mfma_f32_16x16x32_bf16 v[18:21], v[224:227], v[200:203], v[18:21]
	v_mfma_f32_16x16x32_bf16 v[6:9], v[216:219], v[208:211], v[6:9]
	v_mfma_f32_16x16x32_bf16 v[2:5], v[224:227], v[208:211], v[2:5]
	v_mfma_f32_16x16x32_bf16 v[54:57], v[220:223], v[162:165], v[54:57]
	v_mfma_f32_16x16x32_bf16 v[50:53], v[228:231], v[162:165], v[50:53]
	v_mfma_f32_16x16x32_bf16 v[38:41], v[220:223], v[170:173], v[38:41]
	v_mfma_f32_16x16x32_bf16 v[34:37], v[228:231], v[170:173], v[34:37]
	v_mfma_f32_16x16x32_bf16 v[22:25], v[220:223], v[204:207], v[22:25]
	v_mfma_f32_16x16x32_bf16 v[18:21], v[228:231], v[204:207], v[18:21]
	v_mfma_f32_16x16x32_bf16 v[6:9], v[220:223], v[212:215], v[6:9]
	v_mfma_f32_16x16x32_bf16 v[2:5], v[228:231], v[212:215], v[2:5]
	s_setprio 0
	s_add_i32 s54, s54, 2
	s_add_u32 s52, s52, 0x100
	s_addc_u32 s53, s53, 0
	s_cmp_gt_u32 s54, 13
	s_mov_b64 s[18:19], s[20:21]
	s_barrier
	s_cbranch_scc0 .LBB0_1482
	s_cmpk_gt_i32 s16, 0xff
	s_mov_b64 s[18:19], 0x30000
	s_cbranch_scc1 .LBB0_1478
	s_ashr_i32 s1, s16, 3
	s_mul_hi_i32 s19, s1, 0x1800
	s_mul_i32 s18, s1, 0x1800
	s_branch .LBB0_1478

; #define PG8_STAGE(bufoff, gbase, voff) do { _Pragma("unroll") for (int _i = 0; _i < 2; ++_i) \
;     __builtin_amdgcn_global_load_lds((const unsigned*)((const char*)(gbase) + (voff)[_i]), (PG8_LAS unsigned*)(lds + (bufoff) + ldsw + _i * 8192), 16, 0, 0); } while (0)
; #define PG8_LDA(dst, b, h) do { _Pragma("unroll") for (int m = 0; m < 4; ++m) _Pragma("unroll") for (int k = 0; k < 2; ++k) dst[m][k] = *(const PG8_LAS bf16x8*)(lds + PG8_SA(b, h) + aoff + m * 2048 + k * 1024); } while (0)
; #define PG8_LDB(dst, b, h) do { _Pragma("unroll") for (int n = 0; n < 2; ++n) _Pragma("unroll") for (int k = 0; k < 2; ++k) dst[n][k] = *(const PG8_LAS bf16x8*)(lds + PG8_SB(b, h) + boff + n * 2048 + k * 1024); } while (0)
; #define PG8_MMA(ai, bj, At, Bt) do { __builtin_amdgcn_s_setprio(1); _Pragma("unroll") for (int m = 0; m < 4; ++m) _Pragma("unroll") for (int n = 0; n < 2; ++n) _Pragma("unroll") for (int k = 0; k < 2; ++k) \
;     acc[ai][bj][m][n] = __builtin_amdgcn_mfma_f32_16x16x32_bf16(Bt[n][k], At[m][k], acc[ai][bj][m][n], 0, 0, 0); __builtin_amdgcn_s_setprio(0); } while (0)
; #define PG8_WAIT_V(n) asm volatile("s_waitcnt vmcnt(" #n ")" ::: "memory")
; #define PG8_WAIT_L(n) asm volatile("s_waitcnt lgkmcnt(" #n ")" ::: "memory")
; #define PG8_BAR __builtin_amdgcn_s_barrier()
; template <class Epi, class Sched>
; __device__ __forceinline__ void gemm_phase(PG8_LAS unsigned char* lds, const int lda, const int ldb, const Sched& S, const Epi& E) {
;     ...
;     for (int t = 0; t < nt; t += 2) {
;       const bool last = (t == nt - 2);
;       const char* a1 = cA + (size_t)(t + 1) * kstep;
;       const char* a2 = last ? nA : cA + (size_t)(t + 2) * kstep; const char* b2 = last ? nB : cB + (size_t)(t + 2) * kstep;
;       const char* a3 = a2 + kstep; const char* b3 = b2 + kstep;
;       PG8_LDB(B0, 0, 0); PG8_SCHED; PG8_LDA(At, 0, 0); PG8_STAGE(PG8_SA(1, 1), a1 + hstepA, voffA);
;       PG8_WAIT_L(8); PG8_BAR; PG8_WAIT_L(0); PG8_MMA(0, 0, At, B0); PG8_BAR; PG8_SCHED;
;       PG8_LDB(B1, 0, 1); PG8_STAGE(PG8_SB(0, 0), b2, voffB);
;       PG8_BAR; PG8_WAIT_L(0); PG8_MMA(0, 1, At, B1); PG8_BAR;
;       PG8_LDA(At, 0, 1); PG8_STAGE(PG8_SA(0, 0), a2, voffA);
;       PG8_BAR; PG8_WAIT_L(0); PG8_MMA(1, 0, At, B0); PG8_BAR; PG8_SCHED;
;       PG8_STAGE(PG8_SB(0, 1), b2 + hstepB, voffB);
;       PG8_WAIT_V(6); PG8_BAR; PG8_MMA(1, 1, At, B1); PG8_BAR;
.LBB0_1604:
	s_add_u32 s20, s18, 0xfffc0080
	s_addc_u32 s21, s19, -1
	s_add_i32 s33, 0, 0x10000
	v_add_u32_e32 v154, s33, v131
	ds_read_b128 v[142:145], v154
	ds_read_b128 v[146:149], v154 offset:1024
	ds_read_b128 v[150:153], v154 offset:2048
	ds_read_b128 v[154:157], v154 offset:3072
	s_cmp_eq_u32 s46, 12
	s_cselect_b32 s23, s11, s21
	s_cselect_b32 s22, s42, s20
	s_cselect_b32 s21, s1, s45
	s_cselect_b32 s20, s43, s44
	v_lshl_add_u64 v[174:175], s[18:19], 0, v[136:137]
	s_add_i32 m0, s17, 0xc000
	ds_read_b128 v[158:161], v141
	ds_read_b128 v[162:165], v141 offset:1024
	ds_read_b128 v[166:169], v141 offset:2048
	ds_read_b128 v[170:173], v141 offset:3072
	ds_read_b128 v[200:203], v141 offset:4096
	ds_read_b128 v[204:207], v141 offset:5120
	ds_read_b128 v[208:211], v141 offset:6144
	ds_read_b128 v[212:215], v141 offset:7168
	global_load_lds_dwordx4 v[174:175], off
	v_lshl_add_u64 v[174:175], s[18:19], 0, v[138:139]
	s_add_i32 m0, s17, 0xe000
	s_nop 0
	global_load_lds_dwordx4 v[174:175], off
	s_waitcnt lgkmcnt(8)
	s_barrier
	s_waitcnt lgkmcnt(0)
	s_setprio 1
	v_mfma_f32_16x16x32_bf16 v[126:129], v[142:145], v[158:161], v[126:129]
	v_mfma_f32_16x16x32_bf16 v[118:121], v[150:153], v[158:161], v[118:121]
	v_mfma_f32_16x16x32_bf16 v[110:113], v[142:145], v[166:169], v[110:113]
	v_mfma_f32_16x16x32_bf16 v[102:105], v[150:153], v[166:169], v[102:105]
	v_mfma_f32_16x16x32_bf16 v[94:97], v[142:145], v[200:203], v[94:97]
	v_mfma_f32_16x16x32_bf16 v[86:89], v[150:153], v[200:203], v[86:89]
	v_mfma_f32_16x16x32_bf16 v[78:81], v[142:145], v[208:211], v[78:81]
	v_mfma_f32_16x16x32_bf16 v[70:73], v[150:153], v[208:211], v[70:73]
	v_mfma_f32_16x16x32_bf16 v[126:129], v[146:149], v[162:165], v[126:129]
	v_mfma_f32_16x16x32_bf16 v[118:121], v[154:157], v[162:165], v[118:121]
	v_mfma_f32_16x16x32_bf16 v[110:113], v[146:149], v[170:173], v[110:113]
	v_mfma_f32_16x16x32_bf16 v[102:105], v[154:157], v[170:173], v[102:105]
	v_mfma_f32_16x16x32_bf16 v[94:97], v[146:149], v[204:207], v[94:97]
	v_mfma_f32_16x16x32_bf16 v[86:89], v[154:157], v[204:207], v[86:89]
	v_mfma_f32_16x16x32_bf16 v[78:81], v[146:149], v[212:215], v[78:81]
	v_mfma_f32_16x16x32_bf16 v[70:73], v[154:157], v[212:215], v[70:73]
	s_setprio 0
	s_barrier
	s_add_i32 s47, 0, 0x14000
	v_add_u32_e32 v174, s47, v131
	s_add_i32 s33, s33, s30
	ds_read_b128 v[216:219], v174
	ds_read_b128 v[220:223], v174 offset:1024
	ds_read_b128 v[224:227], v174 offset:2048
	ds_read_b128 v[228:231], v174 offset:3072
	v_lshl_add_u64 v[174:175], s[20:21], 0, v[134:135]
	s_mov_b32 m0, s33
	v_lshl_add_u64 v[182:183], s[20:21], 0, v[132:133]
	global_load_lds_dwordx4 v[174:175], off
	s_add_i32 m0, s33, 0x2000
	s_nop 0
	global_load_lds_dwordx4 v[182:183], off
	s_barrier
	s_waitcnt lgkmcnt(0)
	s_setprio 1
	v_mfma_f32_16x16x32_bf16 v[122:125], v[216:219], v[158:161], v[122:125]
	v_mfma_f32_16x16x32_bf16 v[114:117], v[224:227], v[158:161], v[114:117]
	v_mfma_f32_16x16x32_bf16 v[106:109], v[216:219], v[166:169], v[106:109]
	v_mfma_f32_16x16x32_bf16 v[98:101], v[224:227], v[166:169], v[98:101]
	v_mfma_f32_16x16x32_bf16 v[90:93], v[216:219], v[200:203], v[90:93]
	v_mfma_f32_16x16x32_bf16 v[82:85], v[224:227], v[200:203], v[82:85]
	v_mfma_f32_16x16x32_bf16 v[74:77], v[216:219], v[208:211], v[74:77]
	v_mfma_f32_16x16x32_bf16 v[66:69], v[224:227], v[208:211], v[66:69]
	v_mfma_f32_16x16x32_bf16 v[122:125], v[220:223], v[162:165], v[122:125]
	v_mfma_f32_16x16x32_bf16 v[114:117], v[228:231], v[162:165], v[114:117]
	v_mfma_f32_16x16x32_bf16 v[106:109], v[220:223], v[170:173], v[106:109]
	v_mfma_f32_16x16x32_bf16 v[98:101], v[228:231], v[170:173], v[98:101]
	v_mfma_f32_16x16x32_bf16 v[90:93], v[220:223], v[204:207], v[90:93]
	v_mfma_f32_16x16x32_bf16 v[82:85], v[228:231], v[204:207], v[82:85]
	v_mfma_f32_16x16x32_bf16 v[74:77], v[220:223], v[212:215], v[74:77]
	v_mfma_f32_16x16x32_bf16 v[66:69], v[228:231], v[212:215], v[66:69]
	s_setprio 0
	s_mov_b32 m0, s17
	v_lshl_add_u64 v[184:185], s[22:23], 0, v[134:135]
	s_barrier
	ds_read_b128 v[158:161], v141 offset:16384
	ds_read_b128 v[162:165], v141 offset:17408
	ds_read_b128 v[166:169], v141 offset:18432
	ds_read_b128 v[170:173], v141 offset:19456
	ds_read_b128 v[200:203], v141 offset:20480
	ds_read_b128 v[204:207], v141 offset:21504
	ds_read_b128 v[208:211], v141 offset:22528
	ds_read_b128 v[212:215], v141 offset:23552
	global_load_lds_dwordx4 v[184:185], off
	v_lshl_add_u64 v[232:233], s[22:23], 0, v[132:133]
	s_mov_b32 m0, s35
	s_nop 0
	global_load_lds_dwordx4 v[232:233], off
	s_barrier
	s_waitcnt lgkmcnt(0)
	s_setprio 1
	v_mfma_f32_16x16x32_bf16 v[62:65], v[142:145], v[158:161], v[62:65]
	v_mfma_f32_16x16x32_bf16 v[54:57], v[150:153], v[158:161], v[54:57]
	v_mfma_f32_16x16x32_bf16 v[46:49], v[142:145], v[166:169], v[46:49]
	v_mfma_f32_16x16x32_bf16 v[38:41], v[150:153], v[166:169], v[38:41]
	v_mfma_f32_16x16x32_bf16 v[30:33], v[142:145], v[200:203], v[30:33]
	v_mfma_f32_16x16x32_bf16 v[22:25], v[150:153], v[200:203], v[22:25]
	v_mfma_f32_16x16x32_bf16 v[14:17], v[142:145], v[208:211], v[14:17]
	v_mfma_f32_16x16x32_bf16 v[6:9], v[150:153], v[208:211], v[6:9]
	v_mfma_f32_16x16x32_bf16 v[62:65], v[146:149], v[162:165], v[62:65]
	v_mfma_f32_16x16x32_bf16 v[54:57], v[154:157], v[162:165], v[54:57]
	v_mfma_f32_16x16x32_bf16 v[46:49], v[146:149], v[170:173], v[46:49]
	v_mfma_f32_16x16x32_bf16 v[38:41], v[154:157], v[170:173], v[38:41]
	v_mfma_f32_16x16x32_bf16 v[30:33], v[146:149], v[204:207], v[30:33]
	v_mfma_f32_16x16x32_bf16 v[22:25], v[154:157], v[204:207], v[22:25]
	v_mfma_f32_16x16x32_bf16 v[14:17], v[146:149], v[212:215], v[14:17]
	v_mfma_f32_16x16x32_bf16 v[6:9], v[154:157], v[212:215], v[6:9]
	s_setprio 0
	s_barrier
; #define PG8_STAGE(bufoff, gbase, voff) do { _Pragma("unroll") for (int _i = 0; _i < 2; ++_i) \
;     __builtin_amdgcn_global_load_lds((const unsigned*)((const char*)(gbase) + (voff)[_i]), (PG8_LAS unsigned*)(lds + (bufoff) + ldsw + _i * 8192), 16, 0, 0); } while (0)
; #define PG8_LDA(dst, b, h) do { _Pragma("unroll") for (int m = 0; m < 4; ++m) _Pragma("unroll") for (int k = 0; k < 2; ++k) dst[m][k] = *(const PG8_LAS bf16x8*)(lds + PG8_SA(b, h) + aoff + m * 2048 + k * 1024); } while (0)
; #define PG8_LDB(dst, b, h) do { _Pragma("unroll") for (int n = 0; n < 2; ++n) _Pragma("unroll") for (int k = 0; k < 2; ++k) dst[n][k] = *(const PG8_LAS bf16x8*)(lds + PG8_SB(b, h) + boff + n * 2048 + k * 1024); } while (0)
; #define PG8_MMA(ai, bj, At, Bt) do { __builtin_amdgcn_s_setprio(1); _Pragma("unroll") for (int m = 0; m < 4; ++m) _Pragma("unroll") for (int n = 0; n < 2; ++n) _Pragma("unroll") for (int k = 0; k < 2; ++k) \
;     acc[ai][bj][m][n] = __builtin_amdgcn_mfma_f32_16x16x32_bf16(Bt[n][k], At[m][k], acc[ai][bj][m][n], 0, 0, 0); __builtin_amdgcn_s_setprio(0); } while (0)
; #define PG8_WAIT_V(n) asm volatile("s_waitcnt vmcnt(" #n ")" ::: "memory")
; #define PG8_WAIT_L(n) asm volatile("s_waitcnt lgkmcnt(" #n ")" ::: "memory")
; #define PG8_BAR __builtin_amdgcn_s_barrier()
; #define PG8_SCHED __builtin_amdgcn_sched_barrier(0)
; template <class Epi, class Sched>
; __device__ __forceinline__ void gemm_phase(PG8_LAS unsigned char* lds, const int lda, const int ldb, const Sched& S, const Epi& E) {
;     ...
;       PG8_STAGE(PG8_SB(0, 1), b2 + hstepB, voffB);
;       PG8_WAIT_V(6); PG8_BAR; PG8_MMA(1, 1, At, B1); PG8_BAR;
;       PG8_LDB(B0, 1, 0); PG8_SCHED; PG8_LDA(At, 1, 0); PG8_STAGE(PG8_SA(0, 1), a2 + hstepA, voffA);
;       PG8_WAIT_L(8); PG8_BAR; PG8_WAIT_L(0); PG8_MMA(0, 0, At, B0); PG8_BAR; PG8_SCHED;
;       PG8_LDB(B1, 1, 1); PG8_STAGE(PG8_SB(1, 0), b3, voffB);
;       PG8_BAR; PG8_WAIT_L(0); PG8_MMA(0, 1, At, B1); PG8_BAR;
;       PG8_LDA(At, 1, 1); PG8_STAGE(PG8_SA(1, 0), a3, voffA);
;       PG8_BAR; PG8_WAIT_L(0); PG8_MMA(1, 0, At, B0); PG8_BAR; PG8_SCHED;
	s_add_u32 s48, s20, 0x40000
	s_addc_u32 s49, s21, 0
	s_add_i32 s33, s47, s30
	v_lshl_add_u64 v[142:143], s[48:49], 0, v[134:135]
	s_mov_b32 m0, s33
	s_nop 0
	global_load_lds_dwordx4 v[142:143], off
	v_lshl_add_u64 v[142:143], s[48:49], 0, v[132:133]
	s_add_i32 m0, s33, 0x2000
	s_nop 0
	global_load_lds_dwordx4 v[142:143], off
	s_waitcnt vmcnt(6)
	s_barrier
	s_setprio 1
	v_mfma_f32_16x16x32_bf16 v[58:61], v[216:219], v[158:161], v[58:61]
	v_mfma_f32_16x16x32_bf16 v[50:53], v[224:227], v[158:161], v[50:53]
	v_mfma_f32_16x16x32_bf16 v[42:45], v[216:219], v[166:169], v[42:45]
	v_mfma_f32_16x16x32_bf16 v[34:37], v[224:227], v[166:169], v[34:37]
	v_mfma_f32_16x16x32_bf16 v[26:29], v[216:219], v[200:203], v[26:29]
	v_mfma_f32_16x16x32_bf16 v[18:21], v[224:227], v[200:203], v[18:21]
	v_mfma_f32_16x16x32_bf16 v[10:13], v[216:219], v[208:211], v[10:13]
	v_mfma_f32_16x16x32_bf16 v[2:5], v[224:227], v[208:211], v[2:5]
	v_mfma_f32_16x16x32_bf16 v[58:61], v[220:223], v[162:165], v[58:61]
	v_mfma_f32_16x16x32_bf16 v[50:53], v[228:231], v[162:165], v[50:53]
	v_mfma_f32_16x16x32_bf16 v[42:45], v[220:223], v[170:173], v[42:45]
	v_mfma_f32_16x16x32_bf16 v[34:37], v[228:231], v[170:173], v[34:37]
	v_mfma_f32_16x16x32_bf16 v[26:29], v[220:223], v[204:207], v[26:29]
	v_mfma_f32_16x16x32_bf16 v[18:21], v[228:231], v[204:207], v[18:21]
	v_mfma_f32_16x16x32_bf16 v[10:13], v[220:223], v[212:215], v[10:13]
	v_mfma_f32_16x16x32_bf16 v[2:5], v[228:231], v[212:215], v[2:5]
	s_setprio 0
	s_add_i32 s33, 0, 0x18000
	v_add_u32_e32 v154, s33, v131
	s_barrier
	ds_read_b128 v[142:145], v154
	ds_read_b128 v[146:149], v154 offset:1024
	ds_read_b128 v[150:153], v154 offset:2048
	ds_read_b128 v[154:157], v154 offset:3072
	s_add_u32 s22, s22, 0x40000
	s_addc_u32 s23, s23, 0
	s_mov_b32 m0, s36
	v_lshl_add_u64 v[216:217], s[22:23], 0, v[134:135]
	ds_read_b128 v[158:161], v141 offset:32768
	ds_read_b128 v[162:165], v141 offset:33792
	ds_read_b128 v[166:169], v141 offset:34816
	ds_read_b128 v[170:173], v141 offset:35840
	ds_read_b128 v[200:203], v141 offset:36864
	ds_read_b128 v[204:207], v141 offset:37888
	ds_read_b128 v[208:211], v141 offset:38912
	ds_read_b128 v[212:215], v141 offset:39936
	global_load_lds_dwordx4 v[216:217], off
	v_lshl_add_u64 v[216:217], s[22:23], 0, v[132:133]
	s_mov_b32 m0, s37
	s_nop 0
	global_load_lds_dwordx4 v[216:217], off
	s_waitcnt lgkmcnt(8)
	s_barrier
	s_waitcnt lgkmcnt(0)
	s_setprio 1
	v_mfma_f32_16x16x32_bf16 v[126:129], v[142:145], v[158:161], v[126:129]
	v_mfma_f32_16x16x32_bf16 v[118:121], v[150:153], v[158:161], v[118:121]
	v_mfma_f32_16x16x32_bf16 v[110:113], v[142:145], v[166:169], v[110:113]
	v_mfma_f32_16x16x32_bf16 v[102:105], v[150:153], v[166:169], v[102:105]
	v_mfma_f32_16x16x32_bf16 v[94:97], v[142:145], v[200:203], v[94:97]
	v_mfma_f32_16x16x32_bf16 v[86:89], v[150:153], v[200:203], v[86:89]
	v_mfma_f32_16x16x32_bf16 v[78:81], v[142:145], v[208:211], v[78:81]
	v_mfma_f32_16x16x32_bf16 v[70:73], v[150:153], v[208:211], v[70:73]
	v_mfma_f32_16x16x32_bf16 v[126:129], v[146:149], v[162:165], v[126:129]
	v_mfma_f32_16x16x32_bf16 v[118:121], v[154:157], v[162:165], v[118:121]
	v_mfma_f32_16x16x32_bf16 v[110:113], v[146:149], v[170:173], v[110:113]
	v_mfma_f32_16x16x32_bf16 v[102:105], v[154:157], v[170:173], v[102:105]
	v_mfma_f32_16x16x32_bf16 v[94:97], v[146:149], v[204:207], v[94:97]
	v_mfma_f32_16x16x32_bf16 v[86:89], v[154:157], v[204:207], v[86:89]
	v_mfma_f32_16x16x32_bf16 v[78:81], v[146:149], v[212:215], v[78:81]
	v_mfma_f32_16x16x32_bf16 v[70:73], v[154:157], v[212:215], v[70:73]
	s_setprio 0
	s_barrier
	s_add_i32 s22, 0, 0x1c000
	s_add_i32 s23, s33, s30
	v_add_u32_e32 v228, s22, v131
	v_lshl_add_u64 v[174:175], v[174:175], 0, s[86:87]
	s_mov_b32 m0, s23
	ds_read_b128 v[216:219], v228
	ds_read_b128 v[220:223], v228 offset:1024
	ds_read_b128 v[224:227], v228 offset:2048
	ds_read_b128 v[228:231], v228 offset:3072
	global_load_lds_dwordx4 v[174:175], off
	v_lshl_add_u64 v[174:175], v[182:183], 0, s[86:87]
	s_add_i32 m0, s23, 0x2000
	s_nop 0
	global_load_lds_dwordx4 v[174:175], off
	s_barrier
	s_waitcnt lgkmcnt(0)
	s_setprio 1
	v_mfma_f32_16x16x32_bf16 v[122:125], v[216:219], v[158:161], v[122:125]
	v_mfma_f32_16x16x32_bf16 v[114:117], v[224:227], v[158:161], v[114:117]
	v_mfma_f32_16x16x32_bf16 v[106:109], v[216:219], v[166:169], v[106:109]
	v_mfma_f32_16x16x32_bf16 v[98:101], v[224:227], v[166:169], v[98:101]
	v_mfma_f32_16x16x32_bf16 v[90:93], v[216:219], v[200:203], v[90:93]
	v_mfma_f32_16x16x32_bf16 v[82:85], v[224:227], v[200:203], v[82:85]
	v_mfma_f32_16x16x32_bf16 v[74:77], v[216:219], v[208:211], v[74:77]
	v_mfma_f32_16x16x32_bf16 v[66:69], v[224:227], v[208:211], v[66:69]
	v_mfma_f32_16x16x32_bf16 v[122:125], v[220:223], v[162:165], v[122:125]
	v_mfma_f32_16x16x32_bf16 v[114:117], v[228:231], v[162:165], v[114:117]
	v_mfma_f32_16x16x32_bf16 v[106:109], v[220:223], v[170:173], v[106:109]
	v_mfma_f32_16x16x32_bf16 v[98:101], v[228:231], v[170:173], v[98:101]
	v_mfma_f32_16x16x32_bf16 v[90:93], v[220:223], v[204:207], v[90:93]
	v_mfma_f32_16x16x32_bf16 v[82:85], v[228:231], v[204:207], v[82:85]
	v_mfma_f32_16x16x32_bf16 v[74:77], v[220:223], v[212:215], v[74:77]
	v_mfma_f32_16x16x32_bf16 v[66:69], v[228:231], v[212:215], v[66:69]
	s_setprio 0
	s_mov_b32 m0, s38
	v_lshl_add_u64 v[174:175], v[184:185], 0, s[86:87]
	s_barrier
	ds_read_b128 v[158:161], v141 offset:49152
	ds_read_b128 v[162:165], v141 offset:50176
	ds_read_b128 v[166:169], v141 offset:51200
	ds_read_b128 v[170:173], v141 offset:52224
	ds_read_b128 v[200:203], v141 offset:53248
	ds_read_b128 v[204:207], v141 offset:54272
	ds_read_b128 v[208:211], v141 offset:55296
	ds_read_b128 v[212:215], v141 offset:56320
	global_load_lds_dwordx4 v[174:175], off
	v_lshl_add_u64 v[174:175], v[232:233], 0, s[86:87]
	s_mov_b32 m0, s39
	s_nop 0
	global_load_lds_dwordx4 v[174:175], off
	s_barrier
; __device__ __forceinline__ float silu_f(float x) { return x * sigm(x); }
; #define PG8_STAGE(bufoff, gbase, voff) do { _Pragma("unroll") for (int _i = 0; _i < 2; ++_i) \
;     __builtin_amdgcn_global_load_lds((const unsigned*)((const char*)(gbase) + (voff)[_i]), (PG8_LAS unsigned*)(lds + (bufoff) + ldsw + _i * 8192), 16, 0, 0); } while (0)
; #define PG8_MMA(ai, bj, At, Bt) do { __builtin_amdgcn_s_setprio(1); _Pragma("unroll") for (int m = 0; m < 4; ++m) _Pragma("unroll") for (int n = 0; n < 2; ++n) _Pragma("unroll") for (int k = 0; k < 2; ++k) \
;     acc[ai][bj][m][n] = __builtin_amdgcn_mfma_f32_16x16x32_bf16(Bt[n][k], At[m][k], acc[ai][bj][m][n], 0, 0, 0); __builtin_amdgcn_s_setprio(0); } while (0)
; #define PG8_WAIT_V(n) asm volatile("s_waitcnt vmcnt(" #n ")" ::: "memory")
; #define PG8_WAIT_L(n) asm volatile("s_waitcnt lgkmcnt(" #n ")" ::: "memory")
; #define PG8_BAR __builtin_amdgcn_s_barrier()
; #define PG8_SCHED __builtin_amdgcn_sched_barrier(0)
; template <class Epi, class Sched>
; __device__ __forceinline__ void gemm_phase(PG8_LAS unsigned char* lds, const int lda, const int ldb, const Sched& S, const Epi& E) {
;     ...
;       PG8_BAR; PG8_WAIT_L(0); PG8_MMA(1, 0, At, B0); PG8_BAR; PG8_SCHED;
;       PG8_STAGE(PG8_SB(1, 1), b3 + hstepB, voffB);
;       PG8_WAIT_V(6); PG8_BAR; PG8_MMA(1, 1, At, B1); PG8_BAR;
;     }
;   __device__ __forceinline__ void operator()(const f32x4 (&acc)[2][2][4][2], const Unit& u, int wr, int wc, int fr, int fq) const {
;     ...
;         const int r = u.pm * 256 + ai * 128 + wr * 64 + m * 16 + fr;
; #pragma unroll
;         for (int n = 0; n < 2; ++n) {
;           const f32x4 g = acc[ai][0][m][n], up = acc[ai][1][m][n];
;           const int c = u.pn * 128 + wc * 32 + n * 16 + 4 * fq;
;           uint2 w;
;           w.x = pack2(silu_f(g[0]) * up[0], silu_f(g[1]) * up[1]);
;           w.y = pack2(silu_f(g[2]) * up[2], silu_f(g[3]) * up[3]);
;           *reinterpret_cast<uint2*>(HID + (size_t)r * DFF + c) = w;
	s_waitcnt lgkmcnt(0)
	s_setprio 1
	v_mfma_f32_16x16x32_bf16 v[62:65], v[142:145], v[158:161], v[62:65]
	v_mfma_f32_16x16x32_bf16 v[54:57], v[150:153], v[158:161], v[54:57]
	v_mfma_f32_16x16x32_bf16 v[46:49], v[142:145], v[166:169], v[46:49]
	v_mfma_f32_16x16x32_bf16 v[38:41], v[150:153], v[166:169], v[38:41]
	v_mfma_f32_16x16x32_bf16 v[30:33], v[142:145], v[200:203], v[30:33]
	v_mfma_f32_16x16x32_bf16 v[22:25], v[150:153], v[200:203], v[22:25]
	v_mfma_f32_16x16x32_bf16 v[14:17], v[142:145], v[208:211], v[14:17]
	v_mfma_f32_16x16x32_bf16 v[6:9], v[150:153], v[208:211], v[6:9]
	v_mfma_f32_16x16x32_bf16 v[62:65], v[146:149], v[162:165], v[62:65]
	v_mfma_f32_16x16x32_bf16 v[54:57], v[154:157], v[162:165], v[54:57]
	v_mfma_f32_16x16x32_bf16 v[46:49], v[146:149], v[170:173], v[46:49]
	v_mfma_f32_16x16x32_bf16 v[38:41], v[154:157], v[170:173], v[38:41]
	v_mfma_f32_16x16x32_bf16 v[30:33], v[146:149], v[204:207], v[30:33]
	v_mfma_f32_16x16x32_bf16 v[22:25], v[154:157], v[204:207], v[22:25]
	v_mfma_f32_16x16x32_bf16 v[14:17], v[146:149], v[212:215], v[14:17]
	v_mfma_f32_16x16x32_bf16 v[6:9], v[154:157], v[212:215], v[6:9]
	s_setprio 0
	s_barrier
	s_add_u32 s20, s20, 0x40080
	s_addc_u32 s21, s21, 0
	s_add_i32 s22, s22, s30
	v_lshl_add_u64 v[142:143], s[20:21], 0, v[134:135]
	s_mov_b32 m0, s22
	s_nop 0
	global_load_lds_dwordx4 v[142:143], off
	v_lshl_add_u64 v[142:143], s[20:21], 0, v[132:133]
	s_add_i32 m0, s22, 0x2000
	s_nop 0
	global_load_lds_dwordx4 v[142:143], off
	s_waitcnt vmcnt(6)
	s_barrier
	s_setprio 1
	v_mfma_f32_16x16x32_bf16 v[58:61], v[216:219], v[158:161], v[58:61]
	v_mfma_f32_16x16x32_bf16 v[50:53], v[224:227], v[158:161], v[50:53]
	v_mfma_f32_16x16x32_bf16 v[42:45], v[216:219], v[166:169], v[42:45]
	v_mfma_f32_16x16x32_bf16 v[34:37], v[224:227], v[166:169], v[34:37]
	v_mfma_f32_16x16x32_bf16 v[26:29], v[216:219], v[200:203], v[26:29]
	v_mfma_f32_16x16x32_bf16 v[18:21], v[224:227], v[200:203], v[18:21]
	v_mfma_f32_16x16x32_bf16 v[10:13], v[216:219], v[208:211], v[10:13]
	v_mfma_f32_16x16x32_bf16 v[2:5], v[224:227], v[208:211], v[2:5]
	v_mfma_f32_16x16x32_bf16 v[58:61], v[220:223], v[162:165], v[58:61]
	v_mfma_f32_16x16x32_bf16 v[50:53], v[228:231], v[162:165], v[50:53]
	v_mfma_f32_16x16x32_bf16 v[42:45], v[220:223], v[170:173], v[42:45]
	v_mfma_f32_16x16x32_bf16 v[34:37], v[228:231], v[170:173], v[34:37]
	v_mfma_f32_16x16x32_bf16 v[26:29], v[220:223], v[204:207], v[26:29]
	v_mfma_f32_16x16x32_bf16 v[18:21], v[228:231], v[204:207], v[18:21]
	v_mfma_f32_16x16x32_bf16 v[10:13], v[220:223], v[212:215], v[10:13]
	v_mfma_f32_16x16x32_bf16 v[2:5], v[228:231], v[212:215], v[2:5]
	s_setprio 0
	s_add_i32 s46, s46, 2
	s_add_u32 s18, s18, 0x100
	s_addc_u32 s19, s19, 0
	s_add_u32 s44, s44, 0x100
	s_addc_u32 s45, s45, 0
	s_cmp_gt_u32 s46, 13
	s_barrier
	s_cbranch_scc0 .LBB0_1604
	v_mul_f32_e32 v143, 0xbfb8aa3b, v126
	v_exp_f32_e32 v143, v143
	v_lshl_or_b32 v144, s41, 7, v140
	v_lshl_add_u32 v142, s16, 8, v1
	v_ashrrev_i32_e32 v145, 31, v144
	v_add_f32_e32 v143, 1.0, v143
	v_rcp_f32_e32 v146, v143
	v_mul_f32_e32 v143, 0xbfb8aa3b, v127
	v_exp_f32_e32 v143, v143
	s_and_b64 vcc, exec, s[6:7]
	s_mov_b32 s41, s0
	s_mov_b32 s16, s10
	v_add_f32_e32 v143, 1.0, v143
	v_rcp_f32_e32 v147, v143
	s_mov_b64 s[20:21], s[14:15]
	v_pk_mul_f32 v[126:127], v[126:127], v[146:147]
	s_nop 0
	v_pk_mul_f32 v[122:123], v[126:127], v[122:123]
	s_nop 0
	v_cvt_pk_bf16_f32 v126, v122, v123
	v_mul_f32_e32 v122, 0xbfb8aa3b, v128
	v_mul_f32_e32 v123, 0xbfb8aa3b, v129
	v_exp_f32_e32 v122, v122
	v_exp_f32_e32 v123, v123
	v_add_f32_e32 v122, 1.0, v122
	v_add_f32_e32 v123, 1.0, v123
	v_rcp_f32_e32 v122, v122
	v_rcp_f32_e32 v123, v123
	s_nop 0
	v_pk_mul_f32 v[122:123], v[128:129], v[122:123]
	s_nop 0
	v_pk_mul_f32 v[122:123], v[122:123], v[124:125]
	v_lshlrev_b64 v[124:125], 1, v[144:145]
	v_cvt_pk_bf16_f32 v127, v122, v123
	v_mov_b64_e32 v[122:123], s[84:85]
	v_mad_i64_i32 v[128:129], s[18:19], v142, s50, v[122:123]
	v_lshl_add_u64 v[128:129], v[128:129], 0, v[124:125]
	global_store_dwordx2 v[128:129], v[126:127], off
	v_mul_f32_e32 v126, 0xbfb8aa3b, v118
	v_mul_f32_e32 v127, 0xbfb8aa3b, v119
	v_exp_f32_e32 v126, v126
	v_exp_f32_e32 v127, v127
	v_add_f32_e32 v126, 1.0, v126
	v_add_f32_e32 v127, 1.0, v127
	v_rcp_f32_e32 v126, v126
	v_rcp_f32_e32 v127, v127
	s_nop 0
	v_pk_mul_f32 v[118:119], v[118:119], v[126:127]
	s_nop 0
	v_pk_mul_f32 v[114:115], v[118:119], v[114:115]
	s_nop 0
	v_cvt_pk_bf16_f32 v114, v114, v115
	v_mul_f32_e32 v115, 0xbfb8aa3b, v120
	v_exp_f32_e32 v115, v115
	s_nop 0
	v_add_f32_e32 v115, 1.0, v115
	v_rcp_f32_e32 v118, v115
	v_mul_f32_e32 v115, 0xbfb8aa3b, v121
	v_exp_f32_e32 v115, v115
	s_nop 0
	v_add_f32_e32 v115, 1.0, v115
	v_rcp_f32_e32 v119, v115
	s_nop 0
	v_pk_mul_f32 v[118:119], v[120:121], v[118:119]
	s_nop 0
	v_pk_mul_f32 v[116:117], v[118:119], v[116:117]
	s_nop 0
	v_cvt_pk_bf16_f32 v115, v116, v117
	global_store_dwordx2 v[128:129], v[114:115], off offset:32
	v_mul_f32_e32 v114, 0xbfb8aa3b, v110
	v_mul_f32_e32 v115, 0xbfb8aa3b, v111
	v_exp_f32_e32 v114, v114
	v_exp_f32_e32 v115, v115
	v_or_b32_e32 v116, 16, v142
	v_add_f32_e32 v114, 1.0, v114
	v_add_f32_e32 v115, 1.0, v115
	v_rcp_f32_e32 v114, v114
	v_rcp_f32_e32 v115, v115
	s_nop 0
	v_pk_mul_f32 v[110:111], v[110:111], v[114:115]
	s_nop 0
	v_pk_mul_f32 v[106:107], v[110:111], v[106:107]
	s_nop 0
	v_cvt_pk_bf16_f32 v106, v106, v107
	v_mul_f32_e32 v107, 0xbfb8aa3b, v112
	v_exp_f32_e32 v107, v107
	s_nop 0
	v_add_f32_e32 v107, 1.0, v107
	v_rcp_f32_e32 v110, v107
	v_mul_f32_e32 v107, 0xbfb8aa3b, v113
	v_exp_f32_e32 v107, v107
	s_nop 0
	v_add_f32_e32 v107, 1.0, v107
	v_rcp_f32_e32 v111, v107
	s_nop 0
; __device__ __forceinline__ float silu_f(float x) { return x * sigm(x); }
;   __device__ __forceinline__ void operator()(const f32x4 (&acc)[2][2][4][2], const Unit& u, int wr, int wc, int fr, int fq) const {
;     ...
;         const int r = u.pm * 256 + ai * 128 + wr * 64 + m * 16 + fr;
; #pragma unroll
;         for (int n = 0; n < 2; ++n) {
;           const f32x4 g = acc[ai][0][m][n], up = acc[ai][1][m][n];
;           const int c = u.pn * 128 + wc * 32 + n * 16 + 4 * fq;
;           uint2 w;
;           w.x = pack2(silu_f(g[0]) * up[0], silu_f(g[1]) * up[1]);
;           w.y = pack2(silu_f(g[2]) * up[2], silu_f(g[3]) * up[3]);
;           *reinterpret_cast<uint2*>(HID + (size_t)r * DFF + c) = w;
	v_pk_mul_f32 v[110:111], v[112:113], v[110:111]
	s_nop 0
	v_pk_mul_f32 v[108:109], v[110:111], v[108:109]
	s_nop 0
	v_cvt_pk_bf16_f32 v107, v108, v109
	v_mad_i64_i32 v[108:109], s[18:19], v116, s50, v[122:123]
	v_lshl_add_u64 v[108:109], v[108:109], 0, v[124:125]
	global_store_dwordx2 v[108:109], v[106:107], off
	v_mul_f32_e32 v106, 0xbfb8aa3b, v102
	v_mul_f32_e32 v107, 0xbfb8aa3b, v103
	v_exp_f32_e32 v106, v106
	v_exp_f32_e32 v107, v107
	v_add_f32_e32 v106, 1.0, v106
	v_add_f32_e32 v107, 1.0, v107
	v_rcp_f32_e32 v106, v106
	v_rcp_f32_e32 v107, v107
	s_nop 0
	v_pk_mul_f32 v[102:103], v[102:103], v[106:107]
	s_nop 0
	v_pk_mul_f32 v[98:99], v[102:103], v[98:99]
	s_nop 0
	v_cvt_pk_bf16_f32 v98, v98, v99
	v_mul_f32_e32 v99, 0xbfb8aa3b, v104
	v_exp_f32_e32 v99, v99
	s_nop 0
	v_add_f32_e32 v99, 1.0, v99
	v_rcp_f32_e32 v102, v99
	v_mul_f32_e32 v99, 0xbfb8aa3b, v105
	v_exp_f32_e32 v99, v99
	s_nop 0
	v_add_f32_e32 v99, 1.0, v99
	v_rcp_f32_e32 v103, v99
	s_nop 0
	v_pk_mul_f32 v[102:103], v[104:105], v[102:103]
	s_nop 0
	v_pk_mul_f32 v[100:101], v[102:103], v[100:101]
	s_nop 0
	v_cvt_pk_bf16_f32 v99, v100, v101
	global_store_dwordx2 v[108:109], v[98:99], off offset:32
	v_mul_f32_e32 v98, 0xbfb8aa3b, v94
	v_mul_f32_e32 v99, 0xbfb8aa3b, v95
	v_exp_f32_e32 v98, v98
	v_exp_f32_e32 v99, v99
	v_or_b32_e32 v100, 32, v142
	v_add_f32_e32 v98, 1.0, v98
	v_add_f32_e32 v99, 1.0, v99
	v_rcp_f32_e32 v98, v98
	v_rcp_f32_e32 v99, v99
	s_nop 0
	v_pk_mul_f32 v[94:95], v[94:95], v[98:99]
	s_nop 0
	v_pk_mul_f32 v[90:91], v[94:95], v[90:91]
	s_nop 0
	v_cvt_pk_bf16_f32 v90, v90, v91
	v_mul_f32_e32 v91, 0xbfb8aa3b, v96
	v_exp_f32_e32 v91, v91
	s_nop 0
	v_add_f32_e32 v91, 1.0, v91
	v_rcp_f32_e32 v94, v91
	v_mul_f32_e32 v91, 0xbfb8aa3b, v97
	v_exp_f32_e32 v91, v91
	s_nop 0
	v_add_f32_e32 v91, 1.0, v91
	v_rcp_f32_e32 v95, v91
	s_nop 0
	v_pk_mul_f32 v[94:95], v[96:97], v[94:95]
	s_nop 0
	v_pk_mul_f32 v[92:93], v[94:95], v[92:93]
	s_nop 0
	v_cvt_pk_bf16_f32 v91, v92, v93
	v_mad_i64_i32 v[92:93], s[18:19], v100, s50, v[122:123]
	v_lshl_add_u64 v[92:93], v[92:93], 0, v[124:125]
	global_store_dwordx2 v[92:93], v[90:91], off
	v_mul_f32_e32 v90, 0xbfb8aa3b, v86
	v_mul_f32_e32 v91, 0xbfb8aa3b, v87
	v_exp_f32_e32 v90, v90
	v_exp_f32_e32 v91, v91
	v_add_f32_e32 v90, 1.0, v90
	v_add_f32_e32 v91, 1.0, v91
	v_rcp_f32_e32 v90, v90
	v_rcp_f32_e32 v91, v91
	s_nop 0
	v_pk_mul_f32 v[86:87], v[86:87], v[90:91]
	s_nop 0
	v_pk_mul_f32 v[82:83], v[86:87], v[82:83]
	s_nop 0
	v_cvt_pk_bf16_f32 v82, v82, v83
	v_mul_f32_e32 v83, 0xbfb8aa3b, v88
	v_exp_f32_e32 v83, v83
	s_nop 0
	v_add_f32_e32 v83, 1.0, v83
	v_rcp_f32_e32 v86, v83
	v_mul_f32_e32 v83, 0xbfb8aa3b, v89
	v_exp_f32_e32 v83, v83
	s_nop 0
	v_add_f32_e32 v83, 1.0, v83
	v_rcp_f32_e32 v87, v83
	s_nop 0
	v_pk_mul_f32 v[86:87], v[88:89], v[86:87]
	s_nop 0
	v_pk_mul_f32 v[84:85], v[86:87], v[84:85]
	s_nop 0
	v_cvt_pk_bf16_f32 v83, v84, v85
	global_store_dwordx2 v[92:93], v[82:83], off offset:32
	v_mul_f32_e32 v82, 0xbfb8aa3b, v78
	v_mul_f32_e32 v83, 0xbfb8aa3b, v79
	v_exp_f32_e32 v82, v82
	v_exp_f32_e32 v83, v83
	v_or_b32_e32 v84, 48, v142
	v_add_f32_e32 v82, 1.0, v82
	v_add_f32_e32 v83, 1.0, v83
	v_rcp_f32_e32 v82, v82
	v_rcp_f32_e32 v83, v83
	s_nop 0
	v_pk_mul_f32 v[78:79], v[78:79], v[82:83]
	s_nop 0
	v_pk_mul_f32 v[74:75], v[78:79], v[74:75]
	s_nop 0
	v_cvt_pk_bf16_f32 v74, v74, v75
	v_mul_f32_e32 v75, 0xbfb8aa3b, v80
	v_exp_f32_e32 v75, v75
	s_nop 0
	v_add_f32_e32 v75, 1.0, v75
	v_rcp_f32_e32 v78, v75
	v_mul_f32_e32 v75, 0xbfb8aa3b, v81
	v_exp_f32_e32 v75, v75
	s_nop 0
	v_add_f32_e32 v75, 1.0, v75
	v_rcp_f32_e32 v79, v75
	s_nop 0
	v_pk_mul_f32 v[78:79], v[80:81], v[78:79]
	s_nop 0
	v_pk_mul_f32 v[76:77], v[78:79], v[76:77]
	s_nop 0
	v_cvt_pk_bf16_f32 v75, v76, v77
	v_mad_i64_i32 v[76:77], s[18:19], v84, s50, v[122:123]
	v_lshl_add_u64 v[76:77], v[76:77], 0, v[124:125]
	global_store_dwordx2 v[76:77], v[74:75], off
	v_mul_f32_e32 v74, 0xbfb8aa3b, v70
	v_mul_f32_e32 v75, 0xbfb8aa3b, v71
	v_exp_f32_e32 v74, v74
	v_exp_f32_e32 v75, v75
	v_add_f32_e32 v74, 1.0, v74
	v_add_f32_e32 v75, 1.0, v75
	v_rcp_f32_e32 v74, v74
	v_rcp_f32_e32 v75, v75
	s_nop 0
	v_pk_mul_f32 v[70:71], v[70:71], v[74:75]
	s_nop 0
	v_pk_mul_f32 v[66:67], v[70:71], v[66:67]
	s_nop 0
	v_cvt_pk_bf16_f32 v66, v66, v67
	v_mul_f32_e32 v67, 0xbfb8aa3b, v72
	v_exp_f32_e32 v67, v67
	s_nop 0
	v_add_f32_e32 v67, 1.0, v67
	v_rcp_f32_e32 v70, v67
	v_mul_f32_e32 v67, 0xbfb8aa3b, v73
	v_exp_f32_e32 v67, v67
	s_nop 0
	v_add_f32_e32 v67, 1.0, v67
	v_rcp_f32_e32 v71, v67
	s_nop 0
	v_pk_mul_f32 v[70:71], v[72:73], v[70:71]
	s_nop 0
	v_pk_mul_f32 v[68:69], v[70:71], v[68:69]
	s_nop 0
	v_cvt_pk_bf16_f32 v67, v68, v69
	global_store_dwordx2 v[76:77], v[66:67], off offset:32
	v_mul_f32_e32 v66, 0xbfb8aa3b, v62
	v_mul_f32_e32 v67, 0xbfb8aa3b, v63
	v_exp_f32_e32 v66, v66
	v_exp_f32_e32 v67, v67
	v_add_u32_e32 v68, 0x80, v142
	v_add_f32_e32 v66, 1.0, v66
	v_add_f32_e32 v67, 1.0, v67
	v_rcp_f32_e32 v66, v66
	v_rcp_f32_e32 v67, v67
	s_nop 0
	v_pk_mul_f32 v[62:63], v[62:63], v[66:67]
	s_nop 0
	v_pk_mul_f32 v[58:59], v[62:63], v[58:59]
	s_nop 0
	v_cvt_pk_bf16_f32 v58, v58, v59
	v_mul_f32_e32 v59, 0xbfb8aa3b, v64
	v_exp_f32_e32 v59, v59
	s_nop 0
	v_add_f32_e32 v59, 1.0, v59
	v_rcp_f32_e32 v62, v59
	v_mul_f32_e32 v59, 0xbfb8aa3b, v65
	v_exp_f32_e32 v59, v59
	s_nop 0
	v_add_f32_e32 v59, 1.0, v59
	v_rcp_f32_e32 v63, v59
	s_nop 0
	v_pk_mul_f32 v[62:63], v[64:65], v[62:63]
	s_nop 0
	v_pk_mul_f32 v[60:61], v[62:63], v[60:61]
	s_nop 0
	v_cvt_pk_bf16_f32 v59, v60, v61
	v_mad_i64_i32 v[60:61], s[18:19], v68, s50, v[122:123]
	v_lshl_add_u64 v[60:61], v[60:61], 0, v[124:125]
	global_store_dwordx2 v[60:61], v[58:59], off
; __device__ __forceinline__ float silu_f(float x) { return x * sigm(x); }
; #define PG8_WAIT_V(n) asm volatile("s_waitcnt vmcnt(" #n ")" ::: "memory")
; #define PG8_BAR __builtin_amdgcn_s_barrier()
;   __device__ __forceinline__ int kt(const Unit& u) const { return ((u.pn & 7) < 4) ? 4 : 16; }
; template <class Epi, class Sched>
; __device__ __forceinline__ void gemm_phase(PG8_LAS unsigned char* lds, const int lda, const int ldb, const Sched& S, const Epi& E) {
;     ...
;     E(acc, cur, wr, wc, fr, fq);
;     if (!has_next) break;
; #pragma unroll
;     for (int a = 0; a < 2; ++a)
; #pragma unroll
;       for (int b = 0; b < 2; ++b)
; #pragma unroll
;         for (int m = 0; m < 4; ++m)
; #pragma unroll
;           for (int n = 0; n < 2; ++n) acc[a][b][m][n] = (f32x4){0.f, 0.f, 0.f, 0.f};
;     cur = nxt; cA = nA; cB = nB; ++ui;
;     nt = S.kt(cur);
;   }
;   PG8_WAIT_V(0);
;   if (wr == 0) PG8_BAR;
;   PG8_BAR;
;   __device__ __forceinline__ void operator()(const f32x4 (&acc)[2][2][4][2], const Unit& u, int wr, int wc, int fr, int fq) const {
;     ...
;         for (int n = 0; n < 2; ++n) {
;           const f32x4 g = acc[ai][0][m][n], up = acc[ai][1][m][n];
;           const int c = u.pn * 128 + wc * 32 + n * 16 + 4 * fq;
;           uint2 w;
;           w.x = pack2(silu_f(g[0]) * up[0], silu_f(g[1]) * up[1]);
;           w.y = pack2(silu_f(g[2]) * up[2], silu_f(g[3]) * up[3]);
;           *reinterpret_cast<uint2*>(HID + (size_t)r * DFF + c) = w;
	v_mul_f32_e32 v58, 0xbfb8aa3b, v54
	v_mul_f32_e32 v59, 0xbfb8aa3b, v55
	v_exp_f32_e32 v58, v58
	v_exp_f32_e32 v59, v59
	v_add_f32_e32 v58, 1.0, v58
	v_add_f32_e32 v59, 1.0, v59
	v_rcp_f32_e32 v58, v58
	v_rcp_f32_e32 v59, v59
	s_nop 0
	v_pk_mul_f32 v[54:55], v[54:55], v[58:59]
	s_nop 0
	v_pk_mul_f32 v[50:51], v[54:55], v[50:51]
	s_nop 0
	v_cvt_pk_bf16_f32 v50, v50, v51
	v_mul_f32_e32 v51, 0xbfb8aa3b, v56
	v_exp_f32_e32 v51, v51
	s_nop 0
	v_add_f32_e32 v51, 1.0, v51
	v_rcp_f32_e32 v54, v51
	v_mul_f32_e32 v51, 0xbfb8aa3b, v57
	v_exp_f32_e32 v51, v51
	s_nop 0
	v_add_f32_e32 v51, 1.0, v51
	v_rcp_f32_e32 v55, v51
	s_nop 0
	v_pk_mul_f32 v[54:55], v[56:57], v[54:55]
	s_nop 0
	v_pk_mul_f32 v[52:53], v[54:55], v[52:53]
	s_nop 0
	v_cvt_pk_bf16_f32 v51, v52, v53
	global_store_dwordx2 v[60:61], v[50:51], off offset:32
	v_mul_f32_e32 v50, 0xbfb8aa3b, v46
	v_mul_f32_e32 v51, 0xbfb8aa3b, v47
	v_exp_f32_e32 v50, v50
	v_exp_f32_e32 v51, v51
	v_add_u32_e32 v52, 0x90, v142
	v_add_f32_e32 v50, 1.0, v50
	v_add_f32_e32 v51, 1.0, v51
	v_rcp_f32_e32 v50, v50
	v_rcp_f32_e32 v51, v51
	s_nop 0
	v_pk_mul_f32 v[46:47], v[46:47], v[50:51]
	s_nop 0
	v_pk_mul_f32 v[42:43], v[46:47], v[42:43]
	s_nop 0
	v_cvt_pk_bf16_f32 v42, v42, v43
	v_mul_f32_e32 v43, 0xbfb8aa3b, v48
	v_exp_f32_e32 v43, v43
	s_nop 0
	v_add_f32_e32 v43, 1.0, v43
	v_rcp_f32_e32 v46, v43
	v_mul_f32_e32 v43, 0xbfb8aa3b, v49
	v_exp_f32_e32 v43, v43
	s_nop 0
	v_add_f32_e32 v43, 1.0, v43
	v_rcp_f32_e32 v47, v43
	s_nop 0
	v_pk_mul_f32 v[46:47], v[48:49], v[46:47]
	s_nop 0
	v_pk_mul_f32 v[44:45], v[46:47], v[44:45]
	s_nop 0
	v_cvt_pk_bf16_f32 v43, v44, v45
	v_mad_i64_i32 v[44:45], s[18:19], v52, s50, v[122:123]
	v_lshl_add_u64 v[44:45], v[44:45], 0, v[124:125]
	global_store_dwordx2 v[44:45], v[42:43], off
	v_mul_f32_e32 v42, 0xbfb8aa3b, v38
	v_mul_f32_e32 v43, 0xbfb8aa3b, v39
	v_exp_f32_e32 v42, v42
	v_exp_f32_e32 v43, v43
	v_add_f32_e32 v42, 1.0, v42
	v_add_f32_e32 v43, 1.0, v43
	v_rcp_f32_e32 v42, v42
	v_rcp_f32_e32 v43, v43
	s_nop 0
	v_pk_mul_f32 v[38:39], v[38:39], v[42:43]
	s_nop 0
	v_pk_mul_f32 v[34:35], v[38:39], v[34:35]
	s_nop 0
	v_cvt_pk_bf16_f32 v34, v34, v35
	v_mul_f32_e32 v35, 0xbfb8aa3b, v40
	v_exp_f32_e32 v35, v35
	s_nop 0
	v_add_f32_e32 v35, 1.0, v35
	v_rcp_f32_e32 v38, v35
	v_mul_f32_e32 v35, 0xbfb8aa3b, v41
	v_exp_f32_e32 v35, v35
	s_nop 0
	v_add_f32_e32 v35, 1.0, v35
	v_rcp_f32_e32 v39, v35
	s_nop 0
	v_pk_mul_f32 v[38:39], v[40:41], v[38:39]
	s_nop 0
	v_pk_mul_f32 v[36:37], v[38:39], v[36:37]
	s_nop 0
	v_cvt_pk_bf16_f32 v35, v36, v37
	global_store_dwordx2 v[44:45], v[34:35], off offset:32
	v_mul_f32_e32 v34, 0xbfb8aa3b, v30
	v_mul_f32_e32 v35, 0xbfb8aa3b, v31
	v_exp_f32_e32 v34, v34
	v_exp_f32_e32 v35, v35
	v_add_u32_e32 v36, 0xa0, v142
	v_add_f32_e32 v34, 1.0, v34
	v_add_f32_e32 v35, 1.0, v35
	v_rcp_f32_e32 v34, v34
	v_rcp_f32_e32 v35, v35
	s_nop 0
	v_pk_mul_f32 v[30:31], v[30:31], v[34:35]
	s_nop 0
	v_pk_mul_f32 v[26:27], v[30:31], v[26:27]
	s_nop 0
	v_cvt_pk_bf16_f32 v26, v26, v27
	v_mul_f32_e32 v27, 0xbfb8aa3b, v32
	v_exp_f32_e32 v27, v27
	s_nop 0
	v_add_f32_e32 v27, 1.0, v27
	v_rcp_f32_e32 v30, v27
	v_mul_f32_e32 v27, 0xbfb8aa3b, v33
	v_exp_f32_e32 v27, v27
	s_nop 0
	v_add_f32_e32 v27, 1.0, v27
	v_rcp_f32_e32 v31, v27
	s_nop 0
	v_pk_mul_f32 v[30:31], v[32:33], v[30:31]
	s_nop 0
	v_pk_mul_f32 v[28:29], v[30:31], v[28:29]
	s_nop 0
	v_cvt_pk_bf16_f32 v27, v28, v29
	v_mad_i64_i32 v[28:29], s[18:19], v36, s50, v[122:123]
	v_lshl_add_u64 v[28:29], v[28:29], 0, v[124:125]
	global_store_dwordx2 v[28:29], v[26:27], off
	v_mul_f32_e32 v26, 0xbfb8aa3b, v22
	v_mul_f32_e32 v27, 0xbfb8aa3b, v23
	v_exp_f32_e32 v26, v26
	v_exp_f32_e32 v27, v27
	v_add_f32_e32 v26, 1.0, v26
	v_add_f32_e32 v27, 1.0, v27
	v_rcp_f32_e32 v26, v26
	v_rcp_f32_e32 v27, v27
	s_nop 0
	v_pk_mul_f32 v[22:23], v[22:23], v[26:27]
	s_nop 0
	v_pk_mul_f32 v[18:19], v[22:23], v[18:19]
	s_nop 0
	v_cvt_pk_bf16_f32 v18, v18, v19
	v_mul_f32_e32 v19, 0xbfb8aa3b, v24
	v_exp_f32_e32 v19, v19
	s_nop 0
	v_add_f32_e32 v19, 1.0, v19
	v_rcp_f32_e32 v22, v19
	v_mul_f32_e32 v19, 0xbfb8aa3b, v25
	v_exp_f32_e32 v19, v19
	s_nop 0
	v_add_f32_e32 v19, 1.0, v19
	v_rcp_f32_e32 v23, v19
	s_nop 0
	v_pk_mul_f32 v[22:23], v[24:25], v[22:23]
	s_nop 0
	v_pk_mul_f32 v[20:21], v[22:23], v[20:21]
	s_nop 0
	v_cvt_pk_bf16_f32 v19, v20, v21
	global_store_dwordx2 v[28:29], v[18:19], off offset:32
	v_mul_f32_e32 v18, 0xbfb8aa3b, v14
	v_mul_f32_e32 v19, 0xbfb8aa3b, v15
	v_exp_f32_e32 v18, v18
	v_exp_f32_e32 v19, v19
	v_add_u32_e32 v20, 0xb0, v142
	v_add_f32_e32 v18, 1.0, v18
	v_add_f32_e32 v19, 1.0, v19
	v_rcp_f32_e32 v18, v18
	v_rcp_f32_e32 v19, v19
	s_nop 0
	v_pk_mul_f32 v[14:15], v[14:15], v[18:19]
	s_nop 0
	v_pk_mul_f32 v[10:11], v[14:15], v[10:11]
	s_nop 0
	v_cvt_pk_bf16_f32 v10, v10, v11
	v_mul_f32_e32 v11, 0xbfb8aa3b, v16
	v_exp_f32_e32 v11, v11
	s_nop 0
	v_add_f32_e32 v11, 1.0, v11
	v_rcp_f32_e32 v14, v11
	v_mul_f32_e32 v11, 0xbfb8aa3b, v17
	v_exp_f32_e32 v11, v11
	s_nop 0
	v_add_f32_e32 v11, 1.0, v11
	v_rcp_f32_e32 v15, v11
	s_nop 0
	v_pk_mul_f32 v[14:15], v[16:17], v[14:15]
	s_nop 0
	v_pk_mul_f32 v[12:13], v[14:15], v[12:13]
	s_nop 0
	v_cvt_pk_bf16_f32 v11, v12, v13
	v_mad_i64_i32 v[12:13], s[18:19], v20, s50, v[122:123]
	v_lshl_add_u64 v[12:13], v[12:13], 0, v[124:125]
	global_store_dwordx2 v[12:13], v[10:11], off
	v_mul_f32_e32 v10, 0xbfb8aa3b, v6
	v_mul_f32_e32 v11, 0xbfb8aa3b, v7
	v_exp_f32_e32 v10, v10
	v_exp_f32_e32 v11, v11
	s_mov_b64 s[18:19], s[12:13]
	v_add_f32_e32 v10, 1.0, v10
	v_add_f32_e32 v11, 1.0, v11
	v_rcp_f32_e32 v10, v10
	v_rcp_f32_e32 v11, v11
	s_nop 0
	v_pk_mul_f32 v[6:7], v[6:7], v[10:11]
	s_nop 0
	v_pk_mul_f32 v[2:3], v[6:7], v[2:3]
	s_nop 0
	v_cvt_pk_bf16_f32 v2, v2, v3
	v_mul_f32_e32 v3, 0xbfb8aa3b, v8
	v_exp_f32_e32 v3, v3
	s_nop 0
	v_add_f32_e32 v3, 1.0, v3
	v_rcp_f32_e32 v6, v3
	v_mul_f32_e32 v3, 0xbfb8aa3b, v9
	v_exp_f32_e32 v3, v3
	s_nop 0
	v_add_f32_e32 v3, 1.0, v3
	v_rcp_f32_e32 v7, v3
	s_nop 0
	v_pk_mul_f32 v[6:7], v[8:9], v[6:7]
	s_nop 0
	v_pk_mul_f32 v[4:5], v[6:7], v[4:5]
	s_nop 0
	v_cvt_pk_bf16_f32 v3, v4, v5
	global_store_dwordx2 v[12:13], v[2:3], off offset:32
	s_cbranch_vccz .LBB0_1601
	s_waitcnt vmcnt(0)
	v_readlane_b32 s40, v253, 12
	s_cmpk_gt_u32 s9, 0xff
	v_readlane_b32 s41, v253, 13
	v_readlane_b32 s44, v253, 16
	v_readlane_b32 s45, v253, 17
	v_readlane_b32 s52, v253, 24
	v_readlane_b32 s53, v253, 25
	v_readlane_b32 s54, v253, 26
	v_readlane_b32 s55, v253, 27
	v_readlane_b32 s38, v255, 23
	v_readlane_b32 s42, v253, 14
	v_readlane_b32 s43, v253, 15
	v_readlane_b32 s46, v253, 18
	v_readlane_b32 s47, v253, 19
	v_readlane_b32 s48, v253, 20
	v_readlane_b32 s49, v253, 21
	v_readlane_b32 s50, v253, 22
	v_readlane_b32 s51, v253, 23
	v_readlane_b32 s39, v255, 24
	s_cbranch_scc1 .LBB0_1608
	s_barrier

; #define PG8_STAGE(bufoff, gbase, voff) do { _Pragma("unroll") for (int _i = 0; _i < 2; ++_i) \
;     __builtin_amdgcn_global_load_lds((const unsigned*)((const char*)(gbase) + (voff)[_i]), (PG8_LAS unsigned*)(lds + (bufoff) + ldsw + _i * 8192), 16, 0, 0); } while (0)
; #define PG8_LDA(dst, b, h) do { _Pragma("unroll") for (int m = 0; m < 4; ++m) _Pragma("unroll") for (int k = 0; k < 2; ++k) dst[m][k] = *(const PG8_LAS bf16x8*)(lds + PG8_SA(b, h) + aoff + m * 2048 + k * 1024); } while (0)
; #define PG8_LDB(dst, b, h) do { _Pragma("unroll") for (int n = 0; n < 2; ++n) _Pragma("unroll") for (int k = 0; k < 2; ++k) dst[n][k] = *(const PG8_LAS bf16x8*)(lds + PG8_SB(b, h) + boff + n * 2048 + k * 1024); } while (0)
; #define PG8_MMA(ai, bj, At, Bt) do { __builtin_amdgcn_s_setprio(1); _Pragma("unroll") for (int m = 0; m < 4; ++m) _Pragma("unroll") for (int n = 0; n < 2; ++n) _Pragma("unroll") for (int k = 0; k < 2; ++k) \
;     acc[ai][bj][m][n] = __builtin_amdgcn_mfma_f32_16x16x32_bf16(Bt[n][k], At[m][k], acc[ai][bj][m][n], 0, 0, 0); __builtin_amdgcn_s_setprio(0); } while (0)
; #define PG8_WAIT_V(n) asm volatile("s_waitcnt vmcnt(" #n ")" ::: "memory")
; #define PG8_WAIT_L(n) asm volatile("s_waitcnt lgkmcnt(" #n ")" ::: "memory")
; #define PG8_BAR __builtin_amdgcn_s_barrier()
; template <class Epi, class Sched>
; __device__ __forceinline__ void gemm_phase(PG8_LAS unsigned char* lds, const int lda, const int ldb, const Sched& S, const Epi& E) {
;     ...
;     for (int t = 0; t < nt; t += 2) {
;       const bool last = (t == nt - 2);
;       const char* a1 = cA + (size_t)(t + 1) * kstep;
;       const char* a2 = last ? nA : cA + (size_t)(t + 2) * kstep; const char* b2 = last ? nB : cB + (size_t)(t + 2) * kstep;
;       const char* a3 = a2 + kstep; const char* b3 = b2 + kstep;
;       PG8_LDB(B0, 0, 0); PG8_SCHED; PG8_LDA(At, 0, 0); PG8_STAGE(PG8_SA(1, 1), a1 + hstepA, voffA);
;       PG8_WAIT_L(8); PG8_BAR; PG8_WAIT_L(0); PG8_MMA(0, 0, At, B0); PG8_BAR; PG8_SCHED;
;       PG8_LDB(B1, 0, 1); PG8_STAGE(PG8_SB(0, 0), b2, voffB);
;       PG8_BAR; PG8_WAIT_L(0); PG8_MMA(0, 1, At, B1); PG8_BAR;
;       PG8_LDA(At, 0, 1); PG8_STAGE(PG8_SA(0, 0), a2, voffA);
;       PG8_BAR; PG8_WAIT_L(0); PG8_MMA(1, 0, At, B0); PG8_BAR; PG8_SCHED;
;       PG8_STAGE(PG8_SB(0, 1), b2 + hstepB, voffB);
;       PG8_WAIT_V(6); PG8_BAR; PG8_MMA(1, 1, At, B1); PG8_BAR;
.LBB0_1673:
	s_add_u32 s12, s10, 0x100
	s_addc_u32 s13, s11, 0
	s_add_i32 s33, 0, 0x10000
	v_add_u32_e32 v154, s33, v131
	ds_read_b128 v[140:143], v154
	ds_read_b128 v[146:149], v154 offset:1024
	ds_read_b128 v[150:153], v154 offset:2048
	ds_read_b128 v[154:157], v154 offset:3072
	s_cmp_eq_u32 s41, 40
	s_cselect_b32 s17, s7, s13
	s_cselect_b32 s16, s6, s12
	s_cselect_b32 s15, s1, s40
	s_cselect_b32 s14, s0, s39
	v_lshl_add_u64 v[174:175], s[10:11], 0, v[136:137]
	s_add_i32 m0, s23, 0xc000
	ds_read_b128 v[158:161], v145
	ds_read_b128 v[162:165], v145 offset:1024
	ds_read_b128 v[166:169], v145 offset:2048
	ds_read_b128 v[170:173], v145 offset:3072
	ds_read_b128 v[200:203], v145 offset:4096
	ds_read_b128 v[204:207], v145 offset:5120
	ds_read_b128 v[208:211], v145 offset:6144
	ds_read_b128 v[212:215], v145 offset:7168
	global_load_lds_dwordx4 v[174:175], off
	v_lshl_add_u64 v[174:175], s[10:11], 0, v[138:139]
	s_add_i32 m0, s23, 0xe000
	s_nop 0
	global_load_lds_dwordx4 v[174:175], off
	s_waitcnt lgkmcnt(8)
	s_barrier
	s_waitcnt lgkmcnt(0)
	s_setprio 1
	v_mfma_f32_16x16x32_bf16 v[126:129], v[140:143], v[158:161], v[126:129]
	v_mfma_f32_16x16x32_bf16 v[122:125], v[150:153], v[158:161], v[122:125]
	v_mfma_f32_16x16x32_bf16 v[110:113], v[140:143], v[166:169], v[110:113]
	v_mfma_f32_16x16x32_bf16 v[106:109], v[150:153], v[166:169], v[106:109]
	v_mfma_f32_16x16x32_bf16 v[94:97], v[140:143], v[200:203], v[94:97]
	v_mfma_f32_16x16x32_bf16 v[90:93], v[150:153], v[200:203], v[90:93]
	v_mfma_f32_16x16x32_bf16 v[78:81], v[140:143], v[208:211], v[78:81]
	v_mfma_f32_16x16x32_bf16 v[74:77], v[150:153], v[208:211], v[74:77]
	v_mfma_f32_16x16x32_bf16 v[126:129], v[146:149], v[162:165], v[126:129]
	v_mfma_f32_16x16x32_bf16 v[122:125], v[154:157], v[162:165], v[122:125]
	v_mfma_f32_16x16x32_bf16 v[110:113], v[146:149], v[170:173], v[110:113]
	v_mfma_f32_16x16x32_bf16 v[106:109], v[154:157], v[170:173], v[106:109]
	v_mfma_f32_16x16x32_bf16 v[94:97], v[146:149], v[204:207], v[94:97]
	v_mfma_f32_16x16x32_bf16 v[90:93], v[154:157], v[204:207], v[90:93]
	v_mfma_f32_16x16x32_bf16 v[78:81], v[146:149], v[212:215], v[78:81]
	v_mfma_f32_16x16x32_bf16 v[74:77], v[154:157], v[212:215], v[74:77]
	s_setprio 0
	s_barrier
	s_add_i32 s42, 0, 0x14000
	v_add_u32_e32 v174, s42, v131
	s_add_i32 s10, s33, s20
	ds_read_b128 v[216:219], v174
	ds_read_b128 v[220:223], v174 offset:1024
	ds_read_b128 v[224:227], v174 offset:2048
	ds_read_b128 v[228:231], v174 offset:3072
	v_lshl_add_u64 v[174:175], s[14:15], 0, v[134:135]
	s_mov_b32 m0, s10
	v_lshl_add_u64 v[182:183], s[14:15], 0, v[132:133]
	global_load_lds_dwordx4 v[174:175], off
	s_add_i32 m0, s10, 0x2000
	s_nop 0
	global_load_lds_dwordx4 v[182:183], off
	s_barrier
	s_waitcnt lgkmcnt(0)
	s_setprio 1
	v_mfma_f32_16x16x32_bf16 v[118:121], v[216:219], v[158:161], v[118:121]
	v_mfma_f32_16x16x32_bf16 v[114:117], v[224:227], v[158:161], v[114:117]
	v_mfma_f32_16x16x32_bf16 v[102:105], v[216:219], v[166:169], v[102:105]
	v_mfma_f32_16x16x32_bf16 v[98:101], v[224:227], v[166:169], v[98:101]
	v_mfma_f32_16x16x32_bf16 v[86:89], v[216:219], v[200:203], v[86:89]
	v_mfma_f32_16x16x32_bf16 v[82:85], v[224:227], v[200:203], v[82:85]
	v_mfma_f32_16x16x32_bf16 v[70:73], v[216:219], v[208:211], v[70:73]
	v_mfma_f32_16x16x32_bf16 v[66:69], v[224:227], v[208:211], v[66:69]
	v_mfma_f32_16x16x32_bf16 v[118:121], v[220:223], v[162:165], v[118:121]
	v_mfma_f32_16x16x32_bf16 v[114:117], v[228:231], v[162:165], v[114:117]
	v_mfma_f32_16x16x32_bf16 v[102:105], v[220:223], v[170:173], v[102:105]
	v_mfma_f32_16x16x32_bf16 v[98:101], v[228:231], v[170:173], v[98:101]
	v_mfma_f32_16x16x32_bf16 v[86:89], v[220:223], v[204:207], v[86:89]
	v_mfma_f32_16x16x32_bf16 v[82:85], v[228:231], v[204:207], v[82:85]
	v_mfma_f32_16x16x32_bf16 v[70:73], v[220:223], v[212:215], v[70:73]
	v_mfma_f32_16x16x32_bf16 v[66:69], v[228:231], v[212:215], v[66:69]
	s_setprio 0
	s_mov_b32 m0, s23
	v_lshl_add_u64 v[184:185], s[16:17], 0, v[134:135]
	s_barrier
	ds_read_b128 v[158:161], v145 offset:16384
	ds_read_b128 v[162:165], v145 offset:17408
	ds_read_b128 v[166:169], v145 offset:18432
	ds_read_b128 v[170:173], v145 offset:19456
	ds_read_b128 v[200:203], v145 offset:20480
	ds_read_b128 v[204:207], v145 offset:21504
	ds_read_b128 v[208:211], v145 offset:22528
	ds_read_b128 v[212:215], v145 offset:23552
	global_load_lds_dwordx4 v[184:185], off
	v_lshl_add_u64 v[232:233], s[16:17], 0, v[132:133]
	s_mov_b32 m0, s24
	s_nop 0
	global_load_lds_dwordx4 v[232:233], off
	s_barrier
	s_waitcnt lgkmcnt(0)
	s_setprio 1
	v_mfma_f32_16x16x32_bf16 v[62:65], v[140:143], v[158:161], v[62:65]
	v_mfma_f32_16x16x32_bf16 v[58:61], v[150:153], v[158:161], v[58:61]
	v_mfma_f32_16x16x32_bf16 v[46:49], v[140:143], v[166:169], v[46:49]
	v_mfma_f32_16x16x32_bf16 v[42:45], v[150:153], v[166:169], v[42:45]
	v_mfma_f32_16x16x32_bf16 v[30:33], v[140:143], v[200:203], v[30:33]
	v_mfma_f32_16x16x32_bf16 v[26:29], v[150:153], v[200:203], v[26:29]
	v_mfma_f32_16x16x32_bf16 v[14:17], v[140:143], v[208:211], v[14:17]
	v_mfma_f32_16x16x32_bf16 v[10:13], v[150:153], v[208:211], v[10:13]
	v_mfma_f32_16x16x32_bf16 v[62:65], v[146:149], v[162:165], v[62:65]
	v_mfma_f32_16x16x32_bf16 v[58:61], v[154:157], v[162:165], v[58:61]
	v_mfma_f32_16x16x32_bf16 v[46:49], v[146:149], v[170:173], v[46:49]
	v_mfma_f32_16x16x32_bf16 v[42:45], v[154:157], v[170:173], v[42:45]
	v_mfma_f32_16x16x32_bf16 v[30:33], v[146:149], v[204:207], v[30:33]
	v_mfma_f32_16x16x32_bf16 v[26:29], v[154:157], v[204:207], v[26:29]
	v_mfma_f32_16x16x32_bf16 v[14:17], v[146:149], v[212:215], v[14:17]
	v_mfma_f32_16x16x32_bf16 v[10:13], v[154:157], v[212:215], v[10:13]
	s_setprio 0
	s_barrier
; #define PG8_STAGE(bufoff, gbase, voff) do { _Pragma("unroll") for (int _i = 0; _i < 2; ++_i) \
;     __builtin_amdgcn_global_load_lds((const unsigned*)((const char*)(gbase) + (voff)[_i]), (PG8_LAS unsigned*)(lds + (bufoff) + ldsw + _i * 8192), 16, 0, 0); } while (0)
; #define PG8_LDA(dst, b, h) do { _Pragma("unroll") for (int m = 0; m < 4; ++m) _Pragma("unroll") for (int k = 0; k < 2; ++k) dst[m][k] = *(const PG8_LAS bf16x8*)(lds + PG8_SA(b, h) + aoff + m * 2048 + k * 1024); } while (0)
; #define PG8_LDB(dst, b, h) do { _Pragma("unroll") for (int n = 0; n < 2; ++n) _Pragma("unroll") for (int k = 0; k < 2; ++k) dst[n][k] = *(const PG8_LAS bf16x8*)(lds + PG8_SB(b, h) + boff + n * 2048 + k * 1024); } while (0)
; #define PG8_MMA(ai, bj, At, Bt) do { __builtin_amdgcn_s_setprio(1); _Pragma("unroll") for (int m = 0; m < 4; ++m) _Pragma("unroll") for (int n = 0; n < 2; ++n) _Pragma("unroll") for (int k = 0; k < 2; ++k) \
;     acc[ai][bj][m][n] = __builtin_amdgcn_mfma_f32_16x16x32_bf16(Bt[n][k], At[m][k], acc[ai][bj][m][n], 0, 0, 0); __builtin_amdgcn_s_setprio(0); } while (0)
; #define PG8_WAIT_V(n) asm volatile("s_waitcnt vmcnt(" #n ")" ::: "memory")
; #define PG8_WAIT_L(n) asm volatile("s_waitcnt lgkmcnt(" #n ")" ::: "memory")
; #define PG8_BAR __builtin_amdgcn_s_barrier()
; #define PG8_SCHED __builtin_amdgcn_sched_barrier(0)
; template <class Epi, class Sched>
; __device__ __forceinline__ void gemm_phase(PG8_LAS unsigned char* lds, const int lda, const int ldb, const Sched& S, const Epi& E) {
;     ...
;       PG8_STAGE(PG8_SB(0, 1), b2 + hstepB, voffB);
;       PG8_WAIT_V(6); PG8_BAR; PG8_MMA(1, 1, At, B1); PG8_BAR;
;       PG8_LDB(B0, 1, 0); PG8_SCHED; PG8_LDA(At, 1, 0); PG8_STAGE(PG8_SA(0, 1), a2 + hstepA, voffA);
;       PG8_WAIT_L(8); PG8_BAR; PG8_WAIT_L(0); PG8_MMA(0, 0, At, B0); PG8_BAR; PG8_SCHED;
;       PG8_LDB(B1, 1, 1); PG8_STAGE(PG8_SB(1, 0), b3, voffB);
	s_add_u32 s10, s14, 0xb0000
	s_addc_u32 s11, s15, 0
	s_add_i32 s33, s42, s20
	v_lshl_add_u64 v[140:141], s[10:11], 0, v[134:135]
	s_mov_b32 m0, s33
	s_nop 0
	global_load_lds_dwordx4 v[140:141], off
	v_lshl_add_u64 v[140:141], s[10:11], 0, v[132:133]
	s_add_i32 m0, s33, 0x2000
	s_nop 0
	global_load_lds_dwordx4 v[140:141], off
	s_waitcnt vmcnt(6)
	s_barrier
	s_setprio 1
	v_mfma_f32_16x16x32_bf16 v[54:57], v[216:219], v[158:161], v[54:57]
	v_mfma_f32_16x16x32_bf16 v[50:53], v[224:227], v[158:161], v[50:53]
	v_mfma_f32_16x16x32_bf16 v[38:41], v[216:219], v[166:169], v[38:41]
	v_mfma_f32_16x16x32_bf16 v[34:37], v[224:227], v[166:169], v[34:37]
	v_mfma_f32_16x16x32_bf16 v[22:25], v[216:219], v[200:203], v[22:25]
	v_mfma_f32_16x16x32_bf16 v[18:21], v[224:227], v[200:203], v[18:21]
	v_mfma_f32_16x16x32_bf16 v[6:9], v[216:219], v[208:211], v[6:9]
	v_mfma_f32_16x16x32_bf16 v[2:5], v[224:227], v[208:211], v[2:5]
	v_mfma_f32_16x16x32_bf16 v[54:57], v[220:223], v[162:165], v[54:57]
	v_mfma_f32_16x16x32_bf16 v[50:53], v[228:231], v[162:165], v[50:53]
	v_mfma_f32_16x16x32_bf16 v[38:41], v[220:223], v[170:173], v[38:41]
	v_mfma_f32_16x16x32_bf16 v[34:37], v[228:231], v[170:173], v[34:37]
	v_mfma_f32_16x16x32_bf16 v[22:25], v[220:223], v[204:207], v[22:25]
	v_mfma_f32_16x16x32_bf16 v[18:21], v[228:231], v[204:207], v[18:21]
	v_mfma_f32_16x16x32_bf16 v[6:9], v[220:223], v[212:215], v[6:9]
	v_mfma_f32_16x16x32_bf16 v[2:5], v[228:231], v[212:215], v[2:5]
	s_setprio 0
	s_add_i32 s33, 0, 0x18000
	v_add_u32_e32 v154, s33, v131
	s_barrier
	ds_read_b128 v[140:143], v154
	ds_read_b128 v[146:149], v154 offset:1024
	ds_read_b128 v[150:153], v154 offset:2048
	ds_read_b128 v[154:157], v154 offset:3072
	s_add_u32 s10, s16, 0xb0000
	s_addc_u32 s11, s17, 0
	s_mov_b32 m0, s25
	v_lshl_add_u64 v[216:217], s[10:11], 0, v[134:135]
	ds_read_b128 v[158:161], v145 offset:32768
	ds_read_b128 v[162:165], v145 offset:33792
	ds_read_b128 v[166:169], v145 offset:34816
	ds_read_b128 v[170:173], v145 offset:35840
	ds_read_b128 v[200:203], v145 offset:36864
	ds_read_b128 v[204:207], v145 offset:37888
	ds_read_b128 v[208:211], v145 offset:38912
	ds_read_b128 v[212:215], v145 offset:39936
	global_load_lds_dwordx4 v[216:217], off
	v_lshl_add_u64 v[216:217], s[10:11], 0, v[132:133]
	s_mov_b32 m0, s26
	s_nop 0
	global_load_lds_dwordx4 v[216:217], off
	s_waitcnt lgkmcnt(8)
	s_barrier
	s_waitcnt lgkmcnt(0)
	s_setprio 1
	v_mfma_f32_16x16x32_bf16 v[126:129], v[140:143], v[158:161], v[126:129]
	v_mfma_f32_16x16x32_bf16 v[122:125], v[150:153], v[158:161], v[122:125]
	v_mfma_f32_16x16x32_bf16 v[110:113], v[140:143], v[166:169], v[110:113]
	v_mfma_f32_16x16x32_bf16 v[106:109], v[150:153], v[166:169], v[106:109]
	v_mfma_f32_16x16x32_bf16 v[94:97], v[140:143], v[200:203], v[94:97]
	v_mfma_f32_16x16x32_bf16 v[90:93], v[150:153], v[200:203], v[90:93]
	v_mfma_f32_16x16x32_bf16 v[78:81], v[140:143], v[208:211], v[78:81]
	v_mfma_f32_16x16x32_bf16 v[74:77], v[150:153], v[208:211], v[74:77]
	v_mfma_f32_16x16x32_bf16 v[126:129], v[146:149], v[162:165], v[126:129]
	v_mfma_f32_16x16x32_bf16 v[122:125], v[154:157], v[162:165], v[122:125]
	v_mfma_f32_16x16x32_bf16 v[110:113], v[146:149], v[170:173], v[110:113]
	v_mfma_f32_16x16x32_bf16 v[106:109], v[154:157], v[170:173], v[106:109]
	v_mfma_f32_16x16x32_bf16 v[94:97], v[146:149], v[204:207], v[94:97]
	v_mfma_f32_16x16x32_bf16 v[90:93], v[154:157], v[204:207], v[90:93]
	v_mfma_f32_16x16x32_bf16 v[78:81], v[146:149], v[212:215], v[78:81]
	v_mfma_f32_16x16x32_bf16 v[74:77], v[154:157], v[212:215], v[74:77]
	s_setprio 0
	s_barrier
	s_add_i32 s16, 0, 0x1c000
	s_add_i32 s10, s33, s20
	v_add_u32_e32 v228, s16, v131
	v_lshl_add_u64 v[174:175], v[174:175], 0, s[86:87]
	s_mov_b32 m0, s10
	ds_read_b128 v[216:219], v228
	ds_read_b128 v[220:223], v228 offset:1024
	ds_read_b128 v[224:227], v228 offset:2048
	ds_read_b128 v[228:231], v228 offset:3072
	global_load_lds_dwordx4 v[174:175], off
	v_lshl_add_u64 v[174:175], v[182:183], 0, s[86:87]
	s_add_i32 m0, s10, 0x2000
	s_nop 0
	global_load_lds_dwordx4 v[174:175], off
	s_barrier
; #define PG8_STAGE(bufoff, gbase, voff) do { _Pragma("unroll") for (int _i = 0; _i < 2; ++_i) \
;     __builtin_amdgcn_global_load_lds((const unsigned*)((const char*)(gbase) + (voff)[_i]), (PG8_LAS unsigned*)(lds + (bufoff) + ldsw + _i * 8192), 16, 0, 0); } while (0)
; #define PG8_LDA(dst, b, h) do { _Pragma("unroll") for (int m = 0; m < 4; ++m) _Pragma("unroll") for (int k = 0; k < 2; ++k) dst[m][k] = *(const PG8_LAS bf16x8*)(lds + PG8_SA(b, h) + aoff + m * 2048 + k * 1024); } while (0)
; #define PG8_MMA(ai, bj, At, Bt) do { __builtin_amdgcn_s_setprio(1); _Pragma("unroll") for (int m = 0; m < 4; ++m) _Pragma("unroll") for (int n = 0; n < 2; ++n) _Pragma("unroll") for (int k = 0; k < 2; ++k) \
;     acc[ai][bj][m][n] = __builtin_amdgcn_mfma_f32_16x16x32_bf16(Bt[n][k], At[m][k], acc[ai][bj][m][n], 0, 0, 0); __builtin_amdgcn_s_setprio(0); } while (0)
; #define PG8_WAIT_V(n) asm volatile("s_waitcnt vmcnt(" #n ")" ::: "memory")
; #define PG8_WAIT_L(n) asm volatile("s_waitcnt lgkmcnt(" #n ")" ::: "memory")
; #define PG8_BAR __builtin_amdgcn_s_barrier()
; #define PG8_SCHED __builtin_amdgcn_sched_barrier(0)
; template <class Epi, class Sched>
; __device__ __forceinline__ void gemm_phase(PG8_LAS unsigned char* lds, const int lda, const int ldb, const Sched& S, const Epi& E) {
;     ...
;       PG8_BAR; PG8_WAIT_L(0); PG8_MMA(0, 1, At, B1); PG8_BAR;
;       PG8_LDA(At, 1, 1); PG8_STAGE(PG8_SA(1, 0), a3, voffA);
;       PG8_BAR; PG8_WAIT_L(0); PG8_MMA(1, 0, At, B0); PG8_BAR; PG8_SCHED;
;       PG8_STAGE(PG8_SB(1, 1), b3 + hstepB, voffB);
;       PG8_WAIT_V(6); PG8_BAR; PG8_MMA(1, 1, At, B1); PG8_BAR;
;     }
;   __device__ __forceinline__ void operator()(const f32x4 (&acc)[2][2][4][2], const Unit& u, int wr, int wc, int fr, int fq) const {
;     const int mr = (u.pm * 256 < ML) ? ((u.pm * 256) >> 11) : 32;
;     const float* gp = mod + (size_t)mr * 6144 + gate_off;
	s_waitcnt lgkmcnt(0)
	s_setprio 1
	v_mfma_f32_16x16x32_bf16 v[118:121], v[216:219], v[158:161], v[118:121]
	v_mfma_f32_16x16x32_bf16 v[114:117], v[224:227], v[158:161], v[114:117]
	v_mfma_f32_16x16x32_bf16 v[102:105], v[216:219], v[166:169], v[102:105]
	v_mfma_f32_16x16x32_bf16 v[98:101], v[224:227], v[166:169], v[98:101]
	v_mfma_f32_16x16x32_bf16 v[86:89], v[216:219], v[200:203], v[86:89]
	v_mfma_f32_16x16x32_bf16 v[82:85], v[224:227], v[200:203], v[82:85]
	v_mfma_f32_16x16x32_bf16 v[70:73], v[216:219], v[208:211], v[70:73]
	v_mfma_f32_16x16x32_bf16 v[66:69], v[224:227], v[208:211], v[66:69]
	v_mfma_f32_16x16x32_bf16 v[118:121], v[220:223], v[162:165], v[118:121]
	v_mfma_f32_16x16x32_bf16 v[114:117], v[228:231], v[162:165], v[114:117]
	v_mfma_f32_16x16x32_bf16 v[102:105], v[220:223], v[170:173], v[102:105]
	v_mfma_f32_16x16x32_bf16 v[98:101], v[228:231], v[170:173], v[98:101]
	v_mfma_f32_16x16x32_bf16 v[86:89], v[220:223], v[204:207], v[86:89]
	v_mfma_f32_16x16x32_bf16 v[82:85], v[228:231], v[204:207], v[82:85]
	v_mfma_f32_16x16x32_bf16 v[70:73], v[220:223], v[212:215], v[70:73]
	v_mfma_f32_16x16x32_bf16 v[66:69], v[228:231], v[212:215], v[66:69]
	s_setprio 0
	s_mov_b32 m0, s28
	v_lshl_add_u64 v[174:175], v[184:185], 0, s[86:87]
	s_barrier
	ds_read_b128 v[158:161], v145 offset:49152
	ds_read_b128 v[162:165], v145 offset:50176
	ds_read_b128 v[166:169], v145 offset:51200
	ds_read_b128 v[170:173], v145 offset:52224
	ds_read_b128 v[200:203], v145 offset:53248
	ds_read_b128 v[204:207], v145 offset:54272
	ds_read_b128 v[208:211], v145 offset:55296
	ds_read_b128 v[212:215], v145 offset:56320
	global_load_lds_dwordx4 v[174:175], off
	v_lshl_add_u64 v[174:175], v[232:233], 0, s[86:87]
	s_mov_b32 m0, s29
	s_nop 0
	global_load_lds_dwordx4 v[174:175], off
	s_barrier
	s_waitcnt lgkmcnt(0)
	s_setprio 1
	v_mfma_f32_16x16x32_bf16 v[62:65], v[140:143], v[158:161], v[62:65]
	v_mfma_f32_16x16x32_bf16 v[58:61], v[150:153], v[158:161], v[58:61]
	v_mfma_f32_16x16x32_bf16 v[46:49], v[140:143], v[166:169], v[46:49]
	v_mfma_f32_16x16x32_bf16 v[42:45], v[150:153], v[166:169], v[42:45]
	v_mfma_f32_16x16x32_bf16 v[30:33], v[140:143], v[200:203], v[30:33]
	v_mfma_f32_16x16x32_bf16 v[26:29], v[150:153], v[200:203], v[26:29]
	v_mfma_f32_16x16x32_bf16 v[14:17], v[140:143], v[208:211], v[14:17]
	v_mfma_f32_16x16x32_bf16 v[10:13], v[150:153], v[208:211], v[10:13]
	v_mfma_f32_16x16x32_bf16 v[62:65], v[146:149], v[162:165], v[62:65]
	v_mfma_f32_16x16x32_bf16 v[58:61], v[154:157], v[162:165], v[58:61]
	v_mfma_f32_16x16x32_bf16 v[46:49], v[146:149], v[170:173], v[46:49]
	v_mfma_f32_16x16x32_bf16 v[42:45], v[154:157], v[170:173], v[42:45]
	v_mfma_f32_16x16x32_bf16 v[30:33], v[146:149], v[204:207], v[30:33]
	v_mfma_f32_16x16x32_bf16 v[26:29], v[154:157], v[204:207], v[26:29]
	v_mfma_f32_16x16x32_bf16 v[14:17], v[146:149], v[212:215], v[14:17]
	v_mfma_f32_16x16x32_bf16 v[10:13], v[154:157], v[212:215], v[10:13]
	s_setprio 0
	s_barrier
	s_add_u32 s10, s14, 0xb0080
	s_addc_u32 s11, s15, 0
	s_add_i32 s14, s16, s20
	v_lshl_add_u64 v[140:141], s[10:11], 0, v[134:135]
	s_mov_b32 m0, s14
	s_nop 0
	global_load_lds_dwordx4 v[140:141], off
	v_lshl_add_u64 v[140:141], s[10:11], 0, v[132:133]
	s_add_i32 m0, s14, 0x2000
	s_nop 0
	global_load_lds_dwordx4 v[140:141], off
	s_waitcnt vmcnt(6)
	s_barrier
	s_setprio 1
	v_mfma_f32_16x16x32_bf16 v[54:57], v[216:219], v[158:161], v[54:57]
	v_mfma_f32_16x16x32_bf16 v[50:53], v[224:227], v[158:161], v[50:53]
	v_mfma_f32_16x16x32_bf16 v[38:41], v[216:219], v[166:169], v[38:41]
	v_mfma_f32_16x16x32_bf16 v[34:37], v[224:227], v[166:169], v[34:37]
	v_mfma_f32_16x16x32_bf16 v[22:25], v[216:219], v[200:203], v[22:25]
	v_mfma_f32_16x16x32_bf16 v[18:21], v[224:227], v[200:203], v[18:21]
	v_mfma_f32_16x16x32_bf16 v[6:9], v[216:219], v[208:211], v[6:9]
	v_mfma_f32_16x16x32_bf16 v[2:5], v[224:227], v[208:211], v[2:5]
	v_mfma_f32_16x16x32_bf16 v[54:57], v[220:223], v[162:165], v[54:57]
	v_mfma_f32_16x16x32_bf16 v[50:53], v[228:231], v[162:165], v[50:53]
	v_mfma_f32_16x16x32_bf16 v[38:41], v[220:223], v[170:173], v[38:41]
	v_mfma_f32_16x16x32_bf16 v[34:37], v[228:231], v[170:173], v[34:37]
	v_mfma_f32_16x16x32_bf16 v[22:25], v[220:223], v[204:207], v[22:25]
	v_mfma_f32_16x16x32_bf16 v[18:21], v[228:231], v[204:207], v[18:21]
	v_mfma_f32_16x16x32_bf16 v[6:9], v[220:223], v[212:215], v[6:9]
	v_mfma_f32_16x16x32_bf16 v[2:5], v[228:231], v[212:215], v[2:5]
	s_setprio 0
	s_add_i32 s41, s41, 2
	s_add_u32 s39, s39, 0x100
	s_addc_u32 s40, s40, 0
	s_cmp_gt_u32 s41, 41
	s_mov_b64 s[10:11], s[12:13]
	s_barrier
	s_cbranch_scc0 .LBB0_1673
	s_cmpk_gt_i32 s37, 0xff
	s_mov_b64 s[10:11], 0x30000
	s_cbranch_scc1 .LBB0_1665
	s_ashr_i32 s10, s37, 3
	s_mul_hi_i32 s11, s10, 0x1800
	s_mulk_i32 s10, 0x1800
	s_branch .LBB0_1665
